# baseline (speedup 1.0000x reference)
; template <class Epi, class Sched>
; __device__ __forceinline__ void gemm_phase(LAS unsigned char* lds, const Gemm g, const Sched& S, const Epi& E) {
;     ...
;         E(acc, cur, wr, wc, fr, fq);
;         if (!has_next) break;
; #pragma unroll
;         for (int a = 0; a < 2; ++a)
; #pragma unroll
;             for (int b = 0; b < 2; ++b)
; #pragma unroll
;                 for (int m = 0; m < 4; ++m)
; #pragma unroll
;                     for (int n = 0; n < 2; ++n) acc[a][b][m][n] = (f32x4){0.f, 0.f, 0.f, 0.f};
;         cur = nxt; cA = nA; cB = nB; ++ui;
.Lmy_p4_latch:
	s_and_b64 vcc, exec, s[6:7]
	s_mov_b32 s48, s38
	s_mov_b32 s46, s40
	s_mov_b64 s[10:11], s[44:45]
	s_mov_b64 s[8:9], s[42:43]
	s_cbranch_vccnz .LBB0_942

; #define PG8_STAGE(bufoff, gbase, voff) do { _Pragma("unroll") for (int _i = 0; _i < 2; ++_i) \
;         __builtin_amdgcn_global_load_lds((const unsigned*)((const char*)(gbase) + (voff)[_i]), (LAS unsigned*)(lds + (bufoff) + ldsw + _i * 8192), 16, 0, 0); } while (0)
; #define PG8_LDA(dst, b, h) do { _Pragma("unroll") for (int m = 0; m < 4; ++m) _Pragma("unroll") for (int k = 0; k < 2; ++k) dst[m][k] = *(const LAS bf16x8*)(lds + PG8_SA(b, h) + aoff + m * 2048 + k * 1024); } while (0)
; #define PG8_LDB(dst, b, h) do { _Pragma("unroll") for (int n = 0; n < 2; ++n) _Pragma("unroll") for (int k = 0; k < 2; ++k) dst[n][k] = *(const LAS bf16x8*)(lds + PG8_SB(b, h) + boff + n * 2048 + k * 1024); } while (0)
; #define PG8_MMA(ai, bj, At, Bt) do { __builtin_amdgcn_s_setprio(1); _Pragma("unroll") for (int m = 0; m < 4; ++m) _Pragma("unroll") for (int n = 0; n < 2; ++n) _Pragma("unroll") for (int k = 0; k < 2; ++k) \
;         acc[ai][bj][m][n] = __builtin_amdgcn_mfma_f32_16x16x32_bf16(Bt[n][k], At[m][k], acc[ai][bj][m][n], 0, 0, 0); __builtin_amdgcn_s_setprio(0); } while (0)
; #define PG8_WAIT_L(n) asm volatile("s_waitcnt lgkmcnt(" #n ")" ::: "memory")
; #define PG8_BAR __builtin_amdgcn_s_barrier()
; #define PG8_SCHED __builtin_amdgcn_sched_barrier(0)
; template <class Epi, class Sched>
; __device__ __forceinline__ void gemm_phase(LAS unsigned char* lds, const Gemm g, const Sched& S, const Epi& E) {
;     ...
;         for (int t = 0; t < nt; t += 2) {
;             const bool last = (t == nt - 2);
;             const char* a1 = cA + (size_t)(t + 1) * kstep;
;             const char* a2 = last ? nA : cA + (size_t)(t + 2) * kstep; const char* b2 = last ? nB : cB + (size_t)(t + 2) * kstep;
;             const char* a3 = a2 + kstep; const char* b3 = b2 + kstep;
;             PG8_LDB(B0, 0, 0); PG8_SCHED; PG8_LDA(At, 0, 0); PG8_STAGE(PG8_SA(1, 1), a1 + hstep, voffA);
;             PG8_WAIT_L(8); PG8_BAR; PG8_WAIT_L(0); PG8_MMA(0, 0, At, B0); PG8_BAR; PG8_SCHED;
;             PG8_LDB(B1, 0, 1); PG8_STAGE(PG8_SB(0, 0), b2, voffB);
;             PG8_BAR; PG8_WAIT_L(0); PG8_MMA(0, 1, At, B1); PG8_BAR;
;             PG8_LDA(At, 0, 1); PG8_STAGE(PG8_SA(0, 0), a2, voffA);
;             PG8_BAR; PG8_WAIT_L(0); PG8_MMA(1, 0, At, B0); PG8_BAR; PG8_SCHED;
.LBB0_429:
	ds_read_b128 v[150:153], v147
	ds_read_b128 v[154:157], v147 offset:1024
	ds_read_b128 v[158:161], v147 offset:2048
	ds_read_b128 v[162:165], v147 offset:3072
	s_add_u32 s10, s8, 0x4000
	s_addc_u32 s11, s9, 0
	s_cmp_eq_u32 s67, 28
	s_cselect_b32 s52, s41, s10
	s_cselect_b32 s53, s33, s11
	s_cselect_b32 s10, s47, s65
	s_cselect_b32 s11, s39, s66
	s_add_u32 s50, s52, 0x8000
	s_addc_u32 s51, s53, 0
	v_lshl_add_u64 v[166:167], s[8:9], 0, v[136:137]
	s_add_i32 m0, s49, 0xc000
	ds_read_b128 v[170:173], v148
	ds_read_b128 v[174:177], v148 offset:1024
	ds_read_b128 v[178:181], v148 offset:2048
	ds_read_b128 v[182:185], v148 offset:3072
	ds_read_b128 v[186:189], v148 offset:4096
	ds_read_b128 v[190:193], v148 offset:5120
	ds_read_b128 v[194:197], v148 offset:6144
	ds_read_b128 v[198:201], v148 offset:7168
	global_load_lds_dwordx4 v[166:167], off
	v_lshl_add_u64 v[166:167], s[8:9], 0, v[138:139]
	s_add_i32 m0, s49, 0xe000
	s_nop 0
	global_load_lds_dwordx4 v[166:167], off
	s_waitcnt lgkmcnt(8)
	s_barrier
	s_waitcnt lgkmcnt(0)
	s_setprio 1
	s_waitcnt lgkmcnt(0)
	v_mfma_f32_16x16x32_bf16 v[124:127], v[150:153], v[170:173], v[124:127]
	v_mfma_f32_16x16x32_bf16 v[120:123], v[158:161], v[170:173], v[120:123]
	v_mfma_f32_16x16x32_bf16 v[108:111], v[150:153], v[178:181], v[108:111]
	v_mfma_f32_16x16x32_bf16 v[104:107], v[158:161], v[178:181], v[104:107]
	v_mfma_f32_16x16x32_bf16 v[92:95], v[150:153], v[186:189], v[92:95]
	v_mfma_f32_16x16x32_bf16 v[88:91], v[158:161], v[186:189], v[88:91]
	v_mfma_f32_16x16x32_bf16 v[76:79], v[150:153], v[194:197], v[76:79]
	v_mfma_f32_16x16x32_bf16 v[72:75], v[158:161], v[194:197], v[72:75]
	v_mfma_f32_16x16x32_bf16 v[124:127], v[154:157], v[174:177], v[124:127]
	v_mfma_f32_16x16x32_bf16 v[120:123], v[162:165], v[174:177], v[120:123]
	v_mfma_f32_16x16x32_bf16 v[108:111], v[154:157], v[182:185], v[108:111]
	v_mfma_f32_16x16x32_bf16 v[104:107], v[162:165], v[182:185], v[104:107]
	v_mfma_f32_16x16x32_bf16 v[92:95], v[154:157], v[190:193], v[92:95]
	v_mfma_f32_16x16x32_bf16 v[88:91], v[162:165], v[190:193], v[88:91]
	v_mfma_f32_16x16x32_bf16 v[76:79], v[154:157], v[198:201], v[76:79]
	v_mfma_f32_16x16x32_bf16 v[72:75], v[162:165], v[198:201], v[72:75]
	s_setprio 0
	s_barrier
	s_add_i32 s68, s63, s56
	v_lshl_add_u64 v[166:167], s[10:11], 0, v[130:131]
	s_mov_b32 m0, s68
	ds_read_b128 v[206:209], v149
	ds_read_b128 v[210:213], v149 offset:1024
	ds_read_b128 v[214:217], v149 offset:2048
	ds_read_b128 v[218:221], v149 offset:3072
	global_load_lds_dwordx4 v[166:167], off
	v_lshl_add_u64 v[166:167], s[10:11], 0, v[134:135]
	s_add_i32 m0, s68, 0x2000
	s_nop 0
	global_load_lds_dwordx4 v[166:167], off
	s_barrier
	s_waitcnt lgkmcnt(0)
	s_setprio 1
	s_waitcnt lgkmcnt(0)
	v_mfma_f32_16x16x32_bf16 v[116:119], v[206:209], v[170:173], v[116:119]
	v_mfma_f32_16x16x32_bf16 v[112:115], v[214:217], v[170:173], v[112:115]
	v_mfma_f32_16x16x32_bf16 v[100:103], v[206:209], v[178:181], v[100:103]
	v_mfma_f32_16x16x32_bf16 v[96:99], v[214:217], v[178:181], v[96:99]
	v_mfma_f32_16x16x32_bf16 v[84:87], v[206:209], v[186:189], v[84:87]
	v_mfma_f32_16x16x32_bf16 v[80:83], v[214:217], v[186:189], v[80:83]
	v_mfma_f32_16x16x32_bf16 v[68:71], v[206:209], v[194:197], v[68:71]
	v_mfma_f32_16x16x32_bf16 v[64:67], v[214:217], v[194:197], v[64:67]
	v_mfma_f32_16x16x32_bf16 v[116:119], v[210:213], v[174:177], v[116:119]
	v_mfma_f32_16x16x32_bf16 v[112:115], v[218:221], v[174:177], v[112:115]
	v_mfma_f32_16x16x32_bf16 v[100:103], v[210:213], v[182:185], v[100:103]
	v_mfma_f32_16x16x32_bf16 v[96:99], v[218:221], v[182:185], v[96:99]
	v_mfma_f32_16x16x32_bf16 v[84:87], v[210:213], v[190:193], v[84:87]
	v_mfma_f32_16x16x32_bf16 v[80:83], v[218:221], v[190:193], v[80:83]
	v_mfma_f32_16x16x32_bf16 v[68:71], v[210:213], v[198:201], v[68:71]
	v_mfma_f32_16x16x32_bf16 v[64:67], v[218:221], v[198:201], v[64:67]
	s_setprio 0
	s_mov_b32 m0, s49
	v_lshl_add_u64 v[166:167], s[52:53], 0, v[128:129]
	s_barrier
	ds_read_b128 v[170:173], v148 offset:16384
	ds_read_b128 v[174:177], v148 offset:17408
	ds_read_b128 v[178:181], v148 offset:18432
	ds_read_b128 v[182:185], v148 offset:19456
	ds_read_b128 v[186:189], v148 offset:20480
	ds_read_b128 v[190:193], v148 offset:21504
	ds_read_b128 v[194:197], v148 offset:22528
	ds_read_b128 v[198:201], v148 offset:23552
	global_load_lds_dwordx4 v[166:167], off
	v_lshl_add_u64 v[166:167], s[52:53], 0, v[132:133]
	s_mov_b32 m0, s57
	s_nop 0
	global_load_lds_dwordx4 v[166:167], off
	s_barrier
	s_waitcnt lgkmcnt(0)
	s_setprio 1
	s_waitcnt lgkmcnt(0)
	v_mfma_f32_16x16x32_bf16 v[60:63], v[150:153], v[170:173], v[60:63]
	v_mfma_f32_16x16x32_bf16 v[56:59], v[158:161], v[170:173], v[56:59]
	v_mfma_f32_16x16x32_bf16 v[44:47], v[150:153], v[178:181], v[44:47]
	v_mfma_f32_16x16x32_bf16 v[40:43], v[158:161], v[178:181], v[40:43]
	v_mfma_f32_16x16x32_bf16 v[28:31], v[150:153], v[186:189], v[28:31]
	v_mfma_f32_16x16x32_bf16 v[24:27], v[158:161], v[186:189], v[24:27]
	v_mfma_f32_16x16x32_bf16 v[12:15], v[150:153], v[194:197], v[12:15]
	v_mfma_f32_16x16x32_bf16 v[8:11], v[158:161], v[194:197], v[8:11]
	v_mfma_f32_16x16x32_bf16 v[60:63], v[154:157], v[174:177], v[60:63]
	v_mfma_f32_16x16x32_bf16 v[56:59], v[162:165], v[174:177], v[56:59]
	v_mfma_f32_16x16x32_bf16 v[44:47], v[154:157], v[182:185], v[44:47]
	v_mfma_f32_16x16x32_bf16 v[40:43], v[162:165], v[182:185], v[40:43]
	v_mfma_f32_16x16x32_bf16 v[28:31], v[154:157], v[190:193], v[28:31]
	v_mfma_f32_16x16x32_bf16 v[24:27], v[162:165], v[190:193], v[24:27]
	v_mfma_f32_16x16x32_bf16 v[12:15], v[154:157], v[198:201], v[12:15]
	v_mfma_f32_16x16x32_bf16 v[8:11], v[162:165], v[198:201], v[8:11]
	s_setprio 0
	s_barrier
; #define PG8_STAGE(bufoff, gbase, voff) do { _Pragma("unroll") for (int _i = 0; _i < 2; ++_i) \
;         __builtin_amdgcn_global_load_lds((const unsigned*)((const char*)(gbase) + (voff)[_i]), (LAS unsigned*)(lds + (bufoff) + ldsw + _i * 8192), 16, 0, 0); } while (0)
; #define PG8_LDA(dst, b, h) do { _Pragma("unroll") for (int m = 0; m < 4; ++m) _Pragma("unroll") for (int k = 0; k < 2; ++k) dst[m][k] = *(const LAS bf16x8*)(lds + PG8_SA(b, h) + aoff + m * 2048 + k * 1024); } while (0)
; #define PG8_LDB(dst, b, h) do { _Pragma("unroll") for (int n = 0; n < 2; ++n) _Pragma("unroll") for (int k = 0; k < 2; ++k) dst[n][k] = *(const LAS bf16x8*)(lds + PG8_SB(b, h) + boff + n * 2048 + k * 1024); } while (0)
; #define PG8_MMA(ai, bj, At, Bt) do { __builtin_amdgcn_s_setprio(1); _Pragma("unroll") for (int m = 0; m < 4; ++m) _Pragma("unroll") for (int n = 0; n < 2; ++n) _Pragma("unroll") for (int k = 0; k < 2; ++k) \
;         acc[ai][bj][m][n] = __builtin_amdgcn_mfma_f32_16x16x32_bf16(Bt[n][k], At[m][k], acc[ai][bj][m][n], 0, 0, 0); __builtin_amdgcn_s_setprio(0); } while (0)
; #define PG8_WAIT_V(n) asm volatile("s_waitcnt vmcnt(" #n ")" ::: "memory")
; #define PG8_WAIT_L(n) asm volatile("s_waitcnt lgkmcnt(" #n ")" ::: "memory")
; #define PG8_BAR __builtin_amdgcn_s_barrier()
; #define PG8_SCHED __builtin_amdgcn_sched_barrier(0)
; template <class Epi, class Sched>
; __device__ __forceinline__ void gemm_phase(LAS unsigned char* lds, const Gemm g, const Sched& S, const Epi& E) {
;     ...
;             PG8_WAIT_V(6); PG8_BAR; PG8_MMA(1, 1, At, B1); PG8_BAR;
;             PG8_LDB(B0, 1, 0); PG8_SCHED; PG8_LDA(At, 1, 0); PG8_STAGE(PG8_SA(0, 1), a2 + hstep, voffA);
;             PG8_WAIT_L(8); PG8_BAR; PG8_WAIT_L(0); PG8_MMA(0, 0, At, B0); PG8_BAR; PG8_SCHED;
;             PG8_LDB(B1, 1, 1); PG8_STAGE(PG8_SB(1, 0), b3, voffB);
;             PG8_BAR; PG8_WAIT_L(0); PG8_MMA(0, 1, At, B1); PG8_BAR;
	s_add_u32 s68, s10, 0x4000
	s_addc_u32 s69, s11, 0
	s_add_i32 s71, s64, s56
	v_lshl_add_u64 v[150:151], s[68:69], 0, v[130:131]
	s_mov_b32 m0, s71
	s_nop 0
	global_load_lds_dwordx4 v[150:151], off
	v_lshl_add_u64 v[150:151], s[68:69], 0, v[134:135]
	s_add_i32 m0, s71, 0x2000
	s_nop 0
	global_load_lds_dwordx4 v[150:151], off
	s_waitcnt vmcnt(6)
	s_barrier
	s_setprio 1
	v_mfma_f32_16x16x32_bf16 v[52:55], v[206:209], v[170:173], v[52:55]
	v_mfma_f32_16x16x32_bf16 v[48:51], v[214:217], v[170:173], v[48:51]
	v_mfma_f32_16x16x32_bf16 v[36:39], v[206:209], v[178:181], v[36:39]
	v_mfma_f32_16x16x32_bf16 v[32:35], v[214:217], v[178:181], v[32:35]
	v_mfma_f32_16x16x32_bf16 v[20:23], v[206:209], v[186:189], v[20:23]
	v_mfma_f32_16x16x32_bf16 v[16:19], v[214:217], v[186:189], v[16:19]
	v_mfma_f32_16x16x32_bf16 v[4:7], v[206:209], v[194:197], v[4:7]
	v_mfma_f32_16x16x32_bf16 v[0:3], v[214:217], v[194:197], v[0:3]
	v_mfma_f32_16x16x32_bf16 v[52:55], v[210:213], v[174:177], v[52:55]
	v_mfma_f32_16x16x32_bf16 v[48:51], v[218:221], v[174:177], v[48:51]
	v_mfma_f32_16x16x32_bf16 v[36:39], v[210:213], v[182:185], v[36:39]
	v_mfma_f32_16x16x32_bf16 v[32:35], v[218:221], v[182:185], v[32:35]
	v_mfma_f32_16x16x32_bf16 v[20:23], v[210:213], v[190:193], v[20:23]
	v_mfma_f32_16x16x32_bf16 v[16:19], v[218:221], v[190:193], v[16:19]
	v_mfma_f32_16x16x32_bf16 v[4:7], v[210:213], v[198:201], v[4:7]
	v_mfma_f32_16x16x32_bf16 v[0:3], v[218:221], v[198:201], v[0:3]
	s_setprio 0
	s_add_i32 s68, 0, 0x18000
	v_add_u32_e32 v162, s68, v145
	s_barrier
	ds_read_b128 v[150:153], v162
	ds_read_b128 v[154:157], v162 offset:1024
	ds_read_b128 v[158:161], v162 offset:2048
	ds_read_b128 v[162:165], v162 offset:3072
	s_add_u32 s52, s52, 0x4000
	s_addc_u32 s53, s53, 0
	s_mov_b32 m0, s58
	v_lshl_add_u64 v[166:167], s[52:53], 0, v[128:129]
	ds_read_b128 v[170:173], v148 offset:32768
	ds_read_b128 v[174:177], v148 offset:33792
	ds_read_b128 v[178:181], v148 offset:34816
	ds_read_b128 v[182:185], v148 offset:35840
	ds_read_b128 v[186:189], v148 offset:36864
	ds_read_b128 v[190:193], v148 offset:37888
	ds_read_b128 v[194:197], v148 offset:38912
	ds_read_b128 v[198:201], v148 offset:39936
	global_load_lds_dwordx4 v[166:167], off
	v_lshl_add_u64 v[166:167], s[52:53], 0, v[132:133]
	s_mov_b32 m0, s59
	s_nop 0
	global_load_lds_dwordx4 v[166:167], off
	s_waitcnt lgkmcnt(8)
	s_barrier
	s_waitcnt lgkmcnt(0)
	s_setprio 1
	s_waitcnt lgkmcnt(0)
	v_mfma_f32_16x16x32_bf16 v[124:127], v[150:153], v[170:173], v[124:127]
	v_mfma_f32_16x16x32_bf16 v[120:123], v[158:161], v[170:173], v[120:123]
	v_mfma_f32_16x16x32_bf16 v[108:111], v[150:153], v[178:181], v[108:111]
	v_mfma_f32_16x16x32_bf16 v[104:107], v[158:161], v[178:181], v[104:107]
	v_mfma_f32_16x16x32_bf16 v[92:95], v[150:153], v[186:189], v[92:95]
	v_mfma_f32_16x16x32_bf16 v[88:91], v[158:161], v[186:189], v[88:91]
	v_mfma_f32_16x16x32_bf16 v[76:79], v[150:153], v[194:197], v[76:79]
	v_mfma_f32_16x16x32_bf16 v[72:75], v[158:161], v[194:197], v[72:75]
	v_mfma_f32_16x16x32_bf16 v[124:127], v[154:157], v[174:177], v[124:127]
	v_mfma_f32_16x16x32_bf16 v[120:123], v[162:165], v[174:177], v[120:123]
	v_mfma_f32_16x16x32_bf16 v[108:111], v[154:157], v[182:185], v[108:111]
	v_mfma_f32_16x16x32_bf16 v[104:107], v[162:165], v[182:185], v[104:107]
	v_mfma_f32_16x16x32_bf16 v[92:95], v[154:157], v[190:193], v[92:95]
	v_mfma_f32_16x16x32_bf16 v[88:91], v[162:165], v[190:193], v[88:91]
	v_mfma_f32_16x16x32_bf16 v[76:79], v[154:157], v[198:201], v[76:79]
	v_mfma_f32_16x16x32_bf16 v[72:75], v[162:165], v[198:201], v[72:75]
	s_setprio 0
	s_barrier
	s_add_i32 s69, 0, 0x1c000
	s_add_u32 s52, s10, 0x8000
	v_add_u32_e32 v166, s69, v145
	s_addc_u32 s53, s11, 0
	s_add_i32 s68, s68, s56
	ds_read_b128 v[206:209], v166
	ds_read_b128 v[210:213], v166 offset:1024
	ds_read_b128 v[214:217], v166 offset:2048
	ds_read_b128 v[218:221], v166 offset:3072
	v_lshl_add_u64 v[166:167], s[52:53], 0, v[130:131]
	s_mov_b32 m0, s68
	s_nop 0
	global_load_lds_dwordx4 v[166:167], off
	v_lshl_add_u64 v[166:167], s[52:53], 0, v[134:135]
	s_add_i32 m0, s68, 0x2000
	s_nop 0
	global_load_lds_dwordx4 v[166:167], off
	s_barrier
	s_waitcnt lgkmcnt(0)
	s_setprio 1
	s_waitcnt lgkmcnt(0)
	v_mfma_f32_16x16x32_bf16 v[116:119], v[206:209], v[170:173], v[116:119]
	v_mfma_f32_16x16x32_bf16 v[112:115], v[214:217], v[170:173], v[112:115]
	v_mfma_f32_16x16x32_bf16 v[100:103], v[206:209], v[178:181], v[100:103]
	v_mfma_f32_16x16x32_bf16 v[96:99], v[214:217], v[178:181], v[96:99]
	v_mfma_f32_16x16x32_bf16 v[84:87], v[206:209], v[186:189], v[84:87]
	v_mfma_f32_16x16x32_bf16 v[80:83], v[214:217], v[186:189], v[80:83]
	v_mfma_f32_16x16x32_bf16 v[68:71], v[206:209], v[194:197], v[68:71]
	v_mfma_f32_16x16x32_bf16 v[64:67], v[214:217], v[194:197], v[64:67]
	v_mfma_f32_16x16x32_bf16 v[116:119], v[210:213], v[174:177], v[116:119]
	v_mfma_f32_16x16x32_bf16 v[112:115], v[218:221], v[174:177], v[112:115]
	v_mfma_f32_16x16x32_bf16 v[100:103], v[210:213], v[182:185], v[100:103]
	v_mfma_f32_16x16x32_bf16 v[96:99], v[218:221], v[182:185], v[96:99]
	v_mfma_f32_16x16x32_bf16 v[84:87], v[210:213], v[190:193], v[84:87]
	v_mfma_f32_16x16x32_bf16 v[80:83], v[218:221], v[190:193], v[80:83]
	v_mfma_f32_16x16x32_bf16 v[68:71], v[210:213], v[198:201], v[68:71]
	v_mfma_f32_16x16x32_bf16 v[64:67], v[218:221], v[198:201], v[64:67]
	s_setprio 0
	s_mov_b32 m0, s61
	v_lshl_add_u64 v[166:167], s[50:51], 0, v[128:129]
	s_barrier
; __device__ __forceinline__ float gelu_f(float x) { const float u = 1.5957691216f * (x + 0.044715f * x * x * x); return x * sigmoid_f(u); }
; #define PG8_STAGE(bufoff, gbase, voff) do { _Pragma("unroll") for (int _i = 0; _i < 2; ++_i) \
;         __builtin_amdgcn_global_load_lds((const unsigned*)((const char*)(gbase) + (voff)[_i]), (LAS unsigned*)(lds + (bufoff) + ldsw + _i * 8192), 16, 0, 0); } while (0)
; #define PG8_LDA(dst, b, h) do { _Pragma("unroll") for (int m = 0; m < 4; ++m) _Pragma("unroll") for (int k = 0; k < 2; ++k) dst[m][k] = *(const LAS bf16x8*)(lds + PG8_SA(b, h) + aoff + m * 2048 + k * 1024); } while (0)
; #define PG8_MMA(ai, bj, At, Bt) do { __builtin_amdgcn_s_setprio(1); _Pragma("unroll") for (int m = 0; m < 4; ++m) _Pragma("unroll") for (int n = 0; n < 2; ++n) _Pragma("unroll") for (int k = 0; k < 2; ++k) \
;         acc[ai][bj][m][n] = __builtin_amdgcn_mfma_f32_16x16x32_bf16(Bt[n][k], At[m][k], acc[ai][bj][m][n], 0, 0, 0); __builtin_amdgcn_s_setprio(0); } while (0)
; #define PG8_WAIT_V(n) asm volatile("s_waitcnt vmcnt(" #n ")" ::: "memory")
; template <class Epi, class Sched>
; __device__ __forceinline__ void gemm_phase(LAS unsigned char* lds, const Gemm g, const Sched& S, const Epi& E) {
;     ...
;             PG8_LDA(At, 1, 1); PG8_STAGE(PG8_SA(1, 0), a3, voffA);
;             PG8_BAR; PG8_WAIT_L(0); PG8_MMA(1, 0, At, B0); PG8_BAR; PG8_SCHED;
;             PG8_STAGE(PG8_SB(1, 1), b3 + hstep, voffB);
;             PG8_WAIT_V(6); PG8_BAR; PG8_MMA(1, 1, At, B1); PG8_BAR;
;         }
;     __device__ __forceinline__ void operator()(const f32x4 (&acc)[2][2][4][2], const Unit& u, int wr, int wc, int fr, int fq) const {
;         const int row0 = u.pm * BM + wr * 64 + fr, col0 = u.pn * BM + wc * 32 + 8 * fq;
;         const int kind = ACT == 0 ? 0 : (u.pn < 4 ? 0 : (u.pn < 12 ? 1 : 2));
; #pragma unroll
;         for (int ai = 0; ai < 2; ++ai)
; #pragma unroll
;             for (int m = 0; m < 4; ++m) {
;                 bf16_t* rowp = O + (size_t)(row0 + ai * HALF + m * 16) * ldo + col0;
; #pragma unroll
;                 for (int bj = 0; bj < 2; ++bj) {
;                     float v[8];
; #pragma unroll
;                     for (int n = 0; n < 2; ++n)
; #pragma unroll
;                         for (int j = 0; j < 4; ++j) { const float a = acc[ai][bj][m][n][j]; v[n * 4 + j] = kind == 1 ? gelu_f(a) : (kind == 2 ? a * 0.0625f : a); }
	ds_read_b128 v[170:173], v148 offset:49152
	ds_read_b128 v[174:177], v148 offset:50176
	ds_read_b128 v[178:181], v148 offset:51200
	ds_read_b128 v[182:185], v148 offset:52224
	ds_read_b128 v[186:189], v148 offset:53248
	ds_read_b128 v[190:193], v148 offset:54272
	ds_read_b128 v[194:197], v148 offset:55296
	ds_read_b128 v[198:201], v148 offset:56320
	global_load_lds_dwordx4 v[166:167], off
	v_lshl_add_u64 v[166:167], s[50:51], 0, v[132:133]
	s_mov_b32 m0, s62
	s_nop 0
	global_load_lds_dwordx4 v[166:167], off
	s_barrier
	s_waitcnt lgkmcnt(0)
	s_setprio 1
	s_waitcnt lgkmcnt(0)
	v_mfma_f32_16x16x32_bf16 v[60:63], v[150:153], v[170:173], v[60:63]
	v_mfma_f32_16x16x32_bf16 v[56:59], v[158:161], v[170:173], v[56:59]
	v_mfma_f32_16x16x32_bf16 v[44:47], v[150:153], v[178:181], v[44:47]
	v_mfma_f32_16x16x32_bf16 v[40:43], v[158:161], v[178:181], v[40:43]
	v_mfma_f32_16x16x32_bf16 v[28:31], v[150:153], v[186:189], v[28:31]
	v_mfma_f32_16x16x32_bf16 v[24:27], v[158:161], v[186:189], v[24:27]
	v_mfma_f32_16x16x32_bf16 v[12:15], v[150:153], v[194:197], v[12:15]
	v_mfma_f32_16x16x32_bf16 v[8:11], v[158:161], v[194:197], v[8:11]
	v_mfma_f32_16x16x32_bf16 v[60:63], v[154:157], v[174:177], v[60:63]
	v_mfma_f32_16x16x32_bf16 v[56:59], v[162:165], v[174:177], v[56:59]
	v_mfma_f32_16x16x32_bf16 v[44:47], v[154:157], v[182:185], v[44:47]
	v_mfma_f32_16x16x32_bf16 v[40:43], v[162:165], v[182:185], v[40:43]
	v_mfma_f32_16x16x32_bf16 v[28:31], v[154:157], v[190:193], v[28:31]
	v_mfma_f32_16x16x32_bf16 v[24:27], v[162:165], v[190:193], v[24:27]
	v_mfma_f32_16x16x32_bf16 v[12:15], v[154:157], v[198:201], v[12:15]
	v_mfma_f32_16x16x32_bf16 v[8:11], v[162:165], v[198:201], v[8:11]
	s_setprio 0
	s_barrier
	s_add_u32 s10, s10, 0xc000
	s_addc_u32 s11, s11, 0
	s_add_i32 s50, s69, s56
	v_lshl_add_u64 v[150:151], s[10:11], 0, v[130:131]
	s_mov_b32 m0, s50
	s_nop 0
	global_load_lds_dwordx4 v[150:151], off
	v_lshl_add_u64 v[150:151], s[10:11], 0, v[134:135]
	s_add_i32 m0, s50, 0x2000
	s_nop 0
	global_load_lds_dwordx4 v[150:151], off
	s_waitcnt vmcnt(6)
	s_barrier
	s_setprio 1
	v_mfma_f32_16x16x32_bf16 v[52:55], v[206:209], v[170:173], v[52:55]
	v_mfma_f32_16x16x32_bf16 v[48:51], v[214:217], v[170:173], v[48:51]
	v_mfma_f32_16x16x32_bf16 v[36:39], v[206:209], v[178:181], v[36:39]
	v_mfma_f32_16x16x32_bf16 v[32:35], v[214:217], v[178:181], v[32:35]
	v_mfma_f32_16x16x32_bf16 v[20:23], v[206:209], v[186:189], v[20:23]
	v_mfma_f32_16x16x32_bf16 v[16:19], v[214:217], v[186:189], v[16:19]
	v_mfma_f32_16x16x32_bf16 v[4:7], v[206:209], v[194:197], v[4:7]
	v_mfma_f32_16x16x32_bf16 v[0:3], v[214:217], v[194:197], v[0:3]
	v_mfma_f32_16x16x32_bf16 v[52:55], v[210:213], v[174:177], v[52:55]
	v_mfma_f32_16x16x32_bf16 v[48:51], v[218:221], v[174:177], v[48:51]
	v_mfma_f32_16x16x32_bf16 v[36:39], v[210:213], v[182:185], v[36:39]
	v_mfma_f32_16x16x32_bf16 v[32:35], v[218:221], v[182:185], v[32:35]
	v_mfma_f32_16x16x32_bf16 v[20:23], v[210:213], v[190:193], v[20:23]
	v_mfma_f32_16x16x32_bf16 v[16:19], v[218:221], v[190:193], v[16:19]
	v_mfma_f32_16x16x32_bf16 v[4:7], v[210:213], v[198:201], v[4:7]
	v_mfma_f32_16x16x32_bf16 v[0:3], v[218:221], v[198:201], v[0:3]
	s_setprio 0
	s_add_i32 s67, s67, 2
	s_add_u32 s8, s8, 0x10000
	s_addc_u32 s9, s9, 0
	s_add_u32 s65, s65, 0x10000
	s_addc_u32 s66, s66, 0
	s_cmp_gt_u32 s67, 29
	s_barrier
	s_cbranch_scc0 .LBB0_429
	s_nop 7
	s_cmp_lt_i32 s48, 4
	s_cbranch_scc1 .Lmy_p4_store
	s_cmp_lt_i32 s48, 12
	s_cbranch_scc1 .Lmy_p4_gelu
	v_mul_f32_e32 v0, 0x3d800000, v0
	v_mul_f32_e32 v1, 0x3d800000, v1
	v_mul_f32_e32 v2, 0x3d800000, v2
	v_mul_f32_e32 v3, 0x3d800000, v3
	v_mul_f32_e32 v4, 0x3d800000, v4
	v_mul_f32_e32 v5, 0x3d800000, v5
	v_mul_f32_e32 v6, 0x3d800000, v6
	v_mul_f32_e32 v7, 0x3d800000, v7
	v_mul_f32_e32 v8, 0x3d800000, v8
	v_mul_f32_e32 v9, 0x3d800000, v9
	v_mul_f32_e32 v10, 0x3d800000, v10
	v_mul_f32_e32 v11, 0x3d800000, v11
	v_mul_f32_e32 v12, 0x3d800000, v12
	v_mul_f32_e32 v13, 0x3d800000, v13
	v_mul_f32_e32 v14, 0x3d800000, v14
	v_mul_f32_e32 v15, 0x3d800000, v15
	v_mul_f32_e32 v16, 0x3d800000, v16
	v_mul_f32_e32 v17, 0x3d800000, v17
	v_mul_f32_e32 v18, 0x3d800000, v18
	v_mul_f32_e32 v19, 0x3d800000, v19
	v_mul_f32_e32 v20, 0x3d800000, v20
	v_mul_f32_e32 v21, 0x3d800000, v21
	v_mul_f32_e32 v22, 0x3d800000, v22
	v_mul_f32_e32 v23, 0x3d800000, v23
	v_mul_f32_e32 v24, 0x3d800000, v24
	v_mul_f32_e32 v25, 0x3d800000, v25
	v_mul_f32_e32 v26, 0x3d800000, v26
	v_mul_f32_e32 v27, 0x3d800000, v27
	v_mul_f32_e32 v28, 0x3d800000, v28
	v_mul_f32_e32 v29, 0x3d800000, v29
	v_mul_f32_e32 v30, 0x3d800000, v30
	v_mul_f32_e32 v31, 0x3d800000, v31
	v_mul_f32_e32 v32, 0x3d800000, v32
	v_mul_f32_e32 v33, 0x3d800000, v33
	v_mul_f32_e32 v34, 0x3d800000, v34
	v_mul_f32_e32 v35, 0x3d800000, v35
	v_mul_f32_e32 v36, 0x3d800000, v36
	v_mul_f32_e32 v37, 0x3d800000, v37
	v_mul_f32_e32 v38, 0x3d800000, v38
	v_mul_f32_e32 v39, 0x3d800000, v39
	v_mul_f32_e32 v40, 0x3d800000, v40
	v_mul_f32_e32 v41, 0x3d800000, v41
	v_mul_f32_e32 v42, 0x3d800000, v42
	v_mul_f32_e32 v43, 0x3d800000, v43
	v_mul_f32_e32 v44, 0x3d800000, v44
	v_mul_f32_e32 v45, 0x3d800000, v45
	v_mul_f32_e32 v46, 0x3d800000, v46
	v_mul_f32_e32 v47, 0x3d800000, v47
	v_mul_f32_e32 v48, 0x3d800000, v48
	v_mul_f32_e32 v49, 0x3d800000, v49
	v_mul_f32_e32 v50, 0x3d800000, v50
	v_mul_f32_e32 v51, 0x3d800000, v51
	v_mul_f32_e32 v52, 0x3d800000, v52
	v_mul_f32_e32 v53, 0x3d800000, v53
	v_mul_f32_e32 v54, 0x3d800000, v54
	v_mul_f32_e32 v55, 0x3d800000, v55
	v_mul_f32_e32 v56, 0x3d800000, v56
	v_mul_f32_e32 v57, 0x3d800000, v57
	v_mul_f32_e32 v58, 0x3d800000, v58
	v_mul_f32_e32 v59, 0x3d800000, v59
	v_mul_f32_e32 v60, 0x3d800000, v60
; __device__ __forceinline__ float gelu_f(float x) { const float u = 1.5957691216f * (x + 0.044715f * x * x * x); return x * sigmoid_f(u); }
; __device__ __forceinline__ float sigmoid_f(float x) { return __builtin_amdgcn_rcpf(1.0f + __expf(-x)); }
; __device__ __forceinline__ float silu_f(float x) { return x * sigmoid_f(x); }
;     __device__ __forceinline__ void operator()(const f32x4 (&acc)[2][2][4][2], const Unit& u, int wr, int wc, int fr, int fq) const {
;     ...
;                     for (int n = 0; n < 2; ++n)
; #pragma unroll
;                         for (int j = 0; j < 4; ++j) { const float a = acc[ai][bj][m][n][j]; v[n * 4 + j] = kind == 1 ? gelu_f(a) : (kind == 2 ? a * 0.0625f : a); }
	v_mul_f32_e32 v61, 0x3d800000, v61
	v_mul_f32_e32 v62, 0x3d800000, v62
	v_mul_f32_e32 v63, 0x3d800000, v63
	v_mul_f32_e32 v64, 0x3d800000, v64
	v_mul_f32_e32 v65, 0x3d800000, v65
	v_mul_f32_e32 v66, 0x3d800000, v66
	v_mul_f32_e32 v67, 0x3d800000, v67
	v_mul_f32_e32 v68, 0x3d800000, v68
	v_mul_f32_e32 v69, 0x3d800000, v69
	v_mul_f32_e32 v70, 0x3d800000, v70
	v_mul_f32_e32 v71, 0x3d800000, v71
	v_mul_f32_e32 v72, 0x3d800000, v72
	v_mul_f32_e32 v73, 0x3d800000, v73
	v_mul_f32_e32 v74, 0x3d800000, v74
	v_mul_f32_e32 v75, 0x3d800000, v75
	v_mul_f32_e32 v76, 0x3d800000, v76
	v_mul_f32_e32 v77, 0x3d800000, v77
	v_mul_f32_e32 v78, 0x3d800000, v78
	v_mul_f32_e32 v79, 0x3d800000, v79
	v_mul_f32_e32 v80, 0x3d800000, v80
	v_mul_f32_e32 v81, 0x3d800000, v81
	v_mul_f32_e32 v82, 0x3d800000, v82
	v_mul_f32_e32 v83, 0x3d800000, v83
	v_mul_f32_e32 v84, 0x3d800000, v84
	v_mul_f32_e32 v85, 0x3d800000, v85
	v_mul_f32_e32 v86, 0x3d800000, v86
	v_mul_f32_e32 v87, 0x3d800000, v87
	v_mul_f32_e32 v88, 0x3d800000, v88
	v_mul_f32_e32 v89, 0x3d800000, v89
	v_mul_f32_e32 v90, 0x3d800000, v90
	v_mul_f32_e32 v91, 0x3d800000, v91
	v_mul_f32_e32 v92, 0x3d800000, v92
	v_mul_f32_e32 v93, 0x3d800000, v93
	v_mul_f32_e32 v94, 0x3d800000, v94
	v_mul_f32_e32 v95, 0x3d800000, v95
	v_mul_f32_e32 v96, 0x3d800000, v96
	v_mul_f32_e32 v97, 0x3d800000, v97
	v_mul_f32_e32 v98, 0x3d800000, v98
	v_mul_f32_e32 v99, 0x3d800000, v99
	v_mul_f32_e32 v100, 0x3d800000, v100
	v_mul_f32_e32 v101, 0x3d800000, v101
	v_mul_f32_e32 v102, 0x3d800000, v102
	v_mul_f32_e32 v103, 0x3d800000, v103
	v_mul_f32_e32 v104, 0x3d800000, v104
	v_mul_f32_e32 v105, 0x3d800000, v105
	v_mul_f32_e32 v106, 0x3d800000, v106
	v_mul_f32_e32 v107, 0x3d800000, v107
	v_mul_f32_e32 v108, 0x3d800000, v108
	v_mul_f32_e32 v109, 0x3d800000, v109
	v_mul_f32_e32 v110, 0x3d800000, v110
	v_mul_f32_e32 v111, 0x3d800000, v111
	v_mul_f32_e32 v112, 0x3d800000, v112
	v_mul_f32_e32 v113, 0x3d800000, v113
	v_mul_f32_e32 v114, 0x3d800000, v114
	v_mul_f32_e32 v115, 0x3d800000, v115
	v_mul_f32_e32 v116, 0x3d800000, v116
	v_mul_f32_e32 v117, 0x3d800000, v117
	v_mul_f32_e32 v118, 0x3d800000, v118
	v_mul_f32_e32 v119, 0x3d800000, v119
	v_mul_f32_e32 v120, 0x3d800000, v120
	v_mul_f32_e32 v121, 0x3d800000, v121
	v_mul_f32_e32 v122, 0x3d800000, v122
	v_mul_f32_e32 v123, 0x3d800000, v123
	v_mul_f32_e32 v124, 0x3d800000, v124
	v_mul_f32_e32 v125, 0x3d800000, v125
	v_mul_f32_e32 v126, 0x3d800000, v126
	v_mul_f32_e32 v127, 0x3d800000, v127
	s_branch .Lmy_p4_store
.Lmy_p4_gelu:
	v_mul_f32_e32 v150, 0x3d372713, v124
	v_mul_f32_e32 v151, 0x3d372713, v125
	v_mul_f32_e32 v152, 0x3d372713, v126
	v_mul_f32_e32 v153, 0x3d372713, v127
	v_mul_f32_e32 v154, 0x3d372713, v120
	v_mul_f32_e32 v155, 0x3d372713, v121
	v_mul_f32_e32 v156, 0x3d372713, v122
	v_mul_f32_e32 v157, 0x3d372713, v123
	v_mul_f32_e32 v150, v124, v150
	v_mul_f32_e32 v151, v125, v151
	v_mul_f32_e32 v152, v126, v152
	v_mul_f32_e32 v153, v127, v153
	v_mul_f32_e32 v154, v120, v154
	v_mul_f32_e32 v155, v121, v155
	v_mul_f32_e32 v156, v122, v156
	v_mul_f32_e32 v157, v123, v157
	v_fma_f32 v150, v124, v150, v124
	v_fma_f32 v151, v125, v151, v125
	v_fma_f32 v152, v126, v152, v126
	v_fma_f32 v153, v127, v153, v127
	v_fma_f32 v154, v120, v154, v120
	v_fma_f32 v155, v121, v155, v121
	v_fma_f32 v156, v122, v156, v122
	v_fma_f32 v157, v123, v157, v123
	v_mul_f32_e32 v150, 0x3fcc422a, v150
	v_mul_f32_e32 v151, 0x3fcc422a, v151
	v_mul_f32_e32 v152, 0x3fcc422a, v152
	v_mul_f32_e32 v153, 0x3fcc422a, v153
	v_mul_f32_e32 v154, 0x3fcc422a, v154
	v_mul_f32_e32 v155, 0x3fcc422a, v155
	v_mul_f32_e32 v156, 0x3fcc422a, v156
	v_mul_f32_e32 v157, 0x3fcc422a, v157
	v_mul_f32_e32 v150, 0xbfb8aa3b, v150
	v_mul_f32_e32 v151, 0xbfb8aa3b, v151
	v_mul_f32_e32 v152, 0xbfb8aa3b, v152
	v_mul_f32_e32 v153, 0xbfb8aa3b, v153
	v_mul_f32_e32 v154, 0xbfb8aa3b, v154
	v_mul_f32_e32 v155, 0xbfb8aa3b, v155
	v_mul_f32_e32 v156, 0xbfb8aa3b, v156
	v_mul_f32_e32 v157, 0xbfb8aa3b, v157
	v_exp_f32_e32 v150, v150
	v_exp_f32_e32 v151, v151
	v_exp_f32_e32 v152, v152
	v_exp_f32_e32 v153, v153
	v_exp_f32_e32 v154, v154
	v_exp_f32_e32 v155, v155
	v_exp_f32_e32 v156, v156
	v_exp_f32_e32 v157, v157
	v_add_f32_e32 v150, 1.0, v150
	v_add_f32_e32 v151, 1.0, v151
	v_add_f32_e32 v152, 1.0, v152
	v_add_f32_e32 v153, 1.0, v153
	v_add_f32_e32 v154, 1.0, v154
	v_add_f32_e32 v155, 1.0, v155
	v_add_f32_e32 v156, 1.0, v156
	v_add_f32_e32 v157, 1.0, v157
	v_rcp_f32_e32 v150, v150
	v_rcp_f32_e32 v151, v151
	v_rcp_f32_e32 v152, v152
	v_rcp_f32_e32 v153, v153
	v_rcp_f32_e32 v154, v154
	v_rcp_f32_e32 v155, v155
	v_rcp_f32_e32 v156, v156
	v_rcp_f32_e32 v157, v157
	v_mul_f32_e32 v124, v124, v150
	v_mul_f32_e32 v125, v125, v151
	v_mul_f32_e32 v126, v126, v152
	v_mul_f32_e32 v127, v127, v153
	v_mul_f32_e32 v120, v120, v154
	v_mul_f32_e32 v121, v121, v155
	v_mul_f32_e32 v122, v122, v156
	v_mul_f32_e32 v123, v123, v157
	v_mul_f32_e32 v150, 0x3d372713, v116
	v_mul_f32_e32 v151, 0x3d372713, v117
	v_mul_f32_e32 v152, 0x3d372713, v118
	v_mul_f32_e32 v153, 0x3d372713, v119
	v_mul_f32_e32 v154, 0x3d372713, v112
	v_mul_f32_e32 v155, 0x3d372713, v113
	v_mul_f32_e32 v156, 0x3d372713, v114
	v_mul_f32_e32 v157, 0x3d372713, v115
	v_mul_f32_e32 v150, v116, v150
	v_mul_f32_e32 v151, v117, v151
	v_mul_f32_e32 v152, v118, v152
	v_mul_f32_e32 v153, v119, v153
	v_mul_f32_e32 v154, v112, v154
	v_mul_f32_e32 v155, v113, v155
	v_mul_f32_e32 v156, v114, v156
	v_mul_f32_e32 v157, v115, v157
	v_fma_f32 v150, v116, v150, v116
	v_fma_f32 v151, v117, v151, v117
	v_fma_f32 v152, v118, v152, v118
	v_fma_f32 v153, v119, v153, v119
	v_fma_f32 v154, v112, v154, v112
	v_fma_f32 v155, v113, v155, v113
; __device__ __forceinline__ float gelu_f(float x) { const float u = 1.5957691216f * (x + 0.044715f * x * x * x); return x * sigmoid_f(u); }
; __device__ __forceinline__ float sigmoid_f(float x) { return __builtin_amdgcn_rcpf(1.0f + __expf(-x)); }
; __device__ __forceinline__ float silu_f(float x) { return x * sigmoid_f(x); }
;     __device__ __forceinline__ void operator()(const f32x4 (&acc)[2][2][4][2], const Unit& u, int wr, int wc, int fr, int fq) const {
;     ...
;                     for (int n = 0; n < 2; ++n)
; #pragma unroll
;                         for (int j = 0; j < 4; ++j) { const float a = acc[ai][bj][m][n][j]; v[n * 4 + j] = kind == 1 ? gelu_f(a) : (kind == 2 ? a * 0.0625f : a); }
	v_fma_f32 v156, v114, v156, v114
	v_fma_f32 v157, v115, v157, v115
	v_mul_f32_e32 v150, 0x3fcc422a, v150
	v_mul_f32_e32 v151, 0x3fcc422a, v151
	v_mul_f32_e32 v152, 0x3fcc422a, v152
	v_mul_f32_e32 v153, 0x3fcc422a, v153
	v_mul_f32_e32 v154, 0x3fcc422a, v154
	v_mul_f32_e32 v155, 0x3fcc422a, v155
	v_mul_f32_e32 v156, 0x3fcc422a, v156
	v_mul_f32_e32 v157, 0x3fcc422a, v157
	v_mul_f32_e32 v150, 0xbfb8aa3b, v150
	v_mul_f32_e32 v151, 0xbfb8aa3b, v151
	v_mul_f32_e32 v152, 0xbfb8aa3b, v152
	v_mul_f32_e32 v153, 0xbfb8aa3b, v153
	v_mul_f32_e32 v154, 0xbfb8aa3b, v154
	v_mul_f32_e32 v155, 0xbfb8aa3b, v155
	v_mul_f32_e32 v156, 0xbfb8aa3b, v156
	v_mul_f32_e32 v157, 0xbfb8aa3b, v157
	v_exp_f32_e32 v150, v150
	v_exp_f32_e32 v151, v151
	v_exp_f32_e32 v152, v152
	v_exp_f32_e32 v153, v153
	v_exp_f32_e32 v154, v154
	v_exp_f32_e32 v155, v155
	v_exp_f32_e32 v156, v156
	v_exp_f32_e32 v157, v157
	v_add_f32_e32 v150, 1.0, v150
	v_add_f32_e32 v151, 1.0, v151
	v_add_f32_e32 v152, 1.0, v152
	v_add_f32_e32 v153, 1.0, v153
	v_add_f32_e32 v154, 1.0, v154
	v_add_f32_e32 v155, 1.0, v155
	v_add_f32_e32 v156, 1.0, v156
	v_add_f32_e32 v157, 1.0, v157
	v_rcp_f32_e32 v150, v150
	v_rcp_f32_e32 v151, v151
	v_rcp_f32_e32 v152, v152
	v_rcp_f32_e32 v153, v153
	v_rcp_f32_e32 v154, v154
	v_rcp_f32_e32 v155, v155
	v_rcp_f32_e32 v156, v156
	v_rcp_f32_e32 v157, v157
	v_mul_f32_e32 v116, v116, v150
	v_mul_f32_e32 v117, v117, v151
	v_mul_f32_e32 v118, v118, v152
	v_mul_f32_e32 v119, v119, v153
	v_mul_f32_e32 v112, v112, v154
	v_mul_f32_e32 v113, v113, v155
	v_mul_f32_e32 v114, v114, v156
	v_mul_f32_e32 v115, v115, v157
	v_mul_f32_e32 v150, 0x3d372713, v108
	v_mul_f32_e32 v151, 0x3d372713, v109
	v_mul_f32_e32 v152, 0x3d372713, v110
	v_mul_f32_e32 v153, 0x3d372713, v111
	v_mul_f32_e32 v154, 0x3d372713, v104
	v_mul_f32_e32 v155, 0x3d372713, v105
	v_mul_f32_e32 v156, 0x3d372713, v106
	v_mul_f32_e32 v157, 0x3d372713, v107
	v_mul_f32_e32 v150, v108, v150
	v_mul_f32_e32 v151, v109, v151
	v_mul_f32_e32 v152, v110, v152
	v_mul_f32_e32 v153, v111, v153
	v_mul_f32_e32 v154, v104, v154
	v_mul_f32_e32 v155, v105, v155
	v_mul_f32_e32 v156, v106, v156
	v_mul_f32_e32 v157, v107, v157
	v_fma_f32 v150, v108, v150, v108
	v_fma_f32 v151, v109, v151, v109
	v_fma_f32 v152, v110, v152, v110
	v_fma_f32 v153, v111, v153, v111
	v_fma_f32 v154, v104, v154, v104
	v_fma_f32 v155, v105, v155, v105
	v_fma_f32 v156, v106, v156, v106
	v_fma_f32 v157, v107, v157, v107
	v_mul_f32_e32 v150, 0x3fcc422a, v150
	v_mul_f32_e32 v151, 0x3fcc422a, v151
	v_mul_f32_e32 v152, 0x3fcc422a, v152
	v_mul_f32_e32 v153, 0x3fcc422a, v153
	v_mul_f32_e32 v154, 0x3fcc422a, v154
	v_mul_f32_e32 v155, 0x3fcc422a, v155
	v_mul_f32_e32 v156, 0x3fcc422a, v156
	v_mul_f32_e32 v157, 0x3fcc422a, v157
	v_mul_f32_e32 v150, 0xbfb8aa3b, v150
	v_mul_f32_e32 v151, 0xbfb8aa3b, v151
	v_mul_f32_e32 v152, 0xbfb8aa3b, v152
	v_mul_f32_e32 v153, 0xbfb8aa3b, v153
	v_mul_f32_e32 v154, 0xbfb8aa3b, v154
	v_mul_f32_e32 v155, 0xbfb8aa3b, v155
	v_mul_f32_e32 v156, 0xbfb8aa3b, v156
	v_mul_f32_e32 v157, 0xbfb8aa3b, v157
	v_exp_f32_e32 v150, v150
	v_exp_f32_e32 v151, v151
	v_exp_f32_e32 v152, v152
	v_exp_f32_e32 v153, v153
	v_exp_f32_e32 v154, v154
	v_exp_f32_e32 v155, v155
	v_exp_f32_e32 v156, v156
	v_exp_f32_e32 v157, v157
	v_add_f32_e32 v150, 1.0, v150
	v_add_f32_e32 v151, 1.0, v151
	v_add_f32_e32 v152, 1.0, v152
	v_add_f32_e32 v153, 1.0, v153
	v_add_f32_e32 v154, 1.0, v154
	v_add_f32_e32 v155, 1.0, v155
	v_add_f32_e32 v156, 1.0, v156
	v_add_f32_e32 v157, 1.0, v157
	v_rcp_f32_e32 v150, v150
	v_rcp_f32_e32 v151, v151
	v_rcp_f32_e32 v152, v152
	v_rcp_f32_e32 v153, v153
	v_rcp_f32_e32 v154, v154
	v_rcp_f32_e32 v155, v155
	v_rcp_f32_e32 v156, v156
	v_rcp_f32_e32 v157, v157
	v_mul_f32_e32 v108, v108, v150
	v_mul_f32_e32 v109, v109, v151
	v_mul_f32_e32 v110, v110, v152
	v_mul_f32_e32 v111, v111, v153
	v_mul_f32_e32 v104, v104, v154
	v_mul_f32_e32 v105, v105, v155
	v_mul_f32_e32 v106, v106, v156
	v_mul_f32_e32 v107, v107, v157
	v_mul_f32_e32 v150, 0x3d372713, v100
	v_mul_f32_e32 v151, 0x3d372713, v101
	v_mul_f32_e32 v152, 0x3d372713, v102
	v_mul_f32_e32 v153, 0x3d372713, v103
	v_mul_f32_e32 v154, 0x3d372713, v96
	v_mul_f32_e32 v155, 0x3d372713, v97
	v_mul_f32_e32 v156, 0x3d372713, v98
	v_mul_f32_e32 v157, 0x3d372713, v99
	v_mul_f32_e32 v150, v100, v150
	v_mul_f32_e32 v151, v101, v151
	v_mul_f32_e32 v152, v102, v152
	v_mul_f32_e32 v153, v103, v153
	v_mul_f32_e32 v154, v96, v154
	v_mul_f32_e32 v155, v97, v155
	v_mul_f32_e32 v156, v98, v156
	v_mul_f32_e32 v157, v99, v157
	v_fma_f32 v150, v100, v150, v100
	v_fma_f32 v151, v101, v151, v101
	v_fma_f32 v152, v102, v152, v102
	v_fma_f32 v153, v103, v153, v103
	v_fma_f32 v154, v96, v154, v96
	v_fma_f32 v155, v97, v155, v97
	v_fma_f32 v156, v98, v156, v98
	v_fma_f32 v157, v99, v157, v99
	v_mul_f32_e32 v150, 0x3fcc422a, v150
	v_mul_f32_e32 v151, 0x3fcc422a, v151
	v_mul_f32_e32 v152, 0x3fcc422a, v152
	v_mul_f32_e32 v153, 0x3fcc422a, v153
	v_mul_f32_e32 v154, 0x3fcc422a, v154
	v_mul_f32_e32 v155, 0x3fcc422a, v155
	v_mul_f32_e32 v156, 0x3fcc422a, v156
	v_mul_f32_e32 v157, 0x3fcc422a, v157
	v_mul_f32_e32 v150, 0xbfb8aa3b, v150
	v_mul_f32_e32 v151, 0xbfb8aa3b, v151
	v_mul_f32_e32 v152, 0xbfb8aa3b, v152
	v_mul_f32_e32 v153, 0xbfb8aa3b, v153
	v_mul_f32_e32 v154, 0xbfb8aa3b, v154
	v_mul_f32_e32 v155, 0xbfb8aa3b, v155
	v_mul_f32_e32 v156, 0xbfb8aa3b, v156
	v_mul_f32_e32 v157, 0xbfb8aa3b, v157
	v_exp_f32_e32 v150, v150
	v_exp_f32_e32 v151, v151
	v_exp_f32_e32 v152, v152
	v_exp_f32_e32 v153, v153
	v_exp_f32_e32 v154, v154
	v_exp_f32_e32 v155, v155
	v_exp_f32_e32 v156, v156
	v_exp_f32_e32 v157, v157
	v_add_f32_e32 v150, 1.0, v150
	v_add_f32_e32 v151, 1.0, v151
; __device__ __forceinline__ float gelu_f(float x) { const float u = 1.5957691216f * (x + 0.044715f * x * x * x); return x * sigmoid_f(u); }
; __device__ __forceinline__ float sigmoid_f(float x) { return __builtin_amdgcn_rcpf(1.0f + __expf(-x)); }
; __device__ __forceinline__ float silu_f(float x) { return x * sigmoid_f(x); }
;     __device__ __forceinline__ void operator()(const f32x4 (&acc)[2][2][4][2], const Unit& u, int wr, int wc, int fr, int fq) const {
;     ...
;                     for (int n = 0; n < 2; ++n)
; #pragma unroll
;                         for (int j = 0; j < 4; ++j) { const float a = acc[ai][bj][m][n][j]; v[n * 4 + j] = kind == 1 ? gelu_f(a) : (kind == 2 ? a * 0.0625f : a); }
	v_add_f32_e32 v152, 1.0, v152
	v_add_f32_e32 v153, 1.0, v153
	v_add_f32_e32 v154, 1.0, v154
	v_add_f32_e32 v155, 1.0, v155
	v_add_f32_e32 v156, 1.0, v156
	v_add_f32_e32 v157, 1.0, v157
	v_rcp_f32_e32 v150, v150
	v_rcp_f32_e32 v151, v151
	v_rcp_f32_e32 v152, v152
	v_rcp_f32_e32 v153, v153
	v_rcp_f32_e32 v154, v154
	v_rcp_f32_e32 v155, v155
	v_rcp_f32_e32 v156, v156
	v_rcp_f32_e32 v157, v157
	v_mul_f32_e32 v100, v100, v150
	v_mul_f32_e32 v101, v101, v151
	v_mul_f32_e32 v102, v102, v152
	v_mul_f32_e32 v103, v103, v153
	v_mul_f32_e32 v96, v96, v154
	v_mul_f32_e32 v97, v97, v155
	v_mul_f32_e32 v98, v98, v156
	v_mul_f32_e32 v99, v99, v157
	v_mul_f32_e32 v150, 0x3d372713, v92
	v_mul_f32_e32 v151, 0x3d372713, v93
	v_mul_f32_e32 v152, 0x3d372713, v94
	v_mul_f32_e32 v153, 0x3d372713, v95
	v_mul_f32_e32 v154, 0x3d372713, v88
	v_mul_f32_e32 v155, 0x3d372713, v89
	v_mul_f32_e32 v156, 0x3d372713, v90
	v_mul_f32_e32 v157, 0x3d372713, v91
	v_mul_f32_e32 v150, v92, v150
	v_mul_f32_e32 v151, v93, v151
	v_mul_f32_e32 v152, v94, v152
	v_mul_f32_e32 v153, v95, v153
	v_mul_f32_e32 v154, v88, v154
	v_mul_f32_e32 v155, v89, v155
	v_mul_f32_e32 v156, v90, v156
	v_mul_f32_e32 v157, v91, v157
	v_fma_f32 v150, v92, v150, v92
	v_fma_f32 v151, v93, v151, v93
	v_fma_f32 v152, v94, v152, v94
	v_fma_f32 v153, v95, v153, v95
	v_fma_f32 v154, v88, v154, v88
	v_fma_f32 v155, v89, v155, v89
	v_fma_f32 v156, v90, v156, v90
	v_fma_f32 v157, v91, v157, v91
	v_mul_f32_e32 v150, 0x3fcc422a, v150
	v_mul_f32_e32 v151, 0x3fcc422a, v151
	v_mul_f32_e32 v152, 0x3fcc422a, v152
	v_mul_f32_e32 v153, 0x3fcc422a, v153
	v_mul_f32_e32 v154, 0x3fcc422a, v154
	v_mul_f32_e32 v155, 0x3fcc422a, v155
	v_mul_f32_e32 v156, 0x3fcc422a, v156
	v_mul_f32_e32 v157, 0x3fcc422a, v157
	v_mul_f32_e32 v150, 0xbfb8aa3b, v150
	v_mul_f32_e32 v151, 0xbfb8aa3b, v151
	v_mul_f32_e32 v152, 0xbfb8aa3b, v152
	v_mul_f32_e32 v153, 0xbfb8aa3b, v153
	v_mul_f32_e32 v154, 0xbfb8aa3b, v154
	v_mul_f32_e32 v155, 0xbfb8aa3b, v155
	v_mul_f32_e32 v156, 0xbfb8aa3b, v156
	v_mul_f32_e32 v157, 0xbfb8aa3b, v157
	v_exp_f32_e32 v150, v150
	v_exp_f32_e32 v151, v151
	v_exp_f32_e32 v152, v152
	v_exp_f32_e32 v153, v153
	v_exp_f32_e32 v154, v154
	v_exp_f32_e32 v155, v155
	v_exp_f32_e32 v156, v156
	v_exp_f32_e32 v157, v157
	v_add_f32_e32 v150, 1.0, v150
	v_add_f32_e32 v151, 1.0, v151
	v_add_f32_e32 v152, 1.0, v152
	v_add_f32_e32 v153, 1.0, v153
	v_add_f32_e32 v154, 1.0, v154
	v_add_f32_e32 v155, 1.0, v155
	v_add_f32_e32 v156, 1.0, v156
	v_add_f32_e32 v157, 1.0, v157
	v_rcp_f32_e32 v150, v150
	v_rcp_f32_e32 v151, v151
	v_rcp_f32_e32 v152, v152
	v_rcp_f32_e32 v153, v153
	v_rcp_f32_e32 v154, v154
	v_rcp_f32_e32 v155, v155
	v_rcp_f32_e32 v156, v156
	v_rcp_f32_e32 v157, v157
	v_mul_f32_e32 v92, v92, v150
	v_mul_f32_e32 v93, v93, v151
	v_mul_f32_e32 v94, v94, v152
	v_mul_f32_e32 v95, v95, v153
	v_mul_f32_e32 v88, v88, v154
	v_mul_f32_e32 v89, v89, v155
	v_mul_f32_e32 v90, v90, v156
	v_mul_f32_e32 v91, v91, v157
	v_mul_f32_e32 v150, 0x3d372713, v84
	v_mul_f32_e32 v151, 0x3d372713, v85
	v_mul_f32_e32 v152, 0x3d372713, v86
	v_mul_f32_e32 v153, 0x3d372713, v87
	v_mul_f32_e32 v154, 0x3d372713, v80
	v_mul_f32_e32 v155, 0x3d372713, v81
	v_mul_f32_e32 v156, 0x3d372713, v82
	v_mul_f32_e32 v157, 0x3d372713, v83
	v_mul_f32_e32 v150, v84, v150
	v_mul_f32_e32 v151, v85, v151
	v_mul_f32_e32 v152, v86, v152
	v_mul_f32_e32 v153, v87, v153
	v_mul_f32_e32 v154, v80, v154
	v_mul_f32_e32 v155, v81, v155
	v_mul_f32_e32 v156, v82, v156
	v_mul_f32_e32 v157, v83, v157
	v_fma_f32 v150, v84, v150, v84
	v_fma_f32 v151, v85, v151, v85
	v_fma_f32 v152, v86, v152, v86
	v_fma_f32 v153, v87, v153, v87
	v_fma_f32 v154, v80, v154, v80
	v_fma_f32 v155, v81, v155, v81
	v_fma_f32 v156, v82, v156, v82
	v_fma_f32 v157, v83, v157, v83
	v_mul_f32_e32 v150, 0x3fcc422a, v150
	v_mul_f32_e32 v151, 0x3fcc422a, v151
	v_mul_f32_e32 v152, 0x3fcc422a, v152
	v_mul_f32_e32 v153, 0x3fcc422a, v153
	v_mul_f32_e32 v154, 0x3fcc422a, v154
	v_mul_f32_e32 v155, 0x3fcc422a, v155
	v_mul_f32_e32 v156, 0x3fcc422a, v156
	v_mul_f32_e32 v157, 0x3fcc422a, v157
	v_mul_f32_e32 v150, 0xbfb8aa3b, v150
	v_mul_f32_e32 v151, 0xbfb8aa3b, v151
	v_mul_f32_e32 v152, 0xbfb8aa3b, v152
	v_mul_f32_e32 v153, 0xbfb8aa3b, v153
	v_mul_f32_e32 v154, 0xbfb8aa3b, v154
	v_mul_f32_e32 v155, 0xbfb8aa3b, v155
	v_mul_f32_e32 v156, 0xbfb8aa3b, v156
	v_mul_f32_e32 v157, 0xbfb8aa3b, v157
	v_exp_f32_e32 v150, v150
	v_exp_f32_e32 v151, v151
	v_exp_f32_e32 v152, v152
	v_exp_f32_e32 v153, v153
	v_exp_f32_e32 v154, v154
	v_exp_f32_e32 v155, v155
	v_exp_f32_e32 v156, v156
	v_exp_f32_e32 v157, v157
	v_add_f32_e32 v150, 1.0, v150
	v_add_f32_e32 v151, 1.0, v151
	v_add_f32_e32 v152, 1.0, v152
	v_add_f32_e32 v153, 1.0, v153
	v_add_f32_e32 v154, 1.0, v154
	v_add_f32_e32 v155, 1.0, v155
	v_add_f32_e32 v156, 1.0, v156
	v_add_f32_e32 v157, 1.0, v157
	v_rcp_f32_e32 v150, v150
	v_rcp_f32_e32 v151, v151
	v_rcp_f32_e32 v152, v152
	v_rcp_f32_e32 v153, v153
	v_rcp_f32_e32 v154, v154
	v_rcp_f32_e32 v155, v155
	v_rcp_f32_e32 v156, v156
	v_rcp_f32_e32 v157, v157
	v_mul_f32_e32 v84, v84, v150
	v_mul_f32_e32 v85, v85, v151
	v_mul_f32_e32 v86, v86, v152
	v_mul_f32_e32 v87, v87, v153
	v_mul_f32_e32 v80, v80, v154
	v_mul_f32_e32 v81, v81, v155
	v_mul_f32_e32 v82, v82, v156
	v_mul_f32_e32 v83, v83, v157
	v_mul_f32_e32 v150, 0x3d372713, v76
	v_mul_f32_e32 v151, 0x3d372713, v77
	v_mul_f32_e32 v152, 0x3d372713, v78
	v_mul_f32_e32 v153, 0x3d372713, v79
	v_mul_f32_e32 v154, 0x3d372713, v72
	v_mul_f32_e32 v155, 0x3d372713, v73
	v_mul_f32_e32 v156, 0x3d372713, v74
	v_mul_f32_e32 v157, 0x3d372713, v75
	v_mul_f32_e32 v150, v76, v150
	v_mul_f32_e32 v151, v77, v151
	v_mul_f32_e32 v152, v78, v152
; __device__ __forceinline__ float gelu_f(float x) { const float u = 1.5957691216f * (x + 0.044715f * x * x * x); return x * sigmoid_f(u); }
; __device__ __forceinline__ float sigmoid_f(float x) { return __builtin_amdgcn_rcpf(1.0f + __expf(-x)); }
; __device__ __forceinline__ float silu_f(float x) { return x * sigmoid_f(x); }
;     __device__ __forceinline__ void operator()(const f32x4 (&acc)[2][2][4][2], const Unit& u, int wr, int wc, int fr, int fq) const {
;     ...
;                     for (int n = 0; n < 2; ++n)
; #pragma unroll
;                         for (int j = 0; j < 4; ++j) { const float a = acc[ai][bj][m][n][j]; v[n * 4 + j] = kind == 1 ? gelu_f(a) : (kind == 2 ? a * 0.0625f : a); }
	v_mul_f32_e32 v153, v79, v153
	v_mul_f32_e32 v154, v72, v154
	v_mul_f32_e32 v155, v73, v155
	v_mul_f32_e32 v156, v74, v156
	v_mul_f32_e32 v157, v75, v157
	v_fma_f32 v150, v76, v150, v76
	v_fma_f32 v151, v77, v151, v77
	v_fma_f32 v152, v78, v152, v78
	v_fma_f32 v153, v79, v153, v79
	v_fma_f32 v154, v72, v154, v72
	v_fma_f32 v155, v73, v155, v73
	v_fma_f32 v156, v74, v156, v74
	v_fma_f32 v157, v75, v157, v75
	v_mul_f32_e32 v150, 0x3fcc422a, v150
	v_mul_f32_e32 v151, 0x3fcc422a, v151
	v_mul_f32_e32 v152, 0x3fcc422a, v152
	v_mul_f32_e32 v153, 0x3fcc422a, v153
	v_mul_f32_e32 v154, 0x3fcc422a, v154
	v_mul_f32_e32 v155, 0x3fcc422a, v155
	v_mul_f32_e32 v156, 0x3fcc422a, v156
	v_mul_f32_e32 v157, 0x3fcc422a, v157
	v_mul_f32_e32 v150, 0xbfb8aa3b, v150
	v_mul_f32_e32 v151, 0xbfb8aa3b, v151
	v_mul_f32_e32 v152, 0xbfb8aa3b, v152
	v_mul_f32_e32 v153, 0xbfb8aa3b, v153
	v_mul_f32_e32 v154, 0xbfb8aa3b, v154
	v_mul_f32_e32 v155, 0xbfb8aa3b, v155
	v_mul_f32_e32 v156, 0xbfb8aa3b, v156
	v_mul_f32_e32 v157, 0xbfb8aa3b, v157
	v_exp_f32_e32 v150, v150
	v_exp_f32_e32 v151, v151
	v_exp_f32_e32 v152, v152
	v_exp_f32_e32 v153, v153
	v_exp_f32_e32 v154, v154
	v_exp_f32_e32 v155, v155
	v_exp_f32_e32 v156, v156
	v_exp_f32_e32 v157, v157
	v_add_f32_e32 v150, 1.0, v150
	v_add_f32_e32 v151, 1.0, v151
	v_add_f32_e32 v152, 1.0, v152
	v_add_f32_e32 v153, 1.0, v153
	v_add_f32_e32 v154, 1.0, v154
	v_add_f32_e32 v155, 1.0, v155
	v_add_f32_e32 v156, 1.0, v156
	v_add_f32_e32 v157, 1.0, v157
	v_rcp_f32_e32 v150, v150
	v_rcp_f32_e32 v151, v151
	v_rcp_f32_e32 v152, v152
	v_rcp_f32_e32 v153, v153
	v_rcp_f32_e32 v154, v154
	v_rcp_f32_e32 v155, v155
	v_rcp_f32_e32 v156, v156
	v_rcp_f32_e32 v157, v157
	v_mul_f32_e32 v76, v76, v150
	v_mul_f32_e32 v77, v77, v151
	v_mul_f32_e32 v78, v78, v152
	v_mul_f32_e32 v79, v79, v153
	v_mul_f32_e32 v72, v72, v154
	v_mul_f32_e32 v73, v73, v155
	v_mul_f32_e32 v74, v74, v156
	v_mul_f32_e32 v75, v75, v157
	v_mul_f32_e32 v150, 0x3d372713, v68
	v_mul_f32_e32 v151, 0x3d372713, v69
	v_mul_f32_e32 v152, 0x3d372713, v70
	v_mul_f32_e32 v153, 0x3d372713, v71
	v_mul_f32_e32 v154, 0x3d372713, v64
	v_mul_f32_e32 v155, 0x3d372713, v65
	v_mul_f32_e32 v156, 0x3d372713, v66
	v_mul_f32_e32 v157, 0x3d372713, v67
	v_mul_f32_e32 v150, v68, v150
	v_mul_f32_e32 v151, v69, v151
	v_mul_f32_e32 v152, v70, v152
	v_mul_f32_e32 v153, v71, v153
	v_mul_f32_e32 v154, v64, v154
	v_mul_f32_e32 v155, v65, v155
	v_mul_f32_e32 v156, v66, v156
	v_mul_f32_e32 v157, v67, v157
	v_fma_f32 v150, v68, v150, v68
	v_fma_f32 v151, v69, v151, v69
	v_fma_f32 v152, v70, v152, v70
	v_fma_f32 v153, v71, v153, v71
	v_fma_f32 v154, v64, v154, v64
	v_fma_f32 v155, v65, v155, v65
	v_fma_f32 v156, v66, v156, v66
	v_fma_f32 v157, v67, v157, v67
	v_mul_f32_e32 v150, 0x3fcc422a, v150
	v_mul_f32_e32 v151, 0x3fcc422a, v151
	v_mul_f32_e32 v152, 0x3fcc422a, v152
	v_mul_f32_e32 v153, 0x3fcc422a, v153
	v_mul_f32_e32 v154, 0x3fcc422a, v154
	v_mul_f32_e32 v155, 0x3fcc422a, v155
	v_mul_f32_e32 v156, 0x3fcc422a, v156
	v_mul_f32_e32 v157, 0x3fcc422a, v157
	v_mul_f32_e32 v150, 0xbfb8aa3b, v150
	v_mul_f32_e32 v151, 0xbfb8aa3b, v151
	v_mul_f32_e32 v152, 0xbfb8aa3b, v152
	v_mul_f32_e32 v153, 0xbfb8aa3b, v153
	v_mul_f32_e32 v154, 0xbfb8aa3b, v154
	v_mul_f32_e32 v155, 0xbfb8aa3b, v155
	v_mul_f32_e32 v156, 0xbfb8aa3b, v156
	v_mul_f32_e32 v157, 0xbfb8aa3b, v157
	v_exp_f32_e32 v150, v150
	v_exp_f32_e32 v151, v151
	v_exp_f32_e32 v152, v152
	v_exp_f32_e32 v153, v153
	v_exp_f32_e32 v154, v154
	v_exp_f32_e32 v155, v155
	v_exp_f32_e32 v156, v156
	v_exp_f32_e32 v157, v157
	v_add_f32_e32 v150, 1.0, v150
	v_add_f32_e32 v151, 1.0, v151
	v_add_f32_e32 v152, 1.0, v152
	v_add_f32_e32 v153, 1.0, v153
	v_add_f32_e32 v154, 1.0, v154
	v_add_f32_e32 v155, 1.0, v155
	v_add_f32_e32 v156, 1.0, v156
	v_add_f32_e32 v157, 1.0, v157
	v_rcp_f32_e32 v150, v150
	v_rcp_f32_e32 v151, v151
	v_rcp_f32_e32 v152, v152
	v_rcp_f32_e32 v153, v153
	v_rcp_f32_e32 v154, v154
	v_rcp_f32_e32 v155, v155
	v_rcp_f32_e32 v156, v156
	v_rcp_f32_e32 v157, v157
	v_mul_f32_e32 v68, v68, v150
	v_mul_f32_e32 v69, v69, v151
	v_mul_f32_e32 v70, v70, v152
	v_mul_f32_e32 v71, v71, v153
	v_mul_f32_e32 v64, v64, v154
	v_mul_f32_e32 v65, v65, v155
	v_mul_f32_e32 v66, v66, v156
	v_mul_f32_e32 v67, v67, v157
	v_mul_f32_e32 v150, 0x3d372713, v60
	v_mul_f32_e32 v151, 0x3d372713, v61
	v_mul_f32_e32 v152, 0x3d372713, v62
	v_mul_f32_e32 v153, 0x3d372713, v63
	v_mul_f32_e32 v154, 0x3d372713, v56
	v_mul_f32_e32 v155, 0x3d372713, v57
	v_mul_f32_e32 v156, 0x3d372713, v58
	v_mul_f32_e32 v157, 0x3d372713, v59
	v_mul_f32_e32 v150, v60, v150
	v_mul_f32_e32 v151, v61, v151
	v_mul_f32_e32 v152, v62, v152
	v_mul_f32_e32 v153, v63, v153
	v_mul_f32_e32 v154, v56, v154
	v_mul_f32_e32 v155, v57, v155
	v_mul_f32_e32 v156, v58, v156
	v_mul_f32_e32 v157, v59, v157
	v_fma_f32 v150, v60, v150, v60
	v_fma_f32 v151, v61, v151, v61
	v_fma_f32 v152, v62, v152, v62
	v_fma_f32 v153, v63, v153, v63
	v_fma_f32 v154, v56, v154, v56
	v_fma_f32 v155, v57, v155, v57
	v_fma_f32 v156, v58, v156, v58
	v_fma_f32 v157, v59, v157, v59
	v_mul_f32_e32 v150, 0x3fcc422a, v150
	v_mul_f32_e32 v151, 0x3fcc422a, v151
	v_mul_f32_e32 v152, 0x3fcc422a, v152
	v_mul_f32_e32 v153, 0x3fcc422a, v153
	v_mul_f32_e32 v154, 0x3fcc422a, v154
	v_mul_f32_e32 v155, 0x3fcc422a, v155
	v_mul_f32_e32 v156, 0x3fcc422a, v156
	v_mul_f32_e32 v157, 0x3fcc422a, v157
	v_mul_f32_e32 v150, 0xbfb8aa3b, v150
	v_mul_f32_e32 v151, 0xbfb8aa3b, v151
	v_mul_f32_e32 v152, 0xbfb8aa3b, v152
	v_mul_f32_e32 v153, 0xbfb8aa3b, v153
	v_mul_f32_e32 v154, 0xbfb8aa3b, v154
	v_mul_f32_e32 v155, 0xbfb8aa3b, v155
	v_mul_f32_e32 v156, 0xbfb8aa3b, v156
	v_mul_f32_e32 v157, 0xbfb8aa3b, v157
; __device__ __forceinline__ float gelu_f(float x) { const float u = 1.5957691216f * (x + 0.044715f * x * x * x); return x * sigmoid_f(u); }
; __device__ __forceinline__ float sigmoid_f(float x) { return __builtin_amdgcn_rcpf(1.0f + __expf(-x)); }
; __device__ __forceinline__ float silu_f(float x) { return x * sigmoid_f(x); }
;     __device__ __forceinline__ void operator()(const f32x4 (&acc)[2][2][4][2], const Unit& u, int wr, int wc, int fr, int fq) const {
;     ...
;                     for (int n = 0; n < 2; ++n)
; #pragma unroll
;                         for (int j = 0; j < 4; ++j) { const float a = acc[ai][bj][m][n][j]; v[n * 4 + j] = kind == 1 ? gelu_f(a) : (kind == 2 ? a * 0.0625f : a); }
	v_exp_f32_e32 v150, v150
	v_exp_f32_e32 v151, v151
	v_exp_f32_e32 v152, v152
	v_exp_f32_e32 v153, v153
	v_exp_f32_e32 v154, v154
	v_exp_f32_e32 v155, v155
	v_exp_f32_e32 v156, v156
	v_exp_f32_e32 v157, v157
	v_add_f32_e32 v150, 1.0, v150
	v_add_f32_e32 v151, 1.0, v151
	v_add_f32_e32 v152, 1.0, v152
	v_add_f32_e32 v153, 1.0, v153
	v_add_f32_e32 v154, 1.0, v154
	v_add_f32_e32 v155, 1.0, v155
	v_add_f32_e32 v156, 1.0, v156
	v_add_f32_e32 v157, 1.0, v157
	v_rcp_f32_e32 v150, v150
	v_rcp_f32_e32 v151, v151
	v_rcp_f32_e32 v152, v152
	v_rcp_f32_e32 v153, v153
	v_rcp_f32_e32 v154, v154
	v_rcp_f32_e32 v155, v155
	v_rcp_f32_e32 v156, v156
	v_rcp_f32_e32 v157, v157
	v_mul_f32_e32 v60, v60, v150
	v_mul_f32_e32 v61, v61, v151
	v_mul_f32_e32 v62, v62, v152
	v_mul_f32_e32 v63, v63, v153
	v_mul_f32_e32 v56, v56, v154
	v_mul_f32_e32 v57, v57, v155
	v_mul_f32_e32 v58, v58, v156
	v_mul_f32_e32 v59, v59, v157
	v_mul_f32_e32 v150, 0x3d372713, v52
	v_mul_f32_e32 v151, 0x3d372713, v53
	v_mul_f32_e32 v152, 0x3d372713, v54
	v_mul_f32_e32 v153, 0x3d372713, v55
	v_mul_f32_e32 v154, 0x3d372713, v48
	v_mul_f32_e32 v155, 0x3d372713, v49
	v_mul_f32_e32 v156, 0x3d372713, v50
	v_mul_f32_e32 v157, 0x3d372713, v51
	v_mul_f32_e32 v150, v52, v150
	v_mul_f32_e32 v151, v53, v151
	v_mul_f32_e32 v152, v54, v152
	v_mul_f32_e32 v153, v55, v153
	v_mul_f32_e32 v154, v48, v154
	v_mul_f32_e32 v155, v49, v155
	v_mul_f32_e32 v156, v50, v156
	v_mul_f32_e32 v157, v51, v157
	v_fma_f32 v150, v52, v150, v52
	v_fma_f32 v151, v53, v151, v53
	v_fma_f32 v152, v54, v152, v54
	v_fma_f32 v153, v55, v153, v55
	v_fma_f32 v154, v48, v154, v48
	v_fma_f32 v155, v49, v155, v49
	v_fma_f32 v156, v50, v156, v50
	v_fma_f32 v157, v51, v157, v51
	v_mul_f32_e32 v150, 0x3fcc422a, v150
	v_mul_f32_e32 v151, 0x3fcc422a, v151
	v_mul_f32_e32 v152, 0x3fcc422a, v152
	v_mul_f32_e32 v153, 0x3fcc422a, v153
	v_mul_f32_e32 v154, 0x3fcc422a, v154
	v_mul_f32_e32 v155, 0x3fcc422a, v155
	v_mul_f32_e32 v156, 0x3fcc422a, v156
	v_mul_f32_e32 v157, 0x3fcc422a, v157
	v_mul_f32_e32 v150, 0xbfb8aa3b, v150
	v_mul_f32_e32 v151, 0xbfb8aa3b, v151
	v_mul_f32_e32 v152, 0xbfb8aa3b, v152
	v_mul_f32_e32 v153, 0xbfb8aa3b, v153
	v_mul_f32_e32 v154, 0xbfb8aa3b, v154
	v_mul_f32_e32 v155, 0xbfb8aa3b, v155
	v_mul_f32_e32 v156, 0xbfb8aa3b, v156
	v_mul_f32_e32 v157, 0xbfb8aa3b, v157
	v_exp_f32_e32 v150, v150
	v_exp_f32_e32 v151, v151
	v_exp_f32_e32 v152, v152
	v_exp_f32_e32 v153, v153
	v_exp_f32_e32 v154, v154
	v_exp_f32_e32 v155, v155
	v_exp_f32_e32 v156, v156
	v_exp_f32_e32 v157, v157
	v_add_f32_e32 v150, 1.0, v150
	v_add_f32_e32 v151, 1.0, v151
	v_add_f32_e32 v152, 1.0, v152
	v_add_f32_e32 v153, 1.0, v153
	v_add_f32_e32 v154, 1.0, v154
	v_add_f32_e32 v155, 1.0, v155
	v_add_f32_e32 v156, 1.0, v156
	v_add_f32_e32 v157, 1.0, v157
	v_rcp_f32_e32 v150, v150
	v_rcp_f32_e32 v151, v151
	v_rcp_f32_e32 v152, v152
	v_rcp_f32_e32 v153, v153
	v_rcp_f32_e32 v154, v154
	v_rcp_f32_e32 v155, v155
	v_rcp_f32_e32 v156, v156
	v_rcp_f32_e32 v157, v157
	v_mul_f32_e32 v52, v52, v150
	v_mul_f32_e32 v53, v53, v151
	v_mul_f32_e32 v54, v54, v152
	v_mul_f32_e32 v55, v55, v153
	v_mul_f32_e32 v48, v48, v154
	v_mul_f32_e32 v49, v49, v155
	v_mul_f32_e32 v50, v50, v156
	v_mul_f32_e32 v51, v51, v157
	v_mul_f32_e32 v150, 0x3d372713, v44
	v_mul_f32_e32 v151, 0x3d372713, v45
	v_mul_f32_e32 v152, 0x3d372713, v46
	v_mul_f32_e32 v153, 0x3d372713, v47
	v_mul_f32_e32 v154, 0x3d372713, v40
	v_mul_f32_e32 v155, 0x3d372713, v41
	v_mul_f32_e32 v156, 0x3d372713, v42
	v_mul_f32_e32 v157, 0x3d372713, v43
	v_mul_f32_e32 v150, v44, v150
	v_mul_f32_e32 v151, v45, v151
	v_mul_f32_e32 v152, v46, v152
	v_mul_f32_e32 v153, v47, v153
	v_mul_f32_e32 v154, v40, v154
	v_mul_f32_e32 v155, v41, v155
	v_mul_f32_e32 v156, v42, v156
	v_mul_f32_e32 v157, v43, v157
	v_fma_f32 v150, v44, v150, v44
	v_fma_f32 v151, v45, v151, v45
	v_fma_f32 v152, v46, v152, v46
	v_fma_f32 v153, v47, v153, v47
	v_fma_f32 v154, v40, v154, v40
	v_fma_f32 v155, v41, v155, v41
	v_fma_f32 v156, v42, v156, v42
	v_fma_f32 v157, v43, v157, v43
	v_mul_f32_e32 v150, 0x3fcc422a, v150
	v_mul_f32_e32 v151, 0x3fcc422a, v151
	v_mul_f32_e32 v152, 0x3fcc422a, v152
	v_mul_f32_e32 v153, 0x3fcc422a, v153
	v_mul_f32_e32 v154, 0x3fcc422a, v154
	v_mul_f32_e32 v155, 0x3fcc422a, v155
	v_mul_f32_e32 v156, 0x3fcc422a, v156
	v_mul_f32_e32 v157, 0x3fcc422a, v157
	v_mul_f32_e32 v150, 0xbfb8aa3b, v150
	v_mul_f32_e32 v151, 0xbfb8aa3b, v151
	v_mul_f32_e32 v152, 0xbfb8aa3b, v152
	v_mul_f32_e32 v153, 0xbfb8aa3b, v153
	v_mul_f32_e32 v154, 0xbfb8aa3b, v154
	v_mul_f32_e32 v155, 0xbfb8aa3b, v155
	v_mul_f32_e32 v156, 0xbfb8aa3b, v156
	v_mul_f32_e32 v157, 0xbfb8aa3b, v157
	v_exp_f32_e32 v150, v150
	v_exp_f32_e32 v151, v151
	v_exp_f32_e32 v152, v152
	v_exp_f32_e32 v153, v153
	v_exp_f32_e32 v154, v154
	v_exp_f32_e32 v155, v155
	v_exp_f32_e32 v156, v156
	v_exp_f32_e32 v157, v157
	v_add_f32_e32 v150, 1.0, v150
	v_add_f32_e32 v151, 1.0, v151
	v_add_f32_e32 v152, 1.0, v152
	v_add_f32_e32 v153, 1.0, v153
	v_add_f32_e32 v154, 1.0, v154
	v_add_f32_e32 v155, 1.0, v155
	v_add_f32_e32 v156, 1.0, v156
	v_add_f32_e32 v157, 1.0, v157
	v_rcp_f32_e32 v150, v150
	v_rcp_f32_e32 v151, v151
	v_rcp_f32_e32 v152, v152
	v_rcp_f32_e32 v153, v153
	v_rcp_f32_e32 v154, v154
	v_rcp_f32_e32 v155, v155
	v_rcp_f32_e32 v156, v156
	v_rcp_f32_e32 v157, v157
	v_mul_f32_e32 v44, v44, v150
	v_mul_f32_e32 v45, v45, v151
	v_mul_f32_e32 v46, v46, v152
	v_mul_f32_e32 v47, v47, v153
	v_mul_f32_e32 v40, v40, v154
	v_mul_f32_e32 v41, v41, v155
	v_mul_f32_e32 v42, v42, v156
	v_mul_f32_e32 v43, v43, v157
	v_mul_f32_e32 v150, 0x3d372713, v36
	v_mul_f32_e32 v151, 0x3d372713, v37
	v_mul_f32_e32 v152, 0x3d372713, v38
; __device__ __forceinline__ float gelu_f(float x) { const float u = 1.5957691216f * (x + 0.044715f * x * x * x); return x * sigmoid_f(u); }
; __device__ __forceinline__ float sigmoid_f(float x) { return __builtin_amdgcn_rcpf(1.0f + __expf(-x)); }
; __device__ __forceinline__ float silu_f(float x) { return x * sigmoid_f(x); }
;     __device__ __forceinline__ void operator()(const f32x4 (&acc)[2][2][4][2], const Unit& u, int wr, int wc, int fr, int fq) const {
;     ...
;                     for (int n = 0; n < 2; ++n)
; #pragma unroll
;                         for (int j = 0; j < 4; ++j) { const float a = acc[ai][bj][m][n][j]; v[n * 4 + j] = kind == 1 ? gelu_f(a) : (kind == 2 ? a * 0.0625f : a); }
	v_mul_f32_e32 v153, 0x3d372713, v39
	v_mul_f32_e32 v154, 0x3d372713, v32
	v_mul_f32_e32 v155, 0x3d372713, v33
	v_mul_f32_e32 v156, 0x3d372713, v34
	v_mul_f32_e32 v157, 0x3d372713, v35
	v_mul_f32_e32 v150, v36, v150
	v_mul_f32_e32 v151, v37, v151
	v_mul_f32_e32 v152, v38, v152
	v_mul_f32_e32 v153, v39, v153
	v_mul_f32_e32 v154, v32, v154
	v_mul_f32_e32 v155, v33, v155
	v_mul_f32_e32 v156, v34, v156
	v_mul_f32_e32 v157, v35, v157
	v_fma_f32 v150, v36, v150, v36
	v_fma_f32 v151, v37, v151, v37
	v_fma_f32 v152, v38, v152, v38
	v_fma_f32 v153, v39, v153, v39
	v_fma_f32 v154, v32, v154, v32
	v_fma_f32 v155, v33, v155, v33
	v_fma_f32 v156, v34, v156, v34
	v_fma_f32 v157, v35, v157, v35
	v_mul_f32_e32 v150, 0x3fcc422a, v150
	v_mul_f32_e32 v151, 0x3fcc422a, v151
	v_mul_f32_e32 v152, 0x3fcc422a, v152
	v_mul_f32_e32 v153, 0x3fcc422a, v153
	v_mul_f32_e32 v154, 0x3fcc422a, v154
	v_mul_f32_e32 v155, 0x3fcc422a, v155
	v_mul_f32_e32 v156, 0x3fcc422a, v156
	v_mul_f32_e32 v157, 0x3fcc422a, v157
	v_mul_f32_e32 v150, 0xbfb8aa3b, v150
	v_mul_f32_e32 v151, 0xbfb8aa3b, v151
	v_mul_f32_e32 v152, 0xbfb8aa3b, v152
	v_mul_f32_e32 v153, 0xbfb8aa3b, v153
	v_mul_f32_e32 v154, 0xbfb8aa3b, v154
	v_mul_f32_e32 v155, 0xbfb8aa3b, v155
	v_mul_f32_e32 v156, 0xbfb8aa3b, v156
	v_mul_f32_e32 v157, 0xbfb8aa3b, v157
	v_exp_f32_e32 v150, v150
	v_exp_f32_e32 v151, v151
	v_exp_f32_e32 v152, v152
	v_exp_f32_e32 v153, v153
	v_exp_f32_e32 v154, v154
	v_exp_f32_e32 v155, v155
	v_exp_f32_e32 v156, v156
	v_exp_f32_e32 v157, v157
	v_add_f32_e32 v150, 1.0, v150
	v_add_f32_e32 v151, 1.0, v151
	v_add_f32_e32 v152, 1.0, v152
	v_add_f32_e32 v153, 1.0, v153
	v_add_f32_e32 v154, 1.0, v154
	v_add_f32_e32 v155, 1.0, v155
	v_add_f32_e32 v156, 1.0, v156
	v_add_f32_e32 v157, 1.0, v157
	v_rcp_f32_e32 v150, v150
	v_rcp_f32_e32 v151, v151
	v_rcp_f32_e32 v152, v152
	v_rcp_f32_e32 v153, v153
	v_rcp_f32_e32 v154, v154
	v_rcp_f32_e32 v155, v155
	v_rcp_f32_e32 v156, v156
	v_rcp_f32_e32 v157, v157
	v_mul_f32_e32 v36, v36, v150
	v_mul_f32_e32 v37, v37, v151
	v_mul_f32_e32 v38, v38, v152
	v_mul_f32_e32 v39, v39, v153
	v_mul_f32_e32 v32, v32, v154
	v_mul_f32_e32 v33, v33, v155
	v_mul_f32_e32 v34, v34, v156
	v_mul_f32_e32 v35, v35, v157
	v_mul_f32_e32 v150, 0x3d372713, v28
	v_mul_f32_e32 v151, 0x3d372713, v29
	v_mul_f32_e32 v152, 0x3d372713, v30
	v_mul_f32_e32 v153, 0x3d372713, v31
	v_mul_f32_e32 v154, 0x3d372713, v24
	v_mul_f32_e32 v155, 0x3d372713, v25
	v_mul_f32_e32 v156, 0x3d372713, v26
	v_mul_f32_e32 v157, 0x3d372713, v27
	v_mul_f32_e32 v150, v28, v150
	v_mul_f32_e32 v151, v29, v151
	v_mul_f32_e32 v152, v30, v152
	v_mul_f32_e32 v153, v31, v153
	v_mul_f32_e32 v154, v24, v154
	v_mul_f32_e32 v155, v25, v155
	v_mul_f32_e32 v156, v26, v156
	v_mul_f32_e32 v157, v27, v157
	v_fma_f32 v150, v28, v150, v28
	v_fma_f32 v151, v29, v151, v29
	v_fma_f32 v152, v30, v152, v30
	v_fma_f32 v153, v31, v153, v31
	v_fma_f32 v154, v24, v154, v24
	v_fma_f32 v155, v25, v155, v25
	v_fma_f32 v156, v26, v156, v26
	v_fma_f32 v157, v27, v157, v27
	v_mul_f32_e32 v150, 0x3fcc422a, v150
	v_mul_f32_e32 v151, 0x3fcc422a, v151
	v_mul_f32_e32 v152, 0x3fcc422a, v152
	v_mul_f32_e32 v153, 0x3fcc422a, v153
	v_mul_f32_e32 v154, 0x3fcc422a, v154
	v_mul_f32_e32 v155, 0x3fcc422a, v155
	v_mul_f32_e32 v156, 0x3fcc422a, v156
	v_mul_f32_e32 v157, 0x3fcc422a, v157
	v_mul_f32_e32 v150, 0xbfb8aa3b, v150
	v_mul_f32_e32 v151, 0xbfb8aa3b, v151
	v_mul_f32_e32 v152, 0xbfb8aa3b, v152
	v_mul_f32_e32 v153, 0xbfb8aa3b, v153
	v_mul_f32_e32 v154, 0xbfb8aa3b, v154
	v_mul_f32_e32 v155, 0xbfb8aa3b, v155
	v_mul_f32_e32 v156, 0xbfb8aa3b, v156
	v_mul_f32_e32 v157, 0xbfb8aa3b, v157
	v_exp_f32_e32 v150, v150
	v_exp_f32_e32 v151, v151
	v_exp_f32_e32 v152, v152
	v_exp_f32_e32 v153, v153
	v_exp_f32_e32 v154, v154
	v_exp_f32_e32 v155, v155
	v_exp_f32_e32 v156, v156
	v_exp_f32_e32 v157, v157
	v_add_f32_e32 v150, 1.0, v150
	v_add_f32_e32 v151, 1.0, v151
	v_add_f32_e32 v152, 1.0, v152
	v_add_f32_e32 v153, 1.0, v153
	v_add_f32_e32 v154, 1.0, v154
	v_add_f32_e32 v155, 1.0, v155
	v_add_f32_e32 v156, 1.0, v156
	v_add_f32_e32 v157, 1.0, v157
	v_rcp_f32_e32 v150, v150
	v_rcp_f32_e32 v151, v151
	v_rcp_f32_e32 v152, v152
	v_rcp_f32_e32 v153, v153
	v_rcp_f32_e32 v154, v154
	v_rcp_f32_e32 v155, v155
	v_rcp_f32_e32 v156, v156
	v_rcp_f32_e32 v157, v157
	v_mul_f32_e32 v28, v28, v150
	v_mul_f32_e32 v29, v29, v151
	v_mul_f32_e32 v30, v30, v152
	v_mul_f32_e32 v31, v31, v153
	v_mul_f32_e32 v24, v24, v154
	v_mul_f32_e32 v25, v25, v155
	v_mul_f32_e32 v26, v26, v156
	v_mul_f32_e32 v27, v27, v157
	v_mul_f32_e32 v150, 0x3d372713, v20
	v_mul_f32_e32 v151, 0x3d372713, v21
	v_mul_f32_e32 v152, 0x3d372713, v22
	v_mul_f32_e32 v153, 0x3d372713, v23
	v_mul_f32_e32 v154, 0x3d372713, v16
	v_mul_f32_e32 v155, 0x3d372713, v17
	v_mul_f32_e32 v156, 0x3d372713, v18
	v_mul_f32_e32 v157, 0x3d372713, v19
	v_mul_f32_e32 v150, v20, v150
	v_mul_f32_e32 v151, v21, v151
	v_mul_f32_e32 v152, v22, v152
	v_mul_f32_e32 v153, v23, v153
	v_mul_f32_e32 v154, v16, v154
	v_mul_f32_e32 v155, v17, v155
	v_mul_f32_e32 v156, v18, v156
	v_mul_f32_e32 v157, v19, v157
	v_fma_f32 v150, v20, v150, v20
	v_fma_f32 v151, v21, v151, v21
	v_fma_f32 v152, v22, v152, v22
	v_fma_f32 v153, v23, v153, v23
	v_fma_f32 v154, v16, v154, v16
	v_fma_f32 v155, v17, v155, v17
	v_fma_f32 v156, v18, v156, v18
	v_fma_f32 v157, v19, v157, v19
	v_mul_f32_e32 v150, 0x3fcc422a, v150
	v_mul_f32_e32 v151, 0x3fcc422a, v151
	v_mul_f32_e32 v152, 0x3fcc422a, v152
	v_mul_f32_e32 v153, 0x3fcc422a, v153
	v_mul_f32_e32 v154, 0x3fcc422a, v154
	v_mul_f32_e32 v155, 0x3fcc422a, v155
	v_mul_f32_e32 v156, 0x3fcc422a, v156
	v_mul_f32_e32 v157, 0x3fcc422a, v157
	v_mul_f32_e32 v150, 0xbfb8aa3b, v150
; __device__ __forceinline__ float gelu_f(float x) { const float u = 1.5957691216f * (x + 0.044715f * x * x * x); return x * sigmoid_f(u); }
; __device__ __forceinline__ float sigmoid_f(float x) { return __builtin_amdgcn_rcpf(1.0f + __expf(-x)); }
; __device__ __forceinline__ float silu_f(float x) { return x * sigmoid_f(x); }
;     __device__ __forceinline__ void operator()(const f32x4 (&acc)[2][2][4][2], const Unit& u, int wr, int wc, int fr, int fq) const {
;     ...
;                     for (int n = 0; n < 2; ++n)
; #pragma unroll
;                         for (int j = 0; j < 4; ++j) { const float a = acc[ai][bj][m][n][j]; v[n * 4 + j] = kind == 1 ? gelu_f(a) : (kind == 2 ? a * 0.0625f : a); }
	v_mul_f32_e32 v151, 0xbfb8aa3b, v151
	v_mul_f32_e32 v152, 0xbfb8aa3b, v152
	v_mul_f32_e32 v153, 0xbfb8aa3b, v153
	v_mul_f32_e32 v154, 0xbfb8aa3b, v154
	v_mul_f32_e32 v155, 0xbfb8aa3b, v155
	v_mul_f32_e32 v156, 0xbfb8aa3b, v156
	v_mul_f32_e32 v157, 0xbfb8aa3b, v157
	v_exp_f32_e32 v150, v150
	v_exp_f32_e32 v151, v151
	v_exp_f32_e32 v152, v152
	v_exp_f32_e32 v153, v153
	v_exp_f32_e32 v154, v154
	v_exp_f32_e32 v155, v155
	v_exp_f32_e32 v156, v156
	v_exp_f32_e32 v157, v157
	v_add_f32_e32 v150, 1.0, v150
	v_add_f32_e32 v151, 1.0, v151
	v_add_f32_e32 v152, 1.0, v152
	v_add_f32_e32 v153, 1.0, v153
	v_add_f32_e32 v154, 1.0, v154
	v_add_f32_e32 v155, 1.0, v155
	v_add_f32_e32 v156, 1.0, v156
	v_add_f32_e32 v157, 1.0, v157
	v_rcp_f32_e32 v150, v150
	v_rcp_f32_e32 v151, v151
	v_rcp_f32_e32 v152, v152
	v_rcp_f32_e32 v153, v153
	v_rcp_f32_e32 v154, v154
	v_rcp_f32_e32 v155, v155
	v_rcp_f32_e32 v156, v156
	v_rcp_f32_e32 v157, v157
	v_mul_f32_e32 v20, v20, v150
	v_mul_f32_e32 v21, v21, v151
	v_mul_f32_e32 v22, v22, v152
	v_mul_f32_e32 v23, v23, v153
	v_mul_f32_e32 v16, v16, v154
	v_mul_f32_e32 v17, v17, v155
	v_mul_f32_e32 v18, v18, v156
	v_mul_f32_e32 v19, v19, v157
	v_mul_f32_e32 v150, 0x3d372713, v12
	v_mul_f32_e32 v151, 0x3d372713, v13
	v_mul_f32_e32 v152, 0x3d372713, v14
	v_mul_f32_e32 v153, 0x3d372713, v15
	v_mul_f32_e32 v154, 0x3d372713, v8
	v_mul_f32_e32 v155, 0x3d372713, v9
	v_mul_f32_e32 v156, 0x3d372713, v10
	v_mul_f32_e32 v157, 0x3d372713, v11
	v_mul_f32_e32 v150, v12, v150
	v_mul_f32_e32 v151, v13, v151
	v_mul_f32_e32 v152, v14, v152
	v_mul_f32_e32 v153, v15, v153
	v_mul_f32_e32 v154, v8, v154
	v_mul_f32_e32 v155, v9, v155
	v_mul_f32_e32 v156, v10, v156
	v_mul_f32_e32 v157, v11, v157
	v_fma_f32 v150, v12, v150, v12
	v_fma_f32 v151, v13, v151, v13
	v_fma_f32 v152, v14, v152, v14
	v_fma_f32 v153, v15, v153, v15
	v_fma_f32 v154, v8, v154, v8
	v_fma_f32 v155, v9, v155, v9
	v_fma_f32 v156, v10, v156, v10
	v_fma_f32 v157, v11, v157, v11
	v_mul_f32_e32 v150, 0x3fcc422a, v150
	v_mul_f32_e32 v151, 0x3fcc422a, v151
	v_mul_f32_e32 v152, 0x3fcc422a, v152
	v_mul_f32_e32 v153, 0x3fcc422a, v153
	v_mul_f32_e32 v154, 0x3fcc422a, v154
	v_mul_f32_e32 v155, 0x3fcc422a, v155
	v_mul_f32_e32 v156, 0x3fcc422a, v156
	v_mul_f32_e32 v157, 0x3fcc422a, v157
	v_mul_f32_e32 v150, 0xbfb8aa3b, v150
	v_mul_f32_e32 v151, 0xbfb8aa3b, v151
	v_mul_f32_e32 v152, 0xbfb8aa3b, v152
	v_mul_f32_e32 v153, 0xbfb8aa3b, v153
	v_mul_f32_e32 v154, 0xbfb8aa3b, v154
	v_mul_f32_e32 v155, 0xbfb8aa3b, v155
	v_mul_f32_e32 v156, 0xbfb8aa3b, v156
	v_mul_f32_e32 v157, 0xbfb8aa3b, v157
	v_exp_f32_e32 v150, v150
	v_exp_f32_e32 v151, v151
	v_exp_f32_e32 v152, v152
	v_exp_f32_e32 v153, v153
	v_exp_f32_e32 v154, v154
	v_exp_f32_e32 v155, v155
	v_exp_f32_e32 v156, v156
	v_exp_f32_e32 v157, v157
	v_add_f32_e32 v150, 1.0, v150
	v_add_f32_e32 v151, 1.0, v151
	v_add_f32_e32 v152, 1.0, v152
	v_add_f32_e32 v153, 1.0, v153
	v_add_f32_e32 v154, 1.0, v154
	v_add_f32_e32 v155, 1.0, v155
	v_add_f32_e32 v156, 1.0, v156
	v_add_f32_e32 v157, 1.0, v157
	v_rcp_f32_e32 v150, v150
	v_rcp_f32_e32 v151, v151
	v_rcp_f32_e32 v152, v152
	v_rcp_f32_e32 v153, v153
	v_rcp_f32_e32 v154, v154
	v_rcp_f32_e32 v155, v155
	v_rcp_f32_e32 v156, v156
	v_rcp_f32_e32 v157, v157
	v_mul_f32_e32 v12, v12, v150
	v_mul_f32_e32 v13, v13, v151
	v_mul_f32_e32 v14, v14, v152
	v_mul_f32_e32 v15, v15, v153
	v_mul_f32_e32 v8, v8, v154
	v_mul_f32_e32 v9, v9, v155
	v_mul_f32_e32 v10, v10, v156
	v_mul_f32_e32 v11, v11, v157
	v_mul_f32_e32 v150, 0x3d372713, v4
	v_mul_f32_e32 v151, 0x3d372713, v5
	v_mul_f32_e32 v152, 0x3d372713, v6
	v_mul_f32_e32 v153, 0x3d372713, v7
	v_mul_f32_e32 v154, 0x3d372713, v0
	v_mul_f32_e32 v155, 0x3d372713, v1
	v_mul_f32_e32 v156, 0x3d372713, v2
	v_mul_f32_e32 v157, 0x3d372713, v3
	v_mul_f32_e32 v150, v4, v150
	v_mul_f32_e32 v151, v5, v151
	v_mul_f32_e32 v152, v6, v152
	v_mul_f32_e32 v153, v7, v153
	v_mul_f32_e32 v154, v0, v154
	v_mul_f32_e32 v155, v1, v155
	v_mul_f32_e32 v156, v2, v156
	v_mul_f32_e32 v157, v3, v157
	v_fma_f32 v150, v4, v150, v4
	v_fma_f32 v151, v5, v151, v5
	v_fma_f32 v152, v6, v152, v6
	v_fma_f32 v153, v7, v153, v7
	v_fma_f32 v154, v0, v154, v0
	v_fma_f32 v155, v1, v155, v1
	v_fma_f32 v156, v2, v156, v2
	v_fma_f32 v157, v3, v157, v3
	v_mul_f32_e32 v150, 0x3fcc422a, v150
	v_mul_f32_e32 v151, 0x3fcc422a, v151
	v_mul_f32_e32 v152, 0x3fcc422a, v152
	v_mul_f32_e32 v153, 0x3fcc422a, v153
	v_mul_f32_e32 v154, 0x3fcc422a, v154
	v_mul_f32_e32 v155, 0x3fcc422a, v155
	v_mul_f32_e32 v156, 0x3fcc422a, v156
	v_mul_f32_e32 v157, 0x3fcc422a, v157
	v_mul_f32_e32 v150, 0xbfb8aa3b, v150
	v_mul_f32_e32 v151, 0xbfb8aa3b, v151
	v_mul_f32_e32 v152, 0xbfb8aa3b, v152
	v_mul_f32_e32 v153, 0xbfb8aa3b, v153
	v_mul_f32_e32 v154, 0xbfb8aa3b, v154
	v_mul_f32_e32 v155, 0xbfb8aa3b, v155
	v_mul_f32_e32 v156, 0xbfb8aa3b, v156
	v_mul_f32_e32 v157, 0xbfb8aa3b, v157
	v_exp_f32_e32 v150, v150
	v_exp_f32_e32 v151, v151
	v_exp_f32_e32 v152, v152
	v_exp_f32_e32 v153, v153
	v_exp_f32_e32 v154, v154
	v_exp_f32_e32 v155, v155
	v_exp_f32_e32 v156, v156
	v_exp_f32_e32 v157, v157
	v_add_f32_e32 v150, 1.0, v150
	v_add_f32_e32 v151, 1.0, v151
	v_add_f32_e32 v152, 1.0, v152
	v_add_f32_e32 v153, 1.0, v153
	v_add_f32_e32 v154, 1.0, v154
	v_add_f32_e32 v155, 1.0, v155
	v_add_f32_e32 v156, 1.0, v156
	v_add_f32_e32 v157, 1.0, v157
	v_rcp_f32_e32 v150, v150
	v_rcp_f32_e32 v151, v151
	v_rcp_f32_e32 v152, v152
	v_rcp_f32_e32 v153, v153
	v_rcp_f32_e32 v154, v154
	v_rcp_f32_e32 v155, v155
	v_rcp_f32_e32 v156, v156
	v_rcp_f32_e32 v157, v157
	v_mul_f32_e32 v4, v4, v150
	v_mul_f32_e32 v5, v5, v151
	v_mul_f32_e32 v6, v6, v152
	v_mul_f32_e32 v7, v7, v153
	v_mul_f32_e32 v0, v0, v154
	v_mul_f32_e32 v1, v1, v155
	v_mul_f32_e32 v2, v2, v156
	v_mul_f32_e32 v3, v3, v157
; __device__ __forceinline__ unsigned cvt_pk_bf16(float lo, float hi) { f32x2 v = {lo, hi}; bf16x2_t b = __builtin_convertvector(v, bf16x2_t); return __builtin_bit_cast(unsigned, b); }
; __device__ __forceinline__ float gelu_f(float x) { const float u = 1.5957691216f * (x + 0.044715f * x * x * x); return x * sigmoid_f(u); }
;     __device__ __forceinline__ void operator()(const f32x4 (&acc)[2][2][4][2], const Unit& u, int wr, int wc, int fr, int fq) const {
;     ...
;         for (int ai = 0; ai < 2; ++ai)
; #pragma unroll
;             for (int m = 0; m < 4; ++m) {
;                 bf16_t* rowp = O + (size_t)(row0 + ai * HALF + m * 16) * ldo + col0;
; #pragma unroll
;                 for (int bj = 0; bj < 2; ++bj) {
;                     float v[8];
; #pragma unroll
;                     for (int n = 0; n < 2; ++n)
; #pragma unroll
;                         for (int j = 0; j < 4; ++j) { const float a = acc[ai][bj][m][n][j]; v[n * 4 + j] = kind == 1 ? gelu_f(a) : (kind == 2 ? a * 0.0625f : a); }
;                     u32x4 w; w.x = cvt_pk_bf16(v[0], v[1]); w.y = cvt_pk_bf16(v[2], v[3]); w.z = cvt_pk_bf16(v[4], v[5]); w.w = cvt_pk_bf16(v[6], v[7]);
;                     *(u32x4*)(rowp + bj * HALF) = w;
;                 }
.Lmy_p4_store:
	v_lshl_add_u32 v150, s46, 8, v144
	v_lshl_or_b32 v151, s48, 8, v146
	v_mov_b32_e32 v153, 0
	v_lshlrev_b32_e32 v150, 13, v150
	v_lshl_add_u32 v150, v151, 1, v150
	v_mov_b32_e32 v152, v150
	v_cvt_pk_bf16_f32 v156, v124, v125
	v_cvt_pk_bf16_f32 v157, v126, v127
	v_cvt_pk_bf16_f32 v158, v120, v121
	v_cvt_pk_bf16_f32 v159, v122, v123
	v_cvt_pk_bf16_f32 v160, v116, v117
	v_cvt_pk_bf16_f32 v161, v118, v119
	v_cvt_pk_bf16_f32 v162, v112, v113
	v_cvt_pk_bf16_f32 v163, v114, v115
	v_lshl_add_u64 v[154:155], s[14:15], 0, v[152:153]
	global_store_dwordx4 v[154:155], v[156:159], off
	global_store_dwordx4 v[154:155], v[160:163], off offset:256
	v_add_u32_e32 v152, 0x20000, v150
	v_cvt_pk_bf16_f32 v176, v108, v109
	v_cvt_pk_bf16_f32 v177, v110, v111
	v_cvt_pk_bf16_f32 v178, v104, v105
	v_cvt_pk_bf16_f32 v179, v106, v107
	v_cvt_pk_bf16_f32 v180, v100, v101
	v_cvt_pk_bf16_f32 v181, v102, v103
	v_cvt_pk_bf16_f32 v182, v96, v97
	v_cvt_pk_bf16_f32 v183, v98, v99
	v_lshl_add_u64 v[174:175], s[14:15], 0, v[152:153]
	global_store_dwordx4 v[174:175], v[176:179], off
	global_store_dwordx4 v[174:175], v[180:183], off offset:256
	v_add_u32_e32 v152, 0x40000, v150
	v_cvt_pk_bf16_f32 v186, v92, v93
	v_cvt_pk_bf16_f32 v187, v94, v95
	v_cvt_pk_bf16_f32 v188, v88, v89
	v_cvt_pk_bf16_f32 v189, v90, v91
	v_cvt_pk_bf16_f32 v190, v84, v85
	v_cvt_pk_bf16_f32 v191, v86, v87
	v_cvt_pk_bf16_f32 v192, v80, v81
	v_cvt_pk_bf16_f32 v193, v82, v83
	v_lshl_add_u64 v[184:185], s[14:15], 0, v[152:153]
	global_store_dwordx4 v[184:185], v[186:189], off
	global_store_dwordx4 v[184:185], v[190:193], off offset:256
	v_add_u32_e32 v152, 0x60000, v150
	v_cvt_pk_bf16_f32 v208, v76, v77
	v_cvt_pk_bf16_f32 v209, v78, v79
	v_cvt_pk_bf16_f32 v210, v72, v73
	v_cvt_pk_bf16_f32 v211, v74, v75
	v_cvt_pk_bf16_f32 v212, v68, v69
	v_cvt_pk_bf16_f32 v213, v70, v71
	v_cvt_pk_bf16_f32 v214, v64, v65
	v_cvt_pk_bf16_f32 v215, v66, v67
	v_lshl_add_u64 v[206:207], s[14:15], 0, v[152:153]
	global_store_dwordx4 v[206:207], v[208:211], off
	global_store_dwordx4 v[206:207], v[212:215], off offset:256
	v_add_u32_e32 v152, 0x100000, v150
	v_cvt_pk_bf16_f32 v156, v60, v61
	v_cvt_pk_bf16_f32 v157, v62, v63
	v_cvt_pk_bf16_f32 v158, v56, v57
	v_cvt_pk_bf16_f32 v159, v58, v59
	v_cvt_pk_bf16_f32 v160, v52, v53
	v_cvt_pk_bf16_f32 v161, v54, v55
	v_cvt_pk_bf16_f32 v162, v48, v49
	v_cvt_pk_bf16_f32 v163, v50, v51
	v_lshl_add_u64 v[154:155], s[14:15], 0, v[152:153]
	global_store_dwordx4 v[154:155], v[156:159], off
	global_store_dwordx4 v[154:155], v[160:163], off offset:256
	v_add_u32_e32 v152, 0x120000, v150
	v_cvt_pk_bf16_f32 v176, v44, v45
	v_cvt_pk_bf16_f32 v177, v46, v47
	v_cvt_pk_bf16_f32 v178, v40, v41
	v_cvt_pk_bf16_f32 v179, v42, v43
	v_cvt_pk_bf16_f32 v180, v36, v37
	v_cvt_pk_bf16_f32 v181, v38, v39
	v_cvt_pk_bf16_f32 v182, v32, v33
	v_cvt_pk_bf16_f32 v183, v34, v35
	v_lshl_add_u64 v[174:175], s[14:15], 0, v[152:153]
	global_store_dwordx4 v[174:175], v[176:179], off
	global_store_dwordx4 v[174:175], v[180:183], off offset:256
	v_add_u32_e32 v152, 0x140000, v150
	v_cvt_pk_bf16_f32 v186, v28, v29
	v_cvt_pk_bf16_f32 v187, v30, v31
	v_cvt_pk_bf16_f32 v188, v24, v25
	v_cvt_pk_bf16_f32 v189, v26, v27
	v_cvt_pk_bf16_f32 v190, v20, v21
	v_cvt_pk_bf16_f32 v191, v22, v23
	v_cvt_pk_bf16_f32 v192, v16, v17
	v_cvt_pk_bf16_f32 v193, v18, v19
	v_lshl_add_u64 v[184:185], s[14:15], 0, v[152:153]
	global_store_dwordx4 v[184:185], v[186:189], off
	global_store_dwordx4 v[184:185], v[190:193], off offset:256
	v_add_u32_e32 v152, 0x160000, v150
	v_cvt_pk_bf16_f32 v208, v12, v13
	v_cvt_pk_bf16_f32 v209, v14, v15
	v_cvt_pk_bf16_f32 v210, v8, v9
	v_cvt_pk_bf16_f32 v211, v10, v11
	v_cvt_pk_bf16_f32 v212, v4, v5
	v_cvt_pk_bf16_f32 v213, v6, v7
	v_cvt_pk_bf16_f32 v214, v0, v1
	v_cvt_pk_bf16_f32 v215, v2, v3
	v_lshl_add_u64 v[206:207], s[14:15], 0, v[152:153]
	global_store_dwordx4 v[206:207], v[208:211], off
	global_store_dwordx4 v[206:207], v[212:215], off offset:256
	s_branch .Lmy_p4_latch

; template <class Epi, class Sched>
; __device__ __forceinline__ void gemm_phase(LAS unsigned char* lds, const Gemm g, const Sched& S, const Epi& E) {
;     ...
;         E(acc, cur, wr, wc, fr, fq);
;         if (!has_next) break;
; #pragma unroll
;         for (int a = 0; a < 2; ++a)
; #pragma unroll
;             for (int b = 0; b < 2; ++b)
; #pragma unroll
;                 for (int m = 0; m < 4; ++m)
; #pragma unroll
;                     for (int n = 0; n < 2; ++n) acc[a][b][m][n] = (f32x4){0.f, 0.f, 0.f, 0.f};
;         cur = nxt; cA = nA; cB = nB; ++ui;
.Lmy_p9_latch:
	s_and_b64 vcc, exec, s[14:15]
	s_mov_b32 s8, s18
	s_mov_b32 s10, s16
	s_mov_b64 s[36:37], s[30:31]
	s_mov_b64 s[34:35], s[28:29]
	s_cbranch_vccnz .LBB0_1357

; #define PG8_STAGE(bufoff, gbase, voff) do { _Pragma("unroll") for (int _i = 0; _i < 2; ++_i) \
;         __builtin_amdgcn_global_load_lds((const unsigned*)((const char*)(gbase) + (voff)[_i]), (LAS unsigned*)(lds + (bufoff) + ldsw + _i * 8192), 16, 0, 0); } while (0)
; #define PG8_LDA(dst, b, h) do { _Pragma("unroll") for (int m = 0; m < 4; ++m) _Pragma("unroll") for (int k = 0; k < 2; ++k) dst[m][k] = *(const LAS bf16x8*)(lds + PG8_SA(b, h) + aoff + m * 2048 + k * 1024); } while (0)
; #define PG8_LDB(dst, b, h) do { _Pragma("unroll") for (int n = 0; n < 2; ++n) _Pragma("unroll") for (int k = 0; k < 2; ++k) dst[n][k] = *(const LAS bf16x8*)(lds + PG8_SB(b, h) + boff + n * 2048 + k * 1024); } while (0)
; #define PG8_MMA(ai, bj, At, Bt) do { __builtin_amdgcn_s_setprio(1); _Pragma("unroll") for (int m = 0; m < 4; ++m) _Pragma("unroll") for (int n = 0; n < 2; ++n) _Pragma("unroll") for (int k = 0; k < 2; ++k) \
;         acc[ai][bj][m][n] = __builtin_amdgcn_mfma_f32_16x16x32_bf16(Bt[n][k], At[m][k], acc[ai][bj][m][n], 0, 0, 0); __builtin_amdgcn_s_setprio(0); } while (0)
; #define PG8_WAIT_L(n) asm volatile("s_waitcnt lgkmcnt(" #n ")" ::: "memory")
; #define PG8_BAR __builtin_amdgcn_s_barrier()
; #define PG8_SCHED __builtin_amdgcn_sched_barrier(0)
; template <class Epi, class Sched>
; __device__ __forceinline__ void gemm_phase(LAS unsigned char* lds, const Gemm g, const Sched& S, const Epi& E) {
;     ...
;         for (int t = 0; t < nt; t += 2) {
;             const bool last = (t == nt - 2);
;             const char* a1 = cA + (size_t)(t + 1) * kstep;
;             const char* a2 = last ? nA : cA + (size_t)(t + 2) * kstep; const char* b2 = last ? nB : cB + (size_t)(t + 2) * kstep;
;             const char* a3 = a2 + kstep; const char* b3 = b2 + kstep;
;             PG8_LDB(B0, 0, 0); PG8_SCHED; PG8_LDA(At, 0, 0); PG8_STAGE(PG8_SA(1, 1), a1 + hstep, voffA);
;             PG8_WAIT_L(8); PG8_BAR; PG8_WAIT_L(0); PG8_MMA(0, 0, At, B0); PG8_BAR; PG8_SCHED;
;             PG8_LDB(B1, 0, 1); PG8_STAGE(PG8_SB(0, 0), b2, voffB);
;             PG8_BAR; PG8_WAIT_L(0); PG8_MMA(0, 1, At, B1); PG8_BAR;
;             PG8_LDA(At, 0, 1); PG8_STAGE(PG8_SA(0, 0), a2, voffA);
;             PG8_BAR; PG8_WAIT_L(0); PG8_MMA(1, 0, At, B0); PG8_BAR; PG8_SCHED;
.LBB0_1322:
	ds_read_b128 v[128:131], v189
	ds_read_b128 v[132:135], v189 offset:1024
	ds_read_b128 v[136:139], v189 offset:2048
	ds_read_b128 v[140:143], v189 offset:3072
	s_add_u32 s36, s34, 0x4000
	s_addc_u32 s37, s35, 0
	s_cmp_eq_u32 s61, 28
	s_cselect_b32 s40, s17, s36
	s_cselect_b32 s41, s9, s37
	s_cselect_b32 s36, s33, s59
	s_cselect_b32 s37, s19, s60
	s_add_u32 s38, s40, 0x8000
	s_addc_u32 s39, s41, 0
	v_lshl_add_u64 v[196:197], s[34:35], 0, v[170:171]
	s_add_i32 m0, s47, 0xc000
	ds_read_b128 v[144:147], v190
	ds_read_b128 v[148:151], v190 offset:1024
	ds_read_b128 v[152:155], v190 offset:2048
	ds_read_b128 v[156:159], v190 offset:3072
	ds_read_b128 v[174:177], v190 offset:4096
	ds_read_b128 v[178:181], v190 offset:5120
	ds_read_b128 v[182:185], v190 offset:6144
	ds_read_b128 v[192:195], v190 offset:7168
	global_load_lds_dwordx4 v[196:197], off
	v_lshl_add_u64 v[196:197], s[34:35], 0, v[172:173]
	s_add_i32 m0, s47, 0xe000
	s_nop 0
	global_load_lds_dwordx4 v[196:197], off
	s_waitcnt lgkmcnt(8)
	s_barrier
	s_waitcnt lgkmcnt(0)
	s_setprio 1
	s_waitcnt lgkmcnt(0)
	v_mfma_f32_16x16x32_bf16 v[124:127], v[128:131], v[144:147], v[124:127]
	v_mfma_f32_16x16x32_bf16 v[120:123], v[136:139], v[144:147], v[120:123]
	v_mfma_f32_16x16x32_bf16 v[108:111], v[128:131], v[152:155], v[108:111]
	v_mfma_f32_16x16x32_bf16 v[104:107], v[136:139], v[152:155], v[104:107]
	v_mfma_f32_16x16x32_bf16 v[92:95], v[128:131], v[174:177], v[92:95]
	v_mfma_f32_16x16x32_bf16 v[88:91], v[136:139], v[174:177], v[88:91]
	v_mfma_f32_16x16x32_bf16 v[76:79], v[128:131], v[182:185], v[76:79]
	v_mfma_f32_16x16x32_bf16 v[72:75], v[136:139], v[182:185], v[72:75]
	v_mfma_f32_16x16x32_bf16 v[124:127], v[132:135], v[148:151], v[124:127]
	v_mfma_f32_16x16x32_bf16 v[120:123], v[140:143], v[148:151], v[120:123]
	v_mfma_f32_16x16x32_bf16 v[108:111], v[132:135], v[156:159], v[108:111]
	v_mfma_f32_16x16x32_bf16 v[104:107], v[140:143], v[156:159], v[104:107]
	v_mfma_f32_16x16x32_bf16 v[92:95], v[132:135], v[178:181], v[92:95]
	v_mfma_f32_16x16x32_bf16 v[88:91], v[140:143], v[178:181], v[88:91]
	v_mfma_f32_16x16x32_bf16 v[76:79], v[132:135], v[192:195], v[76:79]
	v_mfma_f32_16x16x32_bf16 v[72:75], v[140:143], v[192:195], v[72:75]
	s_setprio 0
	s_barrier
	s_add_i32 s62, s71, s46
	v_lshl_add_u64 v[214:215], s[36:37], 0, v[162:163]
	s_mov_b32 m0, s62
	ds_read_b128 v[196:199], v191
	ds_read_b128 v[200:203], v191 offset:1024
	ds_read_b128 v[206:209], v191 offset:2048
	ds_read_b128 v[210:213], v191 offset:3072
	global_load_lds_dwordx4 v[214:215], off
	v_lshl_add_u64 v[214:215], s[36:37], 0, v[166:167]
	s_add_i32 m0, s62, 0x2000
	s_nop 0
	global_load_lds_dwordx4 v[214:215], off
	s_barrier
	s_waitcnt lgkmcnt(0)
	s_setprio 1
	s_waitcnt lgkmcnt(0)
	v_mfma_f32_16x16x32_bf16 v[116:119], v[196:199], v[144:147], v[116:119]
	v_mfma_f32_16x16x32_bf16 v[112:115], v[206:209], v[144:147], v[112:115]
	v_mfma_f32_16x16x32_bf16 v[100:103], v[196:199], v[152:155], v[100:103]
	v_mfma_f32_16x16x32_bf16 v[96:99], v[206:209], v[152:155], v[96:99]
	v_mfma_f32_16x16x32_bf16 v[84:87], v[196:199], v[174:177], v[84:87]
	v_mfma_f32_16x16x32_bf16 v[80:83], v[206:209], v[174:177], v[80:83]
	v_mfma_f32_16x16x32_bf16 v[68:71], v[196:199], v[182:185], v[68:71]
	v_mfma_f32_16x16x32_bf16 v[64:67], v[206:209], v[182:185], v[64:67]
	v_mfma_f32_16x16x32_bf16 v[116:119], v[200:203], v[148:151], v[116:119]
	v_mfma_f32_16x16x32_bf16 v[112:115], v[210:213], v[148:151], v[112:115]
	v_mfma_f32_16x16x32_bf16 v[100:103], v[200:203], v[156:159], v[100:103]
	v_mfma_f32_16x16x32_bf16 v[96:99], v[210:213], v[156:159], v[96:99]
	v_mfma_f32_16x16x32_bf16 v[84:87], v[200:203], v[178:181], v[84:87]
	v_mfma_f32_16x16x32_bf16 v[80:83], v[210:213], v[178:181], v[80:83]
	v_mfma_f32_16x16x32_bf16 v[68:71], v[200:203], v[192:195], v[68:71]
	v_mfma_f32_16x16x32_bf16 v[64:67], v[210:213], v[192:195], v[64:67]
	s_setprio 0
	s_mov_b32 m0, s47
	v_lshl_add_u64 v[214:215], s[40:41], 0, v[160:161]
	s_barrier
	ds_read_b128 v[144:147], v190 offset:16384
	ds_read_b128 v[148:151], v190 offset:17408
	ds_read_b128 v[152:155], v190 offset:18432
	ds_read_b128 v[156:159], v190 offset:19456
	ds_read_b128 v[174:177], v190 offset:20480
	ds_read_b128 v[178:181], v190 offset:21504
	ds_read_b128 v[182:185], v190 offset:22528
	ds_read_b128 v[192:195], v190 offset:23552
	global_load_lds_dwordx4 v[214:215], off
	v_lshl_add_u64 v[214:215], s[40:41], 0, v[164:165]
	s_mov_b32 m0, s48
	s_nop 0
	global_load_lds_dwordx4 v[214:215], off
	s_barrier
	s_waitcnt lgkmcnt(0)
	s_setprio 1
	s_waitcnt lgkmcnt(0)
	v_mfma_f32_16x16x32_bf16 v[60:63], v[128:131], v[144:147], v[60:63]
	v_mfma_f32_16x16x32_bf16 v[56:59], v[136:139], v[144:147], v[56:59]
	v_mfma_f32_16x16x32_bf16 v[44:47], v[128:131], v[152:155], v[44:47]
	v_mfma_f32_16x16x32_bf16 v[40:43], v[136:139], v[152:155], v[40:43]
	v_mfma_f32_16x16x32_bf16 v[28:31], v[128:131], v[174:177], v[28:31]
	v_mfma_f32_16x16x32_bf16 v[24:27], v[136:139], v[174:177], v[24:27]
	v_mfma_f32_16x16x32_bf16 v[12:15], v[128:131], v[182:185], v[12:15]
	v_mfma_f32_16x16x32_bf16 v[8:11], v[136:139], v[182:185], v[8:11]
	v_mfma_f32_16x16x32_bf16 v[60:63], v[132:135], v[148:151], v[60:63]
	v_mfma_f32_16x16x32_bf16 v[56:59], v[140:143], v[148:151], v[56:59]
	v_mfma_f32_16x16x32_bf16 v[44:47], v[132:135], v[156:159], v[44:47]
	v_mfma_f32_16x16x32_bf16 v[40:43], v[140:143], v[156:159], v[40:43]
	v_mfma_f32_16x16x32_bf16 v[28:31], v[132:135], v[178:181], v[28:31]
	v_mfma_f32_16x16x32_bf16 v[24:27], v[140:143], v[178:181], v[24:27]
	v_mfma_f32_16x16x32_bf16 v[12:15], v[132:135], v[192:195], v[12:15]
	v_mfma_f32_16x16x32_bf16 v[8:11], v[140:143], v[192:195], v[8:11]
	s_setprio 0
	s_barrier
; #define PG8_STAGE(bufoff, gbase, voff) do { _Pragma("unroll") for (int _i = 0; _i < 2; ++_i) \
;         __builtin_amdgcn_global_load_lds((const unsigned*)((const char*)(gbase) + (voff)[_i]), (LAS unsigned*)(lds + (bufoff) + ldsw + _i * 8192), 16, 0, 0); } while (0)
; #define PG8_LDA(dst, b, h) do { _Pragma("unroll") for (int m = 0; m < 4; ++m) _Pragma("unroll") for (int k = 0; k < 2; ++k) dst[m][k] = *(const LAS bf16x8*)(lds + PG8_SA(b, h) + aoff + m * 2048 + k * 1024); } while (0)
; #define PG8_LDB(dst, b, h) do { _Pragma("unroll") for (int n = 0; n < 2; ++n) _Pragma("unroll") for (int k = 0; k < 2; ++k) dst[n][k] = *(const LAS bf16x8*)(lds + PG8_SB(b, h) + boff + n * 2048 + k * 1024); } while (0)
; #define PG8_MMA(ai, bj, At, Bt) do { __builtin_amdgcn_s_setprio(1); _Pragma("unroll") for (int m = 0; m < 4; ++m) _Pragma("unroll") for (int n = 0; n < 2; ++n) _Pragma("unroll") for (int k = 0; k < 2; ++k) \
;         acc[ai][bj][m][n] = __builtin_amdgcn_mfma_f32_16x16x32_bf16(Bt[n][k], At[m][k], acc[ai][bj][m][n], 0, 0, 0); __builtin_amdgcn_s_setprio(0); } while (0)
; #define PG8_WAIT_V(n) asm volatile("s_waitcnt vmcnt(" #n ")" ::: "memory")
; #define PG8_WAIT_L(n) asm volatile("s_waitcnt lgkmcnt(" #n ")" ::: "memory")
; #define PG8_BAR __builtin_amdgcn_s_barrier()
; #define PG8_SCHED __builtin_amdgcn_sched_barrier(0)
; template <class Epi, class Sched>
; __device__ __forceinline__ void gemm_phase(LAS unsigned char* lds, const Gemm g, const Sched& S, const Epi& E) {
;     ...
;             PG8_WAIT_V(6); PG8_BAR; PG8_MMA(1, 1, At, B1); PG8_BAR;
;             PG8_LDB(B0, 1, 0); PG8_SCHED; PG8_LDA(At, 1, 0); PG8_STAGE(PG8_SA(0, 1), a2 + hstep, voffA);
;             PG8_WAIT_L(8); PG8_BAR; PG8_WAIT_L(0); PG8_MMA(0, 0, At, B0); PG8_BAR; PG8_SCHED;
;             PG8_LDB(B1, 1, 1); PG8_STAGE(PG8_SB(1, 0), b3, voffB);
;             PG8_BAR; PG8_WAIT_L(0); PG8_MMA(0, 1, At, B1); PG8_BAR;
	s_add_u32 s62, s36, 0x4000
	s_addc_u32 s63, s37, 0
	s_add_i32 s64, s57, s46
	v_lshl_add_u64 v[128:129], s[62:63], 0, v[162:163]
	s_mov_b32 m0, s64
	s_nop 0
	global_load_lds_dwordx4 v[128:129], off
	v_lshl_add_u64 v[128:129], s[62:63], 0, v[166:167]
	s_add_i32 m0, s64, 0x2000
	s_nop 0
	global_load_lds_dwordx4 v[128:129], off
	s_waitcnt vmcnt(6)
	s_barrier
	s_setprio 1
	v_mfma_f32_16x16x32_bf16 v[52:55], v[196:199], v[144:147], v[52:55]
	v_mfma_f32_16x16x32_bf16 v[48:51], v[206:209], v[144:147], v[48:51]
	v_mfma_f32_16x16x32_bf16 v[36:39], v[196:199], v[152:155], v[36:39]
	v_mfma_f32_16x16x32_bf16 v[32:35], v[206:209], v[152:155], v[32:35]
	v_mfma_f32_16x16x32_bf16 v[20:23], v[196:199], v[174:177], v[20:23]
	v_mfma_f32_16x16x32_bf16 v[16:19], v[206:209], v[174:177], v[16:19]
	v_mfma_f32_16x16x32_bf16 v[4:7], v[196:199], v[182:185], v[4:7]
	v_mfma_f32_16x16x32_bf16 v[0:3], v[206:209], v[182:185], v[0:3]
	v_mfma_f32_16x16x32_bf16 v[52:55], v[200:203], v[148:151], v[52:55]
	v_mfma_f32_16x16x32_bf16 v[48:51], v[210:213], v[148:151], v[48:51]
	v_mfma_f32_16x16x32_bf16 v[36:39], v[200:203], v[156:159], v[36:39]
	v_mfma_f32_16x16x32_bf16 v[32:35], v[210:213], v[156:159], v[32:35]
	v_mfma_f32_16x16x32_bf16 v[20:23], v[200:203], v[178:181], v[20:23]
	v_mfma_f32_16x16x32_bf16 v[16:19], v[210:213], v[178:181], v[16:19]
	v_mfma_f32_16x16x32_bf16 v[4:7], v[200:203], v[192:195], v[4:7]
	v_mfma_f32_16x16x32_bf16 v[0:3], v[210:213], v[192:195], v[0:3]
	s_setprio 0
	s_add_i32 s62, 0, 0x18000
	v_add_u32_e32 v140, s62, v188
	s_barrier
	ds_read_b128 v[128:131], v140
	ds_read_b128 v[132:135], v140 offset:1024
	ds_read_b128 v[136:139], v140 offset:2048
	ds_read_b128 v[140:143], v140 offset:3072
	s_add_u32 s40, s40, 0x4000
	s_addc_u32 s41, s41, 0
	s_mov_b32 m0, s49
	v_lshl_add_u64 v[196:197], s[40:41], 0, v[160:161]
	ds_read_b128 v[144:147], v190 offset:32768
	ds_read_b128 v[148:151], v190 offset:33792
	ds_read_b128 v[152:155], v190 offset:34816
	ds_read_b128 v[156:159], v190 offset:35840
	ds_read_b128 v[174:177], v190 offset:36864
	ds_read_b128 v[178:181], v190 offset:37888
	ds_read_b128 v[182:185], v190 offset:38912
	ds_read_b128 v[192:195], v190 offset:39936
	global_load_lds_dwordx4 v[196:197], off
	v_lshl_add_u64 v[196:197], s[40:41], 0, v[164:165]
	s_mov_b32 m0, s50
	s_nop 0
	global_load_lds_dwordx4 v[196:197], off
	s_waitcnt lgkmcnt(8)
	s_barrier
	s_waitcnt lgkmcnt(0)
	s_setprio 1
	s_waitcnt lgkmcnt(0)
	v_mfma_f32_16x16x32_bf16 v[124:127], v[128:131], v[144:147], v[124:127]
	v_mfma_f32_16x16x32_bf16 v[120:123], v[136:139], v[144:147], v[120:123]
	v_mfma_f32_16x16x32_bf16 v[108:111], v[128:131], v[152:155], v[108:111]
	v_mfma_f32_16x16x32_bf16 v[104:107], v[136:139], v[152:155], v[104:107]
	v_mfma_f32_16x16x32_bf16 v[92:95], v[128:131], v[174:177], v[92:95]
	v_mfma_f32_16x16x32_bf16 v[88:91], v[136:139], v[174:177], v[88:91]
	v_mfma_f32_16x16x32_bf16 v[76:79], v[128:131], v[182:185], v[76:79]
	v_mfma_f32_16x16x32_bf16 v[72:75], v[136:139], v[182:185], v[72:75]
	v_mfma_f32_16x16x32_bf16 v[124:127], v[132:135], v[148:151], v[124:127]
	v_mfma_f32_16x16x32_bf16 v[120:123], v[140:143], v[148:151], v[120:123]
	v_mfma_f32_16x16x32_bf16 v[108:111], v[132:135], v[156:159], v[108:111]
	v_mfma_f32_16x16x32_bf16 v[104:107], v[140:143], v[156:159], v[104:107]
	v_mfma_f32_16x16x32_bf16 v[92:95], v[132:135], v[178:181], v[92:95]
	v_mfma_f32_16x16x32_bf16 v[88:91], v[140:143], v[178:181], v[88:91]
	v_mfma_f32_16x16x32_bf16 v[76:79], v[132:135], v[192:195], v[76:79]
	v_mfma_f32_16x16x32_bf16 v[72:75], v[140:143], v[192:195], v[72:75]
	s_setprio 0
	s_barrier
	s_add_i32 s63, 0, 0x1c000
	s_add_u32 s40, s36, 0x8000
	s_addc_u32 s41, s37, 0
	s_add_i32 s62, s62, s46
	v_add_u32_e32 v168, s63, v188
	v_lshl_add_u64 v[214:215], s[40:41], 0, v[162:163]
	s_mov_b32 m0, s62
	ds_read_b128 v[196:199], v168
	ds_read_b128 v[200:203], v168 offset:1024
	ds_read_b128 v[206:209], v168 offset:2048
	ds_read_b128 v[210:213], v168 offset:3072
	global_load_lds_dwordx4 v[214:215], off
	v_lshl_add_u64 v[214:215], s[40:41], 0, v[166:167]
	s_add_i32 m0, s62, 0x2000
	s_nop 0
	global_load_lds_dwordx4 v[214:215], off
	s_barrier
	s_waitcnt lgkmcnt(0)
	s_setprio 1
	s_waitcnt lgkmcnt(0)
	v_mfma_f32_16x16x32_bf16 v[116:119], v[196:199], v[144:147], v[116:119]
	v_mfma_f32_16x16x32_bf16 v[112:115], v[206:209], v[144:147], v[112:115]
	v_mfma_f32_16x16x32_bf16 v[100:103], v[196:199], v[152:155], v[100:103]
	v_mfma_f32_16x16x32_bf16 v[96:99], v[206:209], v[152:155], v[96:99]
	v_mfma_f32_16x16x32_bf16 v[84:87], v[196:199], v[174:177], v[84:87]
	v_mfma_f32_16x16x32_bf16 v[80:83], v[206:209], v[174:177], v[80:83]
	v_mfma_f32_16x16x32_bf16 v[68:71], v[196:199], v[182:185], v[68:71]
	v_mfma_f32_16x16x32_bf16 v[64:67], v[206:209], v[182:185], v[64:67]
	v_mfma_f32_16x16x32_bf16 v[116:119], v[200:203], v[148:151], v[116:119]
	v_mfma_f32_16x16x32_bf16 v[112:115], v[210:213], v[148:151], v[112:115]
	v_mfma_f32_16x16x32_bf16 v[100:103], v[200:203], v[156:159], v[100:103]
	v_mfma_f32_16x16x32_bf16 v[96:99], v[210:213], v[156:159], v[96:99]
	v_mfma_f32_16x16x32_bf16 v[84:87], v[200:203], v[178:181], v[84:87]
	v_mfma_f32_16x16x32_bf16 v[80:83], v[210:213], v[178:181], v[80:83]
	v_mfma_f32_16x16x32_bf16 v[68:71], v[200:203], v[192:195], v[68:71]
	v_mfma_f32_16x16x32_bf16 v[64:67], v[210:213], v[192:195], v[64:67]
	s_setprio 0
	s_mov_b32 m0, s55
	v_lshl_add_u64 v[214:215], s[38:39], 0, v[160:161]
	s_barrier
; __device__ __forceinline__ size_t tl(int r, int c, int K) { return ((size_t)(r >> 8) * (size_t)(K >> 6) + (size_t)(c >> 6)) * 16384 + (size_t)((r & 255) << 6) + (size_t)(c & 63); }
; #define PG8_STAGE(bufoff, gbase, voff) do { _Pragma("unroll") for (int _i = 0; _i < 2; ++_i) \
;         __builtin_amdgcn_global_load_lds((const unsigned*)((const char*)(gbase) + (voff)[_i]), (LAS unsigned*)(lds + (bufoff) + ldsw + _i * 8192), 16, 0, 0); } while (0)
; #define PG8_LDA(dst, b, h) do { _Pragma("unroll") for (int m = 0; m < 4; ++m) _Pragma("unroll") for (int k = 0; k < 2; ++k) dst[m][k] = *(const LAS bf16x8*)(lds + PG8_SA(b, h) + aoff + m * 2048 + k * 1024); } while (0)
; #define PG8_WAIT_V(n) asm volatile("s_waitcnt vmcnt(" #n ")" ::: "memory")
; #define PG8_WAIT_L(n) asm volatile("s_waitcnt lgkmcnt(" #n ")" ::: "memory")
; template <class Epi, class Sched>
; __device__ __forceinline__ void gemm_phase(LAS unsigned char* lds, const Gemm g, const Sched& S, const Epi& E) {
;     ...
;             PG8_LDA(At, 1, 1); PG8_STAGE(PG8_SA(1, 0), a3, voffA);
;             PG8_BAR; PG8_WAIT_L(0); PG8_MMA(1, 0, At, B0); PG8_BAR; PG8_SCHED;
;             PG8_STAGE(PG8_SB(1, 1), b3 + hstep, voffB);
;             PG8_WAIT_V(6); PG8_BAR; PG8_MMA(1, 1, At, B1); PG8_BAR;
;         }
;     __device__ __forceinline__ void operator()(const f32x4 (&acc)[2][2][4][2], const Unit& u, int wr, int wc, int fr, int fq) const {
;         const int br = u.pn >> 3, pn8 = u.pn & 7;
;         const bf16_t* y = y0 + (long)(br == 1) * d1 + (long)(br == 2) * d2;
;         const int row0 = u.pm * BM + wr * 64 + fr, col0 = pn8 * BM + wc * 32 + 8 * fq;
; #pragma unroll
;         for (int ai = 0; ai < 2; ++ai)
; #pragma unroll
;             for (int mh = 0; mh < 2; ++mh) {
;                 u32x4 yw[2][2], mw[2][2];
; #pragma unroll
;                 for (int mm = 0; mm < 2; ++mm) {
;                     const int rr = row0 + ai * HALF + (mh * 2 + mm) * 16;
;                     const size_t off = (size_t)rr * DM + col0;
; #pragma unroll
;                     for (int bj = 0; bj < 2; ++bj) {
;                         yw[mm][bj] = *(const u32x4*)(y + off + bj * HALF);
;                         mw[mm][bj] = (u32x4){0u, 0u, 0u, 0u};
;                         if (br != 0) mw[mm][bj] = *(const u32x4*)(merged + tl(rr, col0 + bj * HALF, DM));
;                     }
;                 }
	ds_read_b128 v[144:147], v190 offset:49152
	ds_read_b128 v[148:151], v190 offset:50176
	ds_read_b128 v[152:155], v190 offset:51200
	ds_read_b128 v[156:159], v190 offset:52224
	ds_read_b128 v[174:177], v190 offset:53248
	ds_read_b128 v[178:181], v190 offset:54272
	ds_read_b128 v[182:185], v190 offset:55296
	ds_read_b128 v[192:195], v190 offset:56320
	global_load_lds_dwordx4 v[214:215], off
	v_lshl_add_u64 v[214:215], s[38:39], 0, v[164:165]
	s_mov_b32 m0, s56
	s_nop 0
	global_load_lds_dwordx4 v[214:215], off
	s_barrier
	s_waitcnt lgkmcnt(0)
	s_setprio 1
	s_waitcnt lgkmcnt(0)
	v_mfma_f32_16x16x32_bf16 v[60:63], v[128:131], v[144:147], v[60:63]
	v_mfma_f32_16x16x32_bf16 v[56:59], v[136:139], v[144:147], v[56:59]
	v_mfma_f32_16x16x32_bf16 v[44:47], v[128:131], v[152:155], v[44:47]
	v_mfma_f32_16x16x32_bf16 v[40:43], v[136:139], v[152:155], v[40:43]
	v_mfma_f32_16x16x32_bf16 v[28:31], v[128:131], v[174:177], v[28:31]
	v_mfma_f32_16x16x32_bf16 v[24:27], v[136:139], v[174:177], v[24:27]
	v_mfma_f32_16x16x32_bf16 v[12:15], v[128:131], v[182:185], v[12:15]
	v_mfma_f32_16x16x32_bf16 v[8:11], v[136:139], v[182:185], v[8:11]
	v_mfma_f32_16x16x32_bf16 v[60:63], v[132:135], v[148:151], v[60:63]
	v_mfma_f32_16x16x32_bf16 v[56:59], v[140:143], v[148:151], v[56:59]
	v_mfma_f32_16x16x32_bf16 v[44:47], v[132:135], v[156:159], v[44:47]
	v_mfma_f32_16x16x32_bf16 v[40:43], v[140:143], v[156:159], v[40:43]
	v_mfma_f32_16x16x32_bf16 v[28:31], v[132:135], v[178:181], v[28:31]
	v_mfma_f32_16x16x32_bf16 v[24:27], v[140:143], v[178:181], v[24:27]
	v_mfma_f32_16x16x32_bf16 v[12:15], v[132:135], v[192:195], v[12:15]
	v_mfma_f32_16x16x32_bf16 v[8:11], v[140:143], v[192:195], v[8:11]
	s_setprio 0
	s_barrier
	s_add_u32 s36, s36, 0xc000
	s_addc_u32 s37, s37, 0
	s_add_i32 s38, s63, s46
	v_lshl_add_u64 v[128:129], s[36:37], 0, v[162:163]
	s_mov_b32 m0, s38
	s_nop 0
	global_load_lds_dwordx4 v[128:129], off
	v_lshl_add_u64 v[128:129], s[36:37], 0, v[166:167]
	s_add_i32 m0, s38, 0x2000
	s_nop 0
	global_load_lds_dwordx4 v[128:129], off
	s_waitcnt vmcnt(6)
	s_barrier
	s_setprio 1
	v_mfma_f32_16x16x32_bf16 v[52:55], v[196:199], v[144:147], v[52:55]
	v_mfma_f32_16x16x32_bf16 v[48:51], v[206:209], v[144:147], v[48:51]
	v_mfma_f32_16x16x32_bf16 v[36:39], v[196:199], v[152:155], v[36:39]
	v_mfma_f32_16x16x32_bf16 v[32:35], v[206:209], v[152:155], v[32:35]
	v_mfma_f32_16x16x32_bf16 v[20:23], v[196:199], v[174:177], v[20:23]
	v_mfma_f32_16x16x32_bf16 v[16:19], v[206:209], v[174:177], v[16:19]
	v_mfma_f32_16x16x32_bf16 v[4:7], v[196:199], v[182:185], v[4:7]
	v_mfma_f32_16x16x32_bf16 v[0:3], v[206:209], v[182:185], v[0:3]
	v_mfma_f32_16x16x32_bf16 v[52:55], v[200:203], v[148:151], v[52:55]
	v_mfma_f32_16x16x32_bf16 v[48:51], v[210:213], v[148:151], v[48:51]
	v_mfma_f32_16x16x32_bf16 v[36:39], v[200:203], v[156:159], v[36:39]
	v_mfma_f32_16x16x32_bf16 v[32:35], v[210:213], v[156:159], v[32:35]
	v_mfma_f32_16x16x32_bf16 v[20:23], v[200:203], v[178:181], v[20:23]
	v_mfma_f32_16x16x32_bf16 v[16:19], v[210:213], v[178:181], v[16:19]
	v_mfma_f32_16x16x32_bf16 v[4:7], v[200:203], v[192:195], v[4:7]
	v_mfma_f32_16x16x32_bf16 v[0:3], v[210:213], v[192:195], v[0:3]
	s_setprio 0
	s_add_i32 s61, s61, 2
	s_add_u32 s34, s34, 0x10000
	s_addc_u32 s35, s35, 0
	s_add_u32 s59, s59, 0x10000
	s_addc_u32 s60, s60, 0
	s_cmp_gt_u32 s61, 29
	s_barrier
	s_cbranch_scc0 .LBB0_1322
	s_nop 7
	s_ashr_i32 s9, s8, 3
	s_cmp_eq_u32 s9, 1
	s_cselect_b32 s17, 0x4000000, 0
	s_add_u32 s17, s51, s17
	s_addc_u32 s19, s52, 0
	s_cmp_eq_u32 s9, 2
	s_cselect_b32 s38, 0xac00000, 0
	s_add_u32 s34, s17, s38
	s_addc_u32 s35, s19, 0
	s_lshl_b32 s36, s10, 8
	s_add_i32 s36, s36, s53
	s_lshl_b32 s37, s8, 8
	s_and_b32 s37, s37, 0x700
	s_or_b32 s37, s37, s54
	v_or_b32_e32 v174, s36, v186
	v_or_b32_e32 v175, s37, v187
	v_lshlrev_b32_e32 v176, 12, v174
	v_lshl_add_u32 v176, v175, 1, v176
	v_lshrrev_b32_e32 v177, 6, v175
	v_lshl_add_u32 v177, s10, 5, v177
	v_lshlrev_b32_e32 v177, 14, v177
	v_and_b32_e32 v198, 0xff, v174
	v_lshl_add_u32 v177, v198, 6, v177
	v_and_b32_e32 v198, 63, v175
	v_add_u32_e32 v177, v177, v198
	v_lshlrev_b32_e32 v177, 1, v177
	s_cmp_eq_u32 s9, 0
	s_cbranch_scc1 .Lmy_p9_br0
	v_mov_b32_e32 v178, v176
	v_mov_b32_e32 v180, v177
	v_add_u32_e32 v181, 0x10000, v177
	v_add_u32_e32 v179, 0x10000, v176
	v_add_u32_e32 v182, 0x800, v177
	v_add_u32_e32 v183, 0x10800, v177
	global_load_dwordx4 v[216:219], v178, s[34:35]
	global_load_dwordx4 v[220:223], v180, s[12:13]
	global_load_dwordx4 v[224:227], v178, s[34:35] offset:256
	global_load_dwordx4 v[228:231], v181, s[12:13]
	global_load_dwordx4 v[232:235], v179, s[34:35]
	global_load_dwordx4 v[236:239], v182, s[12:13]
	global_load_dwordx4 v[240:243], v179, s[34:35] offset:256
	global_load_dwordx4 v[244:247], v183, s[12:13]
	v_add_u32_e32 v192, 0x20000, v176
	v_add_u32_e32 v194, 0x1000, v177
	v_add_u32_e32 v195, 0x11000, v177
	v_add_u32_e32 v193, 0x30000, v176
	v_add_u32_e32 v196, 0x1800, v177
	v_add_u32_e32 v197, 0x11800, v177
	global_load_dwordx4 v[128:131], v192, s[34:35]
	global_load_dwordx4 v[132:135], v194, s[12:13]
	global_load_dwordx4 v[136:139], v192, s[34:35] offset:256
	global_load_dwordx4 v[140:143], v195, s[12:13]
	global_load_dwordx4 v[144:147], v193, s[34:35]
	global_load_dwordx4 v[148:151], v196, s[12:13]
	global_load_dwordx4 v[152:155], v193, s[34:35] offset:256
	global_load_dwordx4 v[156:159], v197, s[12:13]
	v_mul_f32_e32 v124, 0xbfb8aa3b, v124
	v_mul_f32_e32 v125, 0xbfb8aa3b, v125
	v_mul_f32_e32 v126, 0xbfb8aa3b, v126
	v_mul_f32_e32 v127, 0xbfb8aa3b, v127
	v_mul_f32_e32 v120, 0xbfb8aa3b, v120
	v_mul_f32_e32 v121, 0xbfb8aa3b, v121
	v_mul_f32_e32 v122, 0xbfb8aa3b, v122
; __device__ __forceinline__ unsigned cvt_pk_bf16(float lo, float hi) { f32x2 v = {lo, hi}; bf16x2_t b = __builtin_convertvector(v, bf16x2_t); return __builtin_bit_cast(unsigned, b); }
; __device__ __forceinline__ float bflo(unsigned w) { return __uint_as_float(w << 16); }
; __device__ __forceinline__ float sigmoid_f(float x) { return __builtin_amdgcn_rcpf(1.0f + __expf(-x)); }
;     __device__ __forceinline__ void operator()(const f32x4 (&acc)[2][2][4][2], const Unit& u, int wr, int wc, int fr, int fq) const {
;     ...
;         for (int ai = 0; ai < 2; ++ai)
; #pragma unroll
;             for (int mh = 0; mh < 2; ++mh) {
;                 u32x4 yw[2][2], mw[2][2];
; #pragma unroll
;                 for (int mm = 0; mm < 2; ++mm) {
;                     const int rr = row0 + ai * HALF + (mh * 2 + mm) * 16;
;                     const size_t off = (size_t)rr * DM + col0;
; #pragma unroll
;                     for (int bj = 0; bj < 2; ++bj) {
;                         yw[mm][bj] = *(const u32x4*)(y + off + bj * HALF);
;                         mw[mm][bj] = (u32x4){0u, 0u, 0u, 0u};
;                         if (br != 0) mw[mm][bj] = *(const u32x4*)(merged + tl(rr, col0 + bj * HALF, DM));
;                     }
;                 }
; #pragma unroll
;                 for (int mm = 0; mm < 2; ++mm) {
;                     const int m = mh * 2 + mm;
;                     const int rr = row0 + ai * HALF + m * 16;
; #pragma unroll
;                     for (int bj = 0; bj < 2; ++bj) {
;                         const f32x4 a0 = acc[ai][bj][m][0], a1 = acc[ai][bj][m][1];
;                         const u32x4 yv = yw[mm][bj], mv = mw[mm][bj];
;                         u32x4 w;
;                         w.x = cvt_pk_bf16(sigmoid_f(a0[0]) * bflo(yv.x) + bflo(mv.x), sigmoid_f(a0[1]) * bfhi(yv.x) + bfhi(mv.x));
;                         w.y = cvt_pk_bf16(sigmoid_f(a0[2]) * bflo(yv.y) + bflo(mv.y), sigmoid_f(a0[3]) * bfhi(yv.y) + bfhi(mv.y));
;                         w.z = cvt_pk_bf16(sigmoid_f(a1[0]) * bflo(yv.z) + bflo(mv.z), sigmoid_f(a1[1]) * bfhi(yv.z) + bfhi(mv.z));
;                         w.w = cvt_pk_bf16(sigmoid_f(a1[2]) * bflo(yv.w) + bflo(mv.w), sigmoid_f(a1[3]) * bfhi(yv.w) + bfhi(mv.w));
;                         *(u32x4*)(merged + tl(rr, col0 + bj * HALF, DM)) = w;
;                     }
	v_mul_f32_e32 v123, 0xbfb8aa3b, v123
	v_exp_f32_e32 v124, v124
	v_exp_f32_e32 v125, v125
	v_exp_f32_e32 v126, v126
	v_exp_f32_e32 v127, v127
	v_exp_f32_e32 v120, v120
	v_exp_f32_e32 v121, v121
	v_exp_f32_e32 v122, v122
	v_exp_f32_e32 v123, v123
	v_add_f32_e32 v124, 1.0, v124
	v_add_f32_e32 v125, 1.0, v125
	v_add_f32_e32 v126, 1.0, v126
	v_add_f32_e32 v127, 1.0, v127
	v_add_f32_e32 v120, 1.0, v120
	v_add_f32_e32 v121, 1.0, v121
	v_add_f32_e32 v122, 1.0, v122
	v_add_f32_e32 v123, 1.0, v123
	v_rcp_f32_e32 v124, v124
	v_rcp_f32_e32 v125, v125
	v_rcp_f32_e32 v126, v126
	v_rcp_f32_e32 v127, v127
	v_rcp_f32_e32 v120, v120
	v_rcp_f32_e32 v121, v121
	v_rcp_f32_e32 v122, v122
	v_rcp_f32_e32 v123, v123
	v_mul_f32_e32 v116, 0xbfb8aa3b, v116
	v_mul_f32_e32 v117, 0xbfb8aa3b, v117
	v_mul_f32_e32 v118, 0xbfb8aa3b, v118
	v_mul_f32_e32 v119, 0xbfb8aa3b, v119
	v_mul_f32_e32 v112, 0xbfb8aa3b, v112
	v_mul_f32_e32 v113, 0xbfb8aa3b, v113
	v_mul_f32_e32 v114, 0xbfb8aa3b, v114
	v_mul_f32_e32 v115, 0xbfb8aa3b, v115
	v_exp_f32_e32 v116, v116
	v_exp_f32_e32 v117, v117
	v_exp_f32_e32 v118, v118
	v_exp_f32_e32 v119, v119
	v_exp_f32_e32 v112, v112
	v_exp_f32_e32 v113, v113
	v_exp_f32_e32 v114, v114
	v_exp_f32_e32 v115, v115
	v_add_f32_e32 v116, 1.0, v116
	v_add_f32_e32 v117, 1.0, v117
	v_add_f32_e32 v118, 1.0, v118
	v_add_f32_e32 v119, 1.0, v119
	v_add_f32_e32 v112, 1.0, v112
	v_add_f32_e32 v113, 1.0, v113
	v_add_f32_e32 v114, 1.0, v114
	v_add_f32_e32 v115, 1.0, v115
	v_rcp_f32_e32 v116, v116
	v_rcp_f32_e32 v117, v117
	v_rcp_f32_e32 v118, v118
	v_rcp_f32_e32 v119, v119
	v_rcp_f32_e32 v112, v112
	v_rcp_f32_e32 v113, v113
	v_rcp_f32_e32 v114, v114
	v_rcp_f32_e32 v115, v115
	v_mul_f32_e32 v108, 0xbfb8aa3b, v108
	v_mul_f32_e32 v109, 0xbfb8aa3b, v109
	v_mul_f32_e32 v110, 0xbfb8aa3b, v110
	v_mul_f32_e32 v111, 0xbfb8aa3b, v111
	v_mul_f32_e32 v104, 0xbfb8aa3b, v104
	v_mul_f32_e32 v105, 0xbfb8aa3b, v105
	v_mul_f32_e32 v106, 0xbfb8aa3b, v106
	v_mul_f32_e32 v107, 0xbfb8aa3b, v107
	v_exp_f32_e32 v108, v108
	v_exp_f32_e32 v109, v109
	v_exp_f32_e32 v110, v110
	v_exp_f32_e32 v111, v111
	v_exp_f32_e32 v104, v104
	v_exp_f32_e32 v105, v105
	v_exp_f32_e32 v106, v106
	v_exp_f32_e32 v107, v107
	v_add_f32_e32 v108, 1.0, v108
	v_add_f32_e32 v109, 1.0, v109
	v_add_f32_e32 v110, 1.0, v110
	v_add_f32_e32 v111, 1.0, v111
	v_add_f32_e32 v104, 1.0, v104
	v_add_f32_e32 v105, 1.0, v105
	v_add_f32_e32 v106, 1.0, v106
	v_add_f32_e32 v107, 1.0, v107
	v_rcp_f32_e32 v108, v108
	v_rcp_f32_e32 v109, v109
	v_rcp_f32_e32 v110, v110
	v_rcp_f32_e32 v111, v111
	v_rcp_f32_e32 v104, v104
	v_rcp_f32_e32 v105, v105
	v_rcp_f32_e32 v106, v106
	v_rcp_f32_e32 v107, v107
	v_mul_f32_e32 v100, 0xbfb8aa3b, v100
	v_mul_f32_e32 v101, 0xbfb8aa3b, v101
	v_mul_f32_e32 v102, 0xbfb8aa3b, v102
	v_mul_f32_e32 v103, 0xbfb8aa3b, v103
	v_mul_f32_e32 v96, 0xbfb8aa3b, v96
	v_mul_f32_e32 v97, 0xbfb8aa3b, v97
	v_mul_f32_e32 v98, 0xbfb8aa3b, v98
	v_mul_f32_e32 v99, 0xbfb8aa3b, v99
	v_exp_f32_e32 v100, v100
	v_exp_f32_e32 v101, v101
	v_exp_f32_e32 v102, v102
	v_exp_f32_e32 v103, v103
	v_exp_f32_e32 v96, v96
	v_exp_f32_e32 v97, v97
	v_exp_f32_e32 v98, v98
	v_exp_f32_e32 v99, v99
	v_add_f32_e32 v100, 1.0, v100
	v_add_f32_e32 v101, 1.0, v101
	v_add_f32_e32 v102, 1.0, v102
	v_add_f32_e32 v103, 1.0, v103
	v_add_f32_e32 v96, 1.0, v96
	v_add_f32_e32 v97, 1.0, v97
	v_add_f32_e32 v98, 1.0, v98
	v_add_f32_e32 v99, 1.0, v99
	v_rcp_f32_e32 v100, v100
	v_rcp_f32_e32 v101, v101
	v_rcp_f32_e32 v102, v102
	v_rcp_f32_e32 v103, v103
	v_rcp_f32_e32 v96, v96
	v_rcp_f32_e32 v97, v97
	v_rcp_f32_e32 v98, v98
	v_rcp_f32_e32 v99, v99
	s_waitcnt vmcnt(8)
	v_lshlrev_b32_e32 v198, 16, v216
	v_and_b32_e32 v199, 0xffff0000, v216
	v_lshlrev_b32_e32 v200, 16, v220
	v_and_b32_e32 v201, 0xffff0000, v220
	v_fma_f32 v124, v124, v198, v200
	v_fma_f32 v125, v125, v199, v201
	v_cvt_pk_bf16_f32 v248, v124, v125
	v_lshlrev_b32_e32 v202, 16, v217
	v_and_b32_e32 v203, 0xffff0000, v217
	v_lshlrev_b32_e32 v214, 16, v221
	v_and_b32_e32 v215, 0xffff0000, v221
	v_fma_f32 v126, v126, v202, v214
	v_fma_f32 v127, v127, v203, v215
	v_cvt_pk_bf16_f32 v249, v126, v127
	v_lshlrev_b32_e32 v198, 16, v218
	v_and_b32_e32 v199, 0xffff0000, v218
	v_lshlrev_b32_e32 v200, 16, v222
	v_and_b32_e32 v201, 0xffff0000, v222
	v_fma_f32 v120, v120, v198, v200
	v_fma_f32 v121, v121, v199, v201
	v_cvt_pk_bf16_f32 v250, v120, v121
	v_lshlrev_b32_e32 v202, 16, v219
	v_and_b32_e32 v203, 0xffff0000, v219
	v_lshlrev_b32_e32 v214, 16, v223
	v_and_b32_e32 v215, 0xffff0000, v223
	v_fma_f32 v122, v122, v202, v214
	v_fma_f32 v123, v123, v203, v215
	v_cvt_pk_bf16_f32 v251, v122, v123
	global_store_dwordx4 v180, v[248:251], s[12:13]
	v_lshlrev_b32_e32 v198, 16, v224
	v_and_b32_e32 v199, 0xffff0000, v224
	v_lshlrev_b32_e32 v200, 16, v228
	v_and_b32_e32 v201, 0xffff0000, v228
	v_fma_f32 v116, v116, v198, v200
	v_fma_f32 v117, v117, v199, v201
	v_cvt_pk_bf16_f32 v252, v116, v117
	v_lshlrev_b32_e32 v202, 16, v225
	v_and_b32_e32 v203, 0xffff0000, v225
	v_lshlrev_b32_e32 v214, 16, v229
	v_and_b32_e32 v215, 0xffff0000, v229
	v_fma_f32 v118, v118, v202, v214
	v_fma_f32 v119, v119, v203, v215
	v_cvt_pk_bf16_f32 v253, v118, v119
	v_lshlrev_b32_e32 v198, 16, v226
	v_and_b32_e32 v199, 0xffff0000, v226
	v_lshlrev_b32_e32 v200, 16, v230
	v_and_b32_e32 v201, 0xffff0000, v230
	v_fma_f32 v112, v112, v198, v200
	v_fma_f32 v113, v113, v199, v201
	v_cvt_pk_bf16_f32 v254, v112, v113
	v_lshlrev_b32_e32 v202, 16, v227
	v_and_b32_e32 v203, 0xffff0000, v227
	v_lshlrev_b32_e32 v214, 16, v231
	v_and_b32_e32 v215, 0xffff0000, v231
	v_fma_f32 v114, v114, v202, v214
	v_fma_f32 v115, v115, v203, v215
	v_cvt_pk_bf16_f32 v255, v114, v115
; __device__ __forceinline__ unsigned cvt_pk_bf16(float lo, float hi) { f32x2 v = {lo, hi}; bf16x2_t b = __builtin_convertvector(v, bf16x2_t); return __builtin_bit_cast(unsigned, b); }
; __device__ __forceinline__ float bflo(unsigned w) { return __uint_as_float(w << 16); }
; __device__ __forceinline__ float sigmoid_f(float x) { return __builtin_amdgcn_rcpf(1.0f + __expf(-x)); }
;     __device__ __forceinline__ void operator()(const f32x4 (&acc)[2][2][4][2], const Unit& u, int wr, int wc, int fr, int fq) const {
;     ...
;         for (int ai = 0; ai < 2; ++ai)
; #pragma unroll
;             for (int mh = 0; mh < 2; ++mh) {
;                 u32x4 yw[2][2], mw[2][2];
; #pragma unroll
;                 for (int mm = 0; mm < 2; ++mm) {
;                     const int rr = row0 + ai * HALF + (mh * 2 + mm) * 16;
;                     const size_t off = (size_t)rr * DM + col0;
; #pragma unroll
;                     for (int bj = 0; bj < 2; ++bj) {
;                         yw[mm][bj] = *(const u32x4*)(y + off + bj * HALF);
;                         mw[mm][bj] = (u32x4){0u, 0u, 0u, 0u};
;                         if (br != 0) mw[mm][bj] = *(const u32x4*)(merged + tl(rr, col0 + bj * HALF, DM));
;                     }
;                 }
; #pragma unroll
;                 for (int mm = 0; mm < 2; ++mm) {
;                     const int m = mh * 2 + mm;
;                     const int rr = row0 + ai * HALF + m * 16;
; #pragma unroll
;                     for (int bj = 0; bj < 2; ++bj) {
;                         const f32x4 a0 = acc[ai][bj][m][0], a1 = acc[ai][bj][m][1];
;                         const u32x4 yv = yw[mm][bj], mv = mw[mm][bj];
;                         u32x4 w;
;                         w.x = cvt_pk_bf16(sigmoid_f(a0[0]) * bflo(yv.x) + bflo(mv.x), sigmoid_f(a0[1]) * bfhi(yv.x) + bfhi(mv.x));
;                         w.y = cvt_pk_bf16(sigmoid_f(a0[2]) * bflo(yv.y) + bflo(mv.y), sigmoid_f(a0[3]) * bfhi(yv.y) + bfhi(mv.y));
;                         w.z = cvt_pk_bf16(sigmoid_f(a1[0]) * bflo(yv.z) + bflo(mv.z), sigmoid_f(a1[1]) * bfhi(yv.z) + bfhi(mv.z));
;                         w.w = cvt_pk_bf16(sigmoid_f(a1[2]) * bflo(yv.w) + bflo(mv.w), sigmoid_f(a1[3]) * bfhi(yv.w) + bfhi(mv.w));
;                         *(u32x4*)(merged + tl(rr, col0 + bj * HALF, DM)) = w;
;                     }
	global_store_dwordx4 v181, v[252:255], s[12:13]
	v_lshlrev_b32_e32 v198, 16, v232
	v_and_b32_e32 v199, 0xffff0000, v232
	v_lshlrev_b32_e32 v200, 16, v236
	v_and_b32_e32 v201, 0xffff0000, v236
	v_fma_f32 v108, v108, v198, v200
	v_fma_f32 v109, v109, v199, v201
	v_cvt_pk_bf16_f32 v206, v108, v109
	v_lshlrev_b32_e32 v202, 16, v233
	v_and_b32_e32 v203, 0xffff0000, v233
	v_lshlrev_b32_e32 v214, 16, v237
	v_and_b32_e32 v215, 0xffff0000, v237
	v_fma_f32 v110, v110, v202, v214
	v_fma_f32 v111, v111, v203, v215
	v_cvt_pk_bf16_f32 v207, v110, v111
	v_lshlrev_b32_e32 v198, 16, v234
	v_and_b32_e32 v199, 0xffff0000, v234
	v_lshlrev_b32_e32 v200, 16, v238
	v_and_b32_e32 v201, 0xffff0000, v238
	v_fma_f32 v104, v104, v198, v200
	v_fma_f32 v105, v105, v199, v201
	v_cvt_pk_bf16_f32 v208, v104, v105
	v_lshlrev_b32_e32 v202, 16, v235
	v_and_b32_e32 v203, 0xffff0000, v235
	v_lshlrev_b32_e32 v214, 16, v239
	v_and_b32_e32 v215, 0xffff0000, v239
	v_fma_f32 v106, v106, v202, v214
	v_fma_f32 v107, v107, v203, v215
	v_cvt_pk_bf16_f32 v209, v106, v107
	global_store_dwordx4 v182, v[206:209], s[12:13]
	v_lshlrev_b32_e32 v198, 16, v240
	v_and_b32_e32 v199, 0xffff0000, v240
	v_lshlrev_b32_e32 v200, 16, v244
	v_and_b32_e32 v201, 0xffff0000, v244
	v_fma_f32 v100, v100, v198, v200
	v_fma_f32 v101, v101, v199, v201
	v_cvt_pk_bf16_f32 v210, v100, v101
	v_lshlrev_b32_e32 v202, 16, v241
	v_and_b32_e32 v203, 0xffff0000, v241
	v_lshlrev_b32_e32 v214, 16, v245
	v_and_b32_e32 v215, 0xffff0000, v245
	v_fma_f32 v102, v102, v202, v214
	v_fma_f32 v103, v103, v203, v215
	v_cvt_pk_bf16_f32 v211, v102, v103
	v_lshlrev_b32_e32 v198, 16, v242
	v_and_b32_e32 v199, 0xffff0000, v242
	v_lshlrev_b32_e32 v200, 16, v246
	v_and_b32_e32 v201, 0xffff0000, v246
	v_fma_f32 v96, v96, v198, v200
	v_fma_f32 v97, v97, v199, v201
	v_cvt_pk_bf16_f32 v212, v96, v97
	v_lshlrev_b32_e32 v202, 16, v243
	v_and_b32_e32 v203, 0xffff0000, v243
	v_lshlrev_b32_e32 v214, 16, v247
	v_and_b32_e32 v215, 0xffff0000, v247
	v_fma_f32 v98, v98, v202, v214
	v_fma_f32 v99, v99, v203, v215
	v_cvt_pk_bf16_f32 v213, v98, v99
	global_store_dwordx4 v183, v[210:213], s[12:13]
	v_add_u32_e32 v178, 0x80000, v176
	v_add_u32_e32 v180, 0x4000, v177
	v_add_u32_e32 v181, 0x14000, v177
	v_add_u32_e32 v179, 0x90000, v176
	v_add_u32_e32 v182, 0x4800, v177
	v_add_u32_e32 v183, 0x14800, v177
	global_load_dwordx4 v[216:219], v178, s[34:35]
	global_load_dwordx4 v[220:223], v180, s[12:13]
	global_load_dwordx4 v[224:227], v178, s[34:35] offset:256
	global_load_dwordx4 v[228:231], v181, s[12:13]
	global_load_dwordx4 v[232:235], v179, s[34:35]
	global_load_dwordx4 v[236:239], v182, s[12:13]
	global_load_dwordx4 v[240:243], v179, s[34:35] offset:256
	global_load_dwordx4 v[244:247], v183, s[12:13]
	v_mul_f32_e32 v92, 0xbfb8aa3b, v92
	v_mul_f32_e32 v93, 0xbfb8aa3b, v93
	v_mul_f32_e32 v94, 0xbfb8aa3b, v94
	v_mul_f32_e32 v95, 0xbfb8aa3b, v95
	v_mul_f32_e32 v88, 0xbfb8aa3b, v88
	v_mul_f32_e32 v89, 0xbfb8aa3b, v89
	v_mul_f32_e32 v90, 0xbfb8aa3b, v90
	v_mul_f32_e32 v91, 0xbfb8aa3b, v91
	v_exp_f32_e32 v92, v92
	v_exp_f32_e32 v93, v93
	v_exp_f32_e32 v94, v94
	v_exp_f32_e32 v95, v95
	v_exp_f32_e32 v88, v88
	v_exp_f32_e32 v89, v89
	v_exp_f32_e32 v90, v90
	v_exp_f32_e32 v91, v91
	v_add_f32_e32 v92, 1.0, v92
	v_add_f32_e32 v93, 1.0, v93
	v_add_f32_e32 v94, 1.0, v94
	v_add_f32_e32 v95, 1.0, v95
	v_add_f32_e32 v88, 1.0, v88
	v_add_f32_e32 v89, 1.0, v89
	v_add_f32_e32 v90, 1.0, v90
	v_add_f32_e32 v91, 1.0, v91
	v_rcp_f32_e32 v92, v92
	v_rcp_f32_e32 v93, v93
	v_rcp_f32_e32 v94, v94
	v_rcp_f32_e32 v95, v95
	v_rcp_f32_e32 v88, v88
	v_rcp_f32_e32 v89, v89
	v_rcp_f32_e32 v90, v90
	v_rcp_f32_e32 v91, v91
	v_mul_f32_e32 v84, 0xbfb8aa3b, v84
	v_mul_f32_e32 v85, 0xbfb8aa3b, v85
	v_mul_f32_e32 v86, 0xbfb8aa3b, v86
	v_mul_f32_e32 v87, 0xbfb8aa3b, v87
	v_mul_f32_e32 v80, 0xbfb8aa3b, v80
	v_mul_f32_e32 v81, 0xbfb8aa3b, v81
	v_mul_f32_e32 v82, 0xbfb8aa3b, v82
	v_mul_f32_e32 v83, 0xbfb8aa3b, v83
	v_exp_f32_e32 v84, v84
	v_exp_f32_e32 v85, v85
	v_exp_f32_e32 v86, v86
	v_exp_f32_e32 v87, v87
	v_exp_f32_e32 v80, v80
	v_exp_f32_e32 v81, v81
	v_exp_f32_e32 v82, v82
	v_exp_f32_e32 v83, v83
	v_add_f32_e32 v84, 1.0, v84
	v_add_f32_e32 v85, 1.0, v85
	v_add_f32_e32 v86, 1.0, v86
	v_add_f32_e32 v87, 1.0, v87
	v_add_f32_e32 v80, 1.0, v80
	v_add_f32_e32 v81, 1.0, v81
	v_add_f32_e32 v82, 1.0, v82
	v_add_f32_e32 v83, 1.0, v83
	v_rcp_f32_e32 v84, v84
	v_rcp_f32_e32 v85, v85
	v_rcp_f32_e32 v86, v86
	v_rcp_f32_e32 v87, v87
	v_rcp_f32_e32 v80, v80
	v_rcp_f32_e32 v81, v81
	v_rcp_f32_e32 v82, v82
	v_rcp_f32_e32 v83, v83
	v_mul_f32_e32 v76, 0xbfb8aa3b, v76
	v_mul_f32_e32 v77, 0xbfb8aa3b, v77
	v_mul_f32_e32 v78, 0xbfb8aa3b, v78
	v_mul_f32_e32 v79, 0xbfb8aa3b, v79
	v_mul_f32_e32 v72, 0xbfb8aa3b, v72
	v_mul_f32_e32 v73, 0xbfb8aa3b, v73
	v_mul_f32_e32 v74, 0xbfb8aa3b, v74
	v_mul_f32_e32 v75, 0xbfb8aa3b, v75
	v_exp_f32_e32 v76, v76
	v_exp_f32_e32 v77, v77
	v_exp_f32_e32 v78, v78
	v_exp_f32_e32 v79, v79
	v_exp_f32_e32 v72, v72
	v_exp_f32_e32 v73, v73
	v_exp_f32_e32 v74, v74
	v_exp_f32_e32 v75, v75
	v_add_f32_e32 v76, 1.0, v76
	v_add_f32_e32 v77, 1.0, v77
	v_add_f32_e32 v78, 1.0, v78
	v_add_f32_e32 v79, 1.0, v79
	v_add_f32_e32 v72, 1.0, v72
	v_add_f32_e32 v73, 1.0, v73
	v_add_f32_e32 v74, 1.0, v74
	v_add_f32_e32 v75, 1.0, v75
	v_rcp_f32_e32 v76, v76
	v_rcp_f32_e32 v77, v77
	v_rcp_f32_e32 v78, v78
	v_rcp_f32_e32 v79, v79
	v_rcp_f32_e32 v72, v72
	v_rcp_f32_e32 v73, v73
	v_rcp_f32_e32 v74, v74
	v_rcp_f32_e32 v75, v75
	v_mul_f32_e32 v68, 0xbfb8aa3b, v68
	v_mul_f32_e32 v69, 0xbfb8aa3b, v69
	v_mul_f32_e32 v70, 0xbfb8aa3b, v70
	v_mul_f32_e32 v71, 0xbfb8aa3b, v71
	v_mul_f32_e32 v64, 0xbfb8aa3b, v64
	v_mul_f32_e32 v65, 0xbfb8aa3b, v65
	v_mul_f32_e32 v66, 0xbfb8aa3b, v66
	v_mul_f32_e32 v67, 0xbfb8aa3b, v67
	v_exp_f32_e32 v68, v68
	v_exp_f32_e32 v69, v69
	v_exp_f32_e32 v70, v70
	v_exp_f32_e32 v71, v71
	v_exp_f32_e32 v64, v64
	v_exp_f32_e32 v65, v65
	v_exp_f32_e32 v66, v66
	v_exp_f32_e32 v67, v67
	v_add_f32_e32 v68, 1.0, v68
	v_add_f32_e32 v69, 1.0, v69
	v_add_f32_e32 v70, 1.0, v70
	v_add_f32_e32 v71, 1.0, v71
	v_add_f32_e32 v64, 1.0, v64
	v_add_f32_e32 v65, 1.0, v65
	v_add_f32_e32 v66, 1.0, v66
	v_add_f32_e32 v67, 1.0, v67
	v_rcp_f32_e32 v68, v68
	v_rcp_f32_e32 v69, v69
	v_rcp_f32_e32 v70, v70
	v_rcp_f32_e32 v71, v71
	v_rcp_f32_e32 v64, v64
	v_rcp_f32_e32 v65, v65
	v_rcp_f32_e32 v66, v66
	v_rcp_f32_e32 v67, v67
	s_waitcnt vmcnt(12)
; __device__ __forceinline__ unsigned cvt_pk_bf16(float lo, float hi) { f32x2 v = {lo, hi}; bf16x2_t b = __builtin_convertvector(v, bf16x2_t); return __builtin_bit_cast(unsigned, b); }
; __device__ __forceinline__ float bflo(unsigned w) { return __uint_as_float(w << 16); }
; __device__ __forceinline__ float bfhi(unsigned w) { return __uint_as_float(w & 0xffff0000u); }
;     __device__ __forceinline__ void operator()(const f32x4 (&acc)[2][2][4][2], const Unit& u, int wr, int wc, int fr, int fq) const {
;     ...
;         for (int ai = 0; ai < 2; ++ai)
; #pragma unroll
;             for (int mh = 0; mh < 2; ++mh) {
;                 u32x4 yw[2][2], mw[2][2];
; #pragma unroll
;                 for (int mm = 0; mm < 2; ++mm) {
;                     const int rr = row0 + ai * HALF + (mh * 2 + mm) * 16;
;                     const size_t off = (size_t)rr * DM + col0;
; #pragma unroll
;                     for (int bj = 0; bj < 2; ++bj) {
;                         yw[mm][bj] = *(const u32x4*)(y + off + bj * HALF);
;                         mw[mm][bj] = (u32x4){0u, 0u, 0u, 0u};
;                         if (br != 0) mw[mm][bj] = *(const u32x4*)(merged + tl(rr, col0 + bj * HALF, DM));
;                     }
;                 }
; #pragma unroll
;                 for (int mm = 0; mm < 2; ++mm) {
;                     const int m = mh * 2 + mm;
;                     const int rr = row0 + ai * HALF + m * 16;
; #pragma unroll
;                     for (int bj = 0; bj < 2; ++bj) {
;                         const f32x4 a0 = acc[ai][bj][m][0], a1 = acc[ai][bj][m][1];
;                         const u32x4 yv = yw[mm][bj], mv = mw[mm][bj];
;                         u32x4 w;
;                         w.x = cvt_pk_bf16(sigmoid_f(a0[0]) * bflo(yv.x) + bflo(mv.x), sigmoid_f(a0[1]) * bfhi(yv.x) + bfhi(mv.x));
;                         w.y = cvt_pk_bf16(sigmoid_f(a0[2]) * bflo(yv.y) + bflo(mv.y), sigmoid_f(a0[3]) * bfhi(yv.y) + bfhi(mv.y));
;                         w.z = cvt_pk_bf16(sigmoid_f(a1[0]) * bflo(yv.z) + bflo(mv.z), sigmoid_f(a1[1]) * bfhi(yv.z) + bfhi(mv.z));
;                         w.w = cvt_pk_bf16(sigmoid_f(a1[2]) * bflo(yv.w) + bflo(mv.w), sigmoid_f(a1[3]) * bfhi(yv.w) + bfhi(mv.w));
;                         *(u32x4*)(merged + tl(rr, col0 + bj * HALF, DM)) = w;
;                     }
	v_lshlrev_b32_e32 v198, 16, v128
	v_and_b32_e32 v199, 0xffff0000, v128
	v_lshlrev_b32_e32 v200, 16, v132
	v_and_b32_e32 v201, 0xffff0000, v132
	v_fma_f32 v92, v92, v198, v200
	v_fma_f32 v93, v93, v199, v201
	v_cvt_pk_bf16_f32 v248, v92, v93
	v_lshlrev_b32_e32 v202, 16, v129
	v_and_b32_e32 v203, 0xffff0000, v129
	v_lshlrev_b32_e32 v214, 16, v133
	v_and_b32_e32 v215, 0xffff0000, v133
	v_fma_f32 v94, v94, v202, v214
	v_fma_f32 v95, v95, v203, v215
	v_cvt_pk_bf16_f32 v249, v94, v95
	v_lshlrev_b32_e32 v198, 16, v130
	v_and_b32_e32 v199, 0xffff0000, v130
	v_lshlrev_b32_e32 v200, 16, v134
	v_and_b32_e32 v201, 0xffff0000, v134
	v_fma_f32 v88, v88, v198, v200
	v_fma_f32 v89, v89, v199, v201
	v_cvt_pk_bf16_f32 v250, v88, v89
	v_lshlrev_b32_e32 v202, 16, v131
	v_and_b32_e32 v203, 0xffff0000, v131
	v_lshlrev_b32_e32 v214, 16, v135
	v_and_b32_e32 v215, 0xffff0000, v135
	v_fma_f32 v90, v90, v202, v214
	v_fma_f32 v91, v91, v203, v215
	v_cvt_pk_bf16_f32 v251, v90, v91
	global_store_dwordx4 v194, v[248:251], s[12:13]
	v_lshlrev_b32_e32 v198, 16, v136
	v_and_b32_e32 v199, 0xffff0000, v136
	v_lshlrev_b32_e32 v200, 16, v140
	v_and_b32_e32 v201, 0xffff0000, v140
	v_fma_f32 v84, v84, v198, v200
	v_fma_f32 v85, v85, v199, v201
	v_cvt_pk_bf16_f32 v252, v84, v85
	v_lshlrev_b32_e32 v202, 16, v137
	v_and_b32_e32 v203, 0xffff0000, v137
	v_lshlrev_b32_e32 v214, 16, v141
	v_and_b32_e32 v215, 0xffff0000, v141
	v_fma_f32 v86, v86, v202, v214
	v_fma_f32 v87, v87, v203, v215
	v_cvt_pk_bf16_f32 v253, v86, v87
	v_lshlrev_b32_e32 v198, 16, v138
	v_and_b32_e32 v199, 0xffff0000, v138
	v_lshlrev_b32_e32 v200, 16, v142
	v_and_b32_e32 v201, 0xffff0000, v142
	v_fma_f32 v80, v80, v198, v200
	v_fma_f32 v81, v81, v199, v201
	v_cvt_pk_bf16_f32 v254, v80, v81
	v_lshlrev_b32_e32 v202, 16, v139
	v_and_b32_e32 v203, 0xffff0000, v139
	v_lshlrev_b32_e32 v214, 16, v143
	v_and_b32_e32 v215, 0xffff0000, v143
	v_fma_f32 v82, v82, v202, v214
	v_fma_f32 v83, v83, v203, v215
	v_cvt_pk_bf16_f32 v255, v82, v83
	global_store_dwordx4 v195, v[252:255], s[12:13]
	v_lshlrev_b32_e32 v198, 16, v144
	v_and_b32_e32 v199, 0xffff0000, v144
	v_lshlrev_b32_e32 v200, 16, v148
	v_and_b32_e32 v201, 0xffff0000, v148
	v_fma_f32 v76, v76, v198, v200
	v_fma_f32 v77, v77, v199, v201
	v_cvt_pk_bf16_f32 v206, v76, v77
	v_lshlrev_b32_e32 v202, 16, v145
	v_and_b32_e32 v203, 0xffff0000, v145
	v_lshlrev_b32_e32 v214, 16, v149
	v_and_b32_e32 v215, 0xffff0000, v149
	v_fma_f32 v78, v78, v202, v214
	v_fma_f32 v79, v79, v203, v215
	v_cvt_pk_bf16_f32 v207, v78, v79
	v_lshlrev_b32_e32 v198, 16, v146
	v_and_b32_e32 v199, 0xffff0000, v146
	v_lshlrev_b32_e32 v200, 16, v150
	v_and_b32_e32 v201, 0xffff0000, v150
	v_fma_f32 v72, v72, v198, v200
	v_fma_f32 v73, v73, v199, v201
	v_cvt_pk_bf16_f32 v208, v72, v73
	v_lshlrev_b32_e32 v202, 16, v147
	v_and_b32_e32 v203, 0xffff0000, v147
	v_lshlrev_b32_e32 v214, 16, v151
	v_and_b32_e32 v215, 0xffff0000, v151
	v_fma_f32 v74, v74, v202, v214
	v_fma_f32 v75, v75, v203, v215
	v_cvt_pk_bf16_f32 v209, v74, v75
	global_store_dwordx4 v196, v[206:209], s[12:13]
	v_lshlrev_b32_e32 v198, 16, v152
	v_and_b32_e32 v199, 0xffff0000, v152
	v_lshlrev_b32_e32 v200, 16, v156
	v_and_b32_e32 v201, 0xffff0000, v156
	v_fma_f32 v68, v68, v198, v200
	v_fma_f32 v69, v69, v199, v201
	v_cvt_pk_bf16_f32 v210, v68, v69
	v_lshlrev_b32_e32 v202, 16, v153
	v_and_b32_e32 v203, 0xffff0000, v153
	v_lshlrev_b32_e32 v214, 16, v157
	v_and_b32_e32 v215, 0xffff0000, v157
	v_fma_f32 v70, v70, v202, v214
	v_fma_f32 v71, v71, v203, v215
	v_cvt_pk_bf16_f32 v211, v70, v71
	v_lshlrev_b32_e32 v198, 16, v154
	v_and_b32_e32 v199, 0xffff0000, v154
	v_lshlrev_b32_e32 v200, 16, v158
	v_and_b32_e32 v201, 0xffff0000, v158
	v_fma_f32 v64, v64, v198, v200
	v_fma_f32 v65, v65, v199, v201
	v_cvt_pk_bf16_f32 v212, v64, v65
	v_lshlrev_b32_e32 v202, 16, v155
	v_and_b32_e32 v203, 0xffff0000, v155
	v_lshlrev_b32_e32 v214, 16, v159
	v_and_b32_e32 v215, 0xffff0000, v159
	v_fma_f32 v66, v66, v202, v214
	v_fma_f32 v67, v67, v203, v215
	v_cvt_pk_bf16_f32 v213, v66, v67
	global_store_dwordx4 v197, v[210:213], s[12:13]
	v_add_u32_e32 v192, 0xa0000, v176
	v_add_u32_e32 v194, 0x5000, v177
	v_add_u32_e32 v195, 0x15000, v177
	v_add_u32_e32 v193, 0xb0000, v176
	v_add_u32_e32 v196, 0x5800, v177
	v_add_u32_e32 v197, 0x15800, v177
	global_load_dwordx4 v[128:131], v192, s[34:35]
	global_load_dwordx4 v[132:135], v194, s[12:13]
	global_load_dwordx4 v[136:139], v192, s[34:35] offset:256
	global_load_dwordx4 v[140:143], v195, s[12:13]
	global_load_dwordx4 v[144:147], v193, s[34:35]
	global_load_dwordx4 v[148:151], v196, s[12:13]
	global_load_dwordx4 v[152:155], v193, s[34:35] offset:256
	global_load_dwordx4 v[156:159], v197, s[12:13]
	v_mul_f32_e32 v60, 0xbfb8aa3b, v60
	v_mul_f32_e32 v61, 0xbfb8aa3b, v61
	v_mul_f32_e32 v62, 0xbfb8aa3b, v62
	v_mul_f32_e32 v63, 0xbfb8aa3b, v63
	v_mul_f32_e32 v56, 0xbfb8aa3b, v56
	v_mul_f32_e32 v57, 0xbfb8aa3b, v57
	v_mul_f32_e32 v58, 0xbfb8aa3b, v58
	v_mul_f32_e32 v59, 0xbfb8aa3b, v59
	v_exp_f32_e32 v60, v60
	v_exp_f32_e32 v61, v61
	v_exp_f32_e32 v62, v62
	v_exp_f32_e32 v63, v63
	v_exp_f32_e32 v56, v56
	v_exp_f32_e32 v57, v57
	v_exp_f32_e32 v58, v58
	v_exp_f32_e32 v59, v59
	v_add_f32_e32 v60, 1.0, v60
	v_add_f32_e32 v61, 1.0, v61
	v_add_f32_e32 v62, 1.0, v62
	v_add_f32_e32 v63, 1.0, v63
	v_add_f32_e32 v56, 1.0, v56
	v_add_f32_e32 v57, 1.0, v57
	v_add_f32_e32 v58, 1.0, v58
	v_add_f32_e32 v59, 1.0, v59
	v_rcp_f32_e32 v60, v60
	v_rcp_f32_e32 v61, v61
	v_rcp_f32_e32 v62, v62
	v_rcp_f32_e32 v63, v63
	v_rcp_f32_e32 v56, v56
	v_rcp_f32_e32 v57, v57
	v_rcp_f32_e32 v58, v58
	v_rcp_f32_e32 v59, v59
	v_mul_f32_e32 v52, 0xbfb8aa3b, v52
; __device__ __forceinline__ unsigned cvt_pk_bf16(float lo, float hi) { f32x2 v = {lo, hi}; bf16x2_t b = __builtin_convertvector(v, bf16x2_t); return __builtin_bit_cast(unsigned, b); }
; __device__ __forceinline__ float bflo(unsigned w) { return __uint_as_float(w << 16); }
; __device__ __forceinline__ float sigmoid_f(float x) { return __builtin_amdgcn_rcpf(1.0f + __expf(-x)); }
;     __device__ __forceinline__ void operator()(const f32x4 (&acc)[2][2][4][2], const Unit& u, int wr, int wc, int fr, int fq) const {
;     ...
;         for (int ai = 0; ai < 2; ++ai)
; #pragma unroll
;             for (int mh = 0; mh < 2; ++mh) {
;                 u32x4 yw[2][2], mw[2][2];
; #pragma unroll
;                 for (int mm = 0; mm < 2; ++mm) {
;                     const int rr = row0 + ai * HALF + (mh * 2 + mm) * 16;
;                     const size_t off = (size_t)rr * DM + col0;
; #pragma unroll
;                     for (int bj = 0; bj < 2; ++bj) {
;                         yw[mm][bj] = *(const u32x4*)(y + off + bj * HALF);
;                         mw[mm][bj] = (u32x4){0u, 0u, 0u, 0u};
;                         if (br != 0) mw[mm][bj] = *(const u32x4*)(merged + tl(rr, col0 + bj * HALF, DM));
;                     }
;                 }
; #pragma unroll
;                 for (int mm = 0; mm < 2; ++mm) {
;                     const int m = mh * 2 + mm;
;                     const int rr = row0 + ai * HALF + m * 16;
; #pragma unroll
;                     for (int bj = 0; bj < 2; ++bj) {
;                         const f32x4 a0 = acc[ai][bj][m][0], a1 = acc[ai][bj][m][1];
;                         const u32x4 yv = yw[mm][bj], mv = mw[mm][bj];
;                         u32x4 w;
;                         w.x = cvt_pk_bf16(sigmoid_f(a0[0]) * bflo(yv.x) + bflo(mv.x), sigmoid_f(a0[1]) * bfhi(yv.x) + bfhi(mv.x));
;                         w.y = cvt_pk_bf16(sigmoid_f(a0[2]) * bflo(yv.y) + bflo(mv.y), sigmoid_f(a0[3]) * bfhi(yv.y) + bfhi(mv.y));
;                         w.z = cvt_pk_bf16(sigmoid_f(a1[0]) * bflo(yv.z) + bflo(mv.z), sigmoid_f(a1[1]) * bfhi(yv.z) + bfhi(mv.z));
;                         w.w = cvt_pk_bf16(sigmoid_f(a1[2]) * bflo(yv.w) + bflo(mv.w), sigmoid_f(a1[3]) * bfhi(yv.w) + bfhi(mv.w));
;                         *(u32x4*)(merged + tl(rr, col0 + bj * HALF, DM)) = w;
;                     }
	v_mul_f32_e32 v53, 0xbfb8aa3b, v53
	v_mul_f32_e32 v54, 0xbfb8aa3b, v54
	v_mul_f32_e32 v55, 0xbfb8aa3b, v55
	v_mul_f32_e32 v48, 0xbfb8aa3b, v48
	v_mul_f32_e32 v49, 0xbfb8aa3b, v49
	v_mul_f32_e32 v50, 0xbfb8aa3b, v50
	v_mul_f32_e32 v51, 0xbfb8aa3b, v51
	v_exp_f32_e32 v52, v52
	v_exp_f32_e32 v53, v53
	v_exp_f32_e32 v54, v54
	v_exp_f32_e32 v55, v55
	v_exp_f32_e32 v48, v48
	v_exp_f32_e32 v49, v49
	v_exp_f32_e32 v50, v50
	v_exp_f32_e32 v51, v51
	v_add_f32_e32 v52, 1.0, v52
	v_add_f32_e32 v53, 1.0, v53
	v_add_f32_e32 v54, 1.0, v54
	v_add_f32_e32 v55, 1.0, v55
	v_add_f32_e32 v48, 1.0, v48
	v_add_f32_e32 v49, 1.0, v49
	v_add_f32_e32 v50, 1.0, v50
	v_add_f32_e32 v51, 1.0, v51
	v_rcp_f32_e32 v52, v52
	v_rcp_f32_e32 v53, v53
	v_rcp_f32_e32 v54, v54
	v_rcp_f32_e32 v55, v55
	v_rcp_f32_e32 v48, v48
	v_rcp_f32_e32 v49, v49
	v_rcp_f32_e32 v50, v50
	v_rcp_f32_e32 v51, v51
	v_mul_f32_e32 v44, 0xbfb8aa3b, v44
	v_mul_f32_e32 v45, 0xbfb8aa3b, v45
	v_mul_f32_e32 v46, 0xbfb8aa3b, v46
	v_mul_f32_e32 v47, 0xbfb8aa3b, v47
	v_mul_f32_e32 v40, 0xbfb8aa3b, v40
	v_mul_f32_e32 v41, 0xbfb8aa3b, v41
	v_mul_f32_e32 v42, 0xbfb8aa3b, v42
	v_mul_f32_e32 v43, 0xbfb8aa3b, v43
	v_exp_f32_e32 v44, v44
	v_exp_f32_e32 v45, v45
	v_exp_f32_e32 v46, v46
	v_exp_f32_e32 v47, v47
	v_exp_f32_e32 v40, v40
	v_exp_f32_e32 v41, v41
	v_exp_f32_e32 v42, v42
	v_exp_f32_e32 v43, v43
	v_add_f32_e32 v44, 1.0, v44
	v_add_f32_e32 v45, 1.0, v45
	v_add_f32_e32 v46, 1.0, v46
	v_add_f32_e32 v47, 1.0, v47
	v_add_f32_e32 v40, 1.0, v40
	v_add_f32_e32 v41, 1.0, v41
	v_add_f32_e32 v42, 1.0, v42
	v_add_f32_e32 v43, 1.0, v43
	v_rcp_f32_e32 v44, v44
	v_rcp_f32_e32 v45, v45
	v_rcp_f32_e32 v46, v46
	v_rcp_f32_e32 v47, v47
	v_rcp_f32_e32 v40, v40
	v_rcp_f32_e32 v41, v41
	v_rcp_f32_e32 v42, v42
	v_rcp_f32_e32 v43, v43
	v_mul_f32_e32 v36, 0xbfb8aa3b, v36
	v_mul_f32_e32 v37, 0xbfb8aa3b, v37
	v_mul_f32_e32 v38, 0xbfb8aa3b, v38
	v_mul_f32_e32 v39, 0xbfb8aa3b, v39
	v_mul_f32_e32 v32, 0xbfb8aa3b, v32
	v_mul_f32_e32 v33, 0xbfb8aa3b, v33
	v_mul_f32_e32 v34, 0xbfb8aa3b, v34
	v_mul_f32_e32 v35, 0xbfb8aa3b, v35
	v_exp_f32_e32 v36, v36
	v_exp_f32_e32 v37, v37
	v_exp_f32_e32 v38, v38
	v_exp_f32_e32 v39, v39
	v_exp_f32_e32 v32, v32
	v_exp_f32_e32 v33, v33
	v_exp_f32_e32 v34, v34
	v_exp_f32_e32 v35, v35
	v_add_f32_e32 v36, 1.0, v36
	v_add_f32_e32 v37, 1.0, v37
	v_add_f32_e32 v38, 1.0, v38
	v_add_f32_e32 v39, 1.0, v39
	v_add_f32_e32 v32, 1.0, v32
	v_add_f32_e32 v33, 1.0, v33
	v_add_f32_e32 v34, 1.0, v34
	v_add_f32_e32 v35, 1.0, v35
	v_rcp_f32_e32 v36, v36
	v_rcp_f32_e32 v37, v37
	v_rcp_f32_e32 v38, v38
	v_rcp_f32_e32 v39, v39
	v_rcp_f32_e32 v32, v32
	v_rcp_f32_e32 v33, v33
	v_rcp_f32_e32 v34, v34
	v_rcp_f32_e32 v35, v35
	s_waitcnt vmcnt(12)
	v_lshlrev_b32_e32 v198, 16, v216
	v_and_b32_e32 v199, 0xffff0000, v216
	v_lshlrev_b32_e32 v200, 16, v220
	v_and_b32_e32 v201, 0xffff0000, v220
	v_fma_f32 v60, v60, v198, v200
	v_fma_f32 v61, v61, v199, v201
	v_cvt_pk_bf16_f32 v248, v60, v61
	v_lshlrev_b32_e32 v202, 16, v217
	v_and_b32_e32 v203, 0xffff0000, v217
	v_lshlrev_b32_e32 v214, 16, v221
	v_and_b32_e32 v215, 0xffff0000, v221
	v_fma_f32 v62, v62, v202, v214
	v_fma_f32 v63, v63, v203, v215
	v_cvt_pk_bf16_f32 v249, v62, v63
	v_lshlrev_b32_e32 v198, 16, v218
	v_and_b32_e32 v199, 0xffff0000, v218
	v_lshlrev_b32_e32 v200, 16, v222
	v_and_b32_e32 v201, 0xffff0000, v222
	v_fma_f32 v56, v56, v198, v200
	v_fma_f32 v57, v57, v199, v201
	v_cvt_pk_bf16_f32 v250, v56, v57
	v_lshlrev_b32_e32 v202, 16, v219
	v_and_b32_e32 v203, 0xffff0000, v219
	v_lshlrev_b32_e32 v214, 16, v223
	v_and_b32_e32 v215, 0xffff0000, v223
	v_fma_f32 v58, v58, v202, v214
	v_fma_f32 v59, v59, v203, v215
	v_cvt_pk_bf16_f32 v251, v58, v59
	global_store_dwordx4 v180, v[248:251], s[12:13]
	v_lshlrev_b32_e32 v198, 16, v224
	v_and_b32_e32 v199, 0xffff0000, v224
	v_lshlrev_b32_e32 v200, 16, v228
	v_and_b32_e32 v201, 0xffff0000, v228
	v_fma_f32 v52, v52, v198, v200
	v_fma_f32 v53, v53, v199, v201
	v_cvt_pk_bf16_f32 v252, v52, v53
	v_lshlrev_b32_e32 v202, 16, v225
	v_and_b32_e32 v203, 0xffff0000, v225
	v_lshlrev_b32_e32 v214, 16, v229
	v_and_b32_e32 v215, 0xffff0000, v229
	v_fma_f32 v54, v54, v202, v214
	v_fma_f32 v55, v55, v203, v215
	v_cvt_pk_bf16_f32 v253, v54, v55
	v_lshlrev_b32_e32 v198, 16, v226
	v_and_b32_e32 v199, 0xffff0000, v226
	v_lshlrev_b32_e32 v200, 16, v230
	v_and_b32_e32 v201, 0xffff0000, v230
	v_fma_f32 v48, v48, v198, v200
	v_fma_f32 v49, v49, v199, v201
	v_cvt_pk_bf16_f32 v254, v48, v49
	v_lshlrev_b32_e32 v202, 16, v227
	v_and_b32_e32 v203, 0xffff0000, v227
	v_lshlrev_b32_e32 v214, 16, v231
	v_and_b32_e32 v215, 0xffff0000, v231
	v_fma_f32 v50, v50, v202, v214
	v_fma_f32 v51, v51, v203, v215
	v_cvt_pk_bf16_f32 v255, v50, v51
	global_store_dwordx4 v181, v[252:255], s[12:13]
	v_lshlrev_b32_e32 v198, 16, v232
	v_and_b32_e32 v199, 0xffff0000, v232
	v_lshlrev_b32_e32 v200, 16, v236
	v_and_b32_e32 v201, 0xffff0000, v236
	v_fma_f32 v44, v44, v198, v200
	v_fma_f32 v45, v45, v199, v201
	v_cvt_pk_bf16_f32 v206, v44, v45
	v_lshlrev_b32_e32 v202, 16, v233
	v_and_b32_e32 v203, 0xffff0000, v233
	v_lshlrev_b32_e32 v214, 16, v237
	v_and_b32_e32 v215, 0xffff0000, v237
	v_fma_f32 v46, v46, v202, v214
	v_fma_f32 v47, v47, v203, v215
	v_cvt_pk_bf16_f32 v207, v46, v47
	v_lshlrev_b32_e32 v198, 16, v234
	v_and_b32_e32 v199, 0xffff0000, v234
	v_lshlrev_b32_e32 v200, 16, v238
	v_and_b32_e32 v201, 0xffff0000, v238
	v_fma_f32 v40, v40, v198, v200
	v_fma_f32 v41, v41, v199, v201
	v_cvt_pk_bf16_f32 v208, v40, v41
	v_lshlrev_b32_e32 v202, 16, v235
	v_and_b32_e32 v203, 0xffff0000, v235
	v_lshlrev_b32_e32 v214, 16, v239
	v_and_b32_e32 v215, 0xffff0000, v239
	v_fma_f32 v42, v42, v202, v214
; __device__ __forceinline__ unsigned cvt_pk_bf16(float lo, float hi) { f32x2 v = {lo, hi}; bf16x2_t b = __builtin_convertvector(v, bf16x2_t); return __builtin_bit_cast(unsigned, b); }
; __device__ __forceinline__ float bflo(unsigned w) { return __uint_as_float(w << 16); }
; __device__ __forceinline__ float sigmoid_f(float x) { return __builtin_amdgcn_rcpf(1.0f + __expf(-x)); }
;     __device__ __forceinline__ void operator()(const f32x4 (&acc)[2][2][4][2], const Unit& u, int wr, int wc, int fr, int fq) const {
;     ...
;         for (int ai = 0; ai < 2; ++ai)
; #pragma unroll
;             for (int mh = 0; mh < 2; ++mh) {
;                 u32x4 yw[2][2], mw[2][2];
; #pragma unroll
;                 for (int mm = 0; mm < 2; ++mm) {
;                     const int rr = row0 + ai * HALF + (mh * 2 + mm) * 16;
;                     const size_t off = (size_t)rr * DM + col0;
; #pragma unroll
;                     for (int bj = 0; bj < 2; ++bj) {
;                         yw[mm][bj] = *(const u32x4*)(y + off + bj * HALF);
;                         mw[mm][bj] = (u32x4){0u, 0u, 0u, 0u};
;                         if (br != 0) mw[mm][bj] = *(const u32x4*)(merged + tl(rr, col0 + bj * HALF, DM));
;                     }
;                 }
; #pragma unroll
;                 for (int mm = 0; mm < 2; ++mm) {
;                     const int m = mh * 2 + mm;
;                     const int rr = row0 + ai * HALF + m * 16;
; #pragma unroll
;                     for (int bj = 0; bj < 2; ++bj) {
;                         const f32x4 a0 = acc[ai][bj][m][0], a1 = acc[ai][bj][m][1];
;                         const u32x4 yv = yw[mm][bj], mv = mw[mm][bj];
;                         u32x4 w;
;                         w.x = cvt_pk_bf16(sigmoid_f(a0[0]) * bflo(yv.x) + bflo(mv.x), sigmoid_f(a0[1]) * bfhi(yv.x) + bfhi(mv.x));
;                         w.y = cvt_pk_bf16(sigmoid_f(a0[2]) * bflo(yv.y) + bflo(mv.y), sigmoid_f(a0[3]) * bfhi(yv.y) + bfhi(mv.y));
;                         w.z = cvt_pk_bf16(sigmoid_f(a1[0]) * bflo(yv.z) + bflo(mv.z), sigmoid_f(a1[1]) * bfhi(yv.z) + bfhi(mv.z));
;                         w.w = cvt_pk_bf16(sigmoid_f(a1[2]) * bflo(yv.w) + bflo(mv.w), sigmoid_f(a1[3]) * bfhi(yv.w) + bfhi(mv.w));
;                         *(u32x4*)(merged + tl(rr, col0 + bj * HALF, DM)) = w;
;                     }
	v_fma_f32 v43, v43, v203, v215
	v_cvt_pk_bf16_f32 v209, v42, v43
	global_store_dwordx4 v182, v[206:209], s[12:13]
	v_lshlrev_b32_e32 v198, 16, v240
	v_and_b32_e32 v199, 0xffff0000, v240
	v_lshlrev_b32_e32 v200, 16, v244
	v_and_b32_e32 v201, 0xffff0000, v244
	v_fma_f32 v36, v36, v198, v200
	v_fma_f32 v37, v37, v199, v201
	v_cvt_pk_bf16_f32 v210, v36, v37
	v_lshlrev_b32_e32 v202, 16, v241
	v_and_b32_e32 v203, 0xffff0000, v241
	v_lshlrev_b32_e32 v214, 16, v245
	v_and_b32_e32 v215, 0xffff0000, v245
	v_fma_f32 v38, v38, v202, v214
	v_fma_f32 v39, v39, v203, v215
	v_cvt_pk_bf16_f32 v211, v38, v39
	v_lshlrev_b32_e32 v198, 16, v242
	v_and_b32_e32 v199, 0xffff0000, v242
	v_lshlrev_b32_e32 v200, 16, v246
	v_and_b32_e32 v201, 0xffff0000, v246
	v_fma_f32 v32, v32, v198, v200
	v_fma_f32 v33, v33, v199, v201
	v_cvt_pk_bf16_f32 v212, v32, v33
	v_lshlrev_b32_e32 v202, 16, v243
	v_and_b32_e32 v203, 0xffff0000, v243
	v_lshlrev_b32_e32 v214, 16, v247
	v_and_b32_e32 v215, 0xffff0000, v247
	v_fma_f32 v34, v34, v202, v214
	v_fma_f32 v35, v35, v203, v215
	v_cvt_pk_bf16_f32 v213, v34, v35
	global_store_dwordx4 v183, v[210:213], s[12:13]
	v_mul_f32_e32 v28, 0xbfb8aa3b, v28
	v_mul_f32_e32 v29, 0xbfb8aa3b, v29
	v_mul_f32_e32 v30, 0xbfb8aa3b, v30
	v_mul_f32_e32 v31, 0xbfb8aa3b, v31
	v_mul_f32_e32 v24, 0xbfb8aa3b, v24
	v_mul_f32_e32 v25, 0xbfb8aa3b, v25
	v_mul_f32_e32 v26, 0xbfb8aa3b, v26
	v_mul_f32_e32 v27, 0xbfb8aa3b, v27
	v_exp_f32_e32 v28, v28
	v_exp_f32_e32 v29, v29
	v_exp_f32_e32 v30, v30
	v_exp_f32_e32 v31, v31
	v_exp_f32_e32 v24, v24
	v_exp_f32_e32 v25, v25
	v_exp_f32_e32 v26, v26
	v_exp_f32_e32 v27, v27
	v_add_f32_e32 v28, 1.0, v28
	v_add_f32_e32 v29, 1.0, v29
	v_add_f32_e32 v30, 1.0, v30
	v_add_f32_e32 v31, 1.0, v31
	v_add_f32_e32 v24, 1.0, v24
	v_add_f32_e32 v25, 1.0, v25
	v_add_f32_e32 v26, 1.0, v26
	v_add_f32_e32 v27, 1.0, v27
	v_rcp_f32_e32 v28, v28
	v_rcp_f32_e32 v29, v29
	v_rcp_f32_e32 v30, v30
	v_rcp_f32_e32 v31, v31
	v_rcp_f32_e32 v24, v24
	v_rcp_f32_e32 v25, v25
	v_rcp_f32_e32 v26, v26
	v_rcp_f32_e32 v27, v27
	v_mul_f32_e32 v20, 0xbfb8aa3b, v20
	v_mul_f32_e32 v21, 0xbfb8aa3b, v21
	v_mul_f32_e32 v22, 0xbfb8aa3b, v22
	v_mul_f32_e32 v23, 0xbfb8aa3b, v23
	v_mul_f32_e32 v16, 0xbfb8aa3b, v16
	v_mul_f32_e32 v17, 0xbfb8aa3b, v17
	v_mul_f32_e32 v18, 0xbfb8aa3b, v18
	v_mul_f32_e32 v19, 0xbfb8aa3b, v19
	v_exp_f32_e32 v20, v20
	v_exp_f32_e32 v21, v21
	v_exp_f32_e32 v22, v22
	v_exp_f32_e32 v23, v23
	v_exp_f32_e32 v16, v16
	v_exp_f32_e32 v17, v17
	v_exp_f32_e32 v18, v18
	v_exp_f32_e32 v19, v19
	v_add_f32_e32 v20, 1.0, v20
	v_add_f32_e32 v21, 1.0, v21
	v_add_f32_e32 v22, 1.0, v22
	v_add_f32_e32 v23, 1.0, v23
	v_add_f32_e32 v16, 1.0, v16
	v_add_f32_e32 v17, 1.0, v17
	v_add_f32_e32 v18, 1.0, v18
	v_add_f32_e32 v19, 1.0, v19
	v_rcp_f32_e32 v20, v20
	v_rcp_f32_e32 v21, v21
	v_rcp_f32_e32 v22, v22
	v_rcp_f32_e32 v23, v23
	v_rcp_f32_e32 v16, v16
	v_rcp_f32_e32 v17, v17
	v_rcp_f32_e32 v18, v18
	v_rcp_f32_e32 v19, v19
	v_mul_f32_e32 v12, 0xbfb8aa3b, v12
	v_mul_f32_e32 v13, 0xbfb8aa3b, v13
	v_mul_f32_e32 v14, 0xbfb8aa3b, v14
	v_mul_f32_e32 v15, 0xbfb8aa3b, v15
	v_mul_f32_e32 v8, 0xbfb8aa3b, v8
	v_mul_f32_e32 v9, 0xbfb8aa3b, v9
	v_mul_f32_e32 v10, 0xbfb8aa3b, v10
	v_mul_f32_e32 v11, 0xbfb8aa3b, v11
	v_exp_f32_e32 v12, v12
	v_exp_f32_e32 v13, v13
	v_exp_f32_e32 v14, v14
	v_exp_f32_e32 v15, v15
	v_exp_f32_e32 v8, v8
	v_exp_f32_e32 v9, v9
	v_exp_f32_e32 v10, v10
	v_exp_f32_e32 v11, v11
	v_add_f32_e32 v12, 1.0, v12
	v_add_f32_e32 v13, 1.0, v13
	v_add_f32_e32 v14, 1.0, v14
	v_add_f32_e32 v15, 1.0, v15
	v_add_f32_e32 v8, 1.0, v8
	v_add_f32_e32 v9, 1.0, v9
	v_add_f32_e32 v10, 1.0, v10
	v_add_f32_e32 v11, 1.0, v11
	v_rcp_f32_e32 v12, v12
	v_rcp_f32_e32 v13, v13
	v_rcp_f32_e32 v14, v14
	v_rcp_f32_e32 v15, v15
	v_rcp_f32_e32 v8, v8
	v_rcp_f32_e32 v9, v9
	v_rcp_f32_e32 v10, v10
	v_rcp_f32_e32 v11, v11
	v_mul_f32_e32 v4, 0xbfb8aa3b, v4
	v_mul_f32_e32 v5, 0xbfb8aa3b, v5
	v_mul_f32_e32 v6, 0xbfb8aa3b, v6
	v_mul_f32_e32 v7, 0xbfb8aa3b, v7
	v_mul_f32_e32 v0, 0xbfb8aa3b, v0
	v_mul_f32_e32 v1, 0xbfb8aa3b, v1
	v_mul_f32_e32 v2, 0xbfb8aa3b, v2
	v_mul_f32_e32 v3, 0xbfb8aa3b, v3
	v_exp_f32_e32 v4, v4
	v_exp_f32_e32 v5, v5
	v_exp_f32_e32 v6, v6
	v_exp_f32_e32 v7, v7
	v_exp_f32_e32 v0, v0
	v_exp_f32_e32 v1, v1
	v_exp_f32_e32 v2, v2
	v_exp_f32_e32 v3, v3
	v_add_f32_e32 v4, 1.0, v4
	v_add_f32_e32 v5, 1.0, v5
	v_add_f32_e32 v6, 1.0, v6
	v_add_f32_e32 v7, 1.0, v7
	v_add_f32_e32 v0, 1.0, v0
	v_add_f32_e32 v1, 1.0, v1
	v_add_f32_e32 v2, 1.0, v2
	v_add_f32_e32 v3, 1.0, v3
	v_rcp_f32_e32 v4, v4
	v_rcp_f32_e32 v5, v5
	v_rcp_f32_e32 v6, v6
	v_rcp_f32_e32 v7, v7
	v_rcp_f32_e32 v0, v0
	v_rcp_f32_e32 v1, v1
	v_rcp_f32_e32 v2, v2
	v_rcp_f32_e32 v3, v3
	s_waitcnt vmcnt(4)
; __device__ __forceinline__ unsigned cvt_pk_bf16(float lo, float hi) { f32x2 v = {lo, hi}; bf16x2_t b = __builtin_convertvector(v, bf16x2_t); return __builtin_bit_cast(unsigned, b); }
; __device__ __forceinline__ float bflo(unsigned w) { return __uint_as_float(w << 16); }
; __device__ __forceinline__ float bfhi(unsigned w) { return __uint_as_float(w & 0xffff0000u); }
;     __device__ __forceinline__ void operator()(const f32x4 (&acc)[2][2][4][2], const Unit& u, int wr, int wc, int fr, int fq) const {
;     ...
;         for (int ai = 0; ai < 2; ++ai)
; #pragma unroll
;             for (int mh = 0; mh < 2; ++mh) {
;                 u32x4 yw[2][2], mw[2][2];
; #pragma unroll
;                 for (int mm = 0; mm < 2; ++mm) {
;                     const int rr = row0 + ai * HALF + (mh * 2 + mm) * 16;
;                     const size_t off = (size_t)rr * DM + col0;
; #pragma unroll
;                     for (int bj = 0; bj < 2; ++bj) {
;                         yw[mm][bj] = *(const u32x4*)(y + off + bj * HALF);
;                         mw[mm][bj] = (u32x4){0u, 0u, 0u, 0u};
;                         if (br != 0) mw[mm][bj] = *(const u32x4*)(merged + tl(rr, col0 + bj * HALF, DM));
;                     }
;                 }
; #pragma unroll
;                 for (int mm = 0; mm < 2; ++mm) {
;                     const int m = mh * 2 + mm;
;                     const int rr = row0 + ai * HALF + m * 16;
; #pragma unroll
;                     for (int bj = 0; bj < 2; ++bj) {
;                         const f32x4 a0 = acc[ai][bj][m][0], a1 = acc[ai][bj][m][1];
;                         const u32x4 yv = yw[mm][bj], mv = mw[mm][bj];
;                         u32x4 w;
;                         w.x = cvt_pk_bf16(sigmoid_f(a0[0]) * bflo(yv.x) + bflo(mv.x), sigmoid_f(a0[1]) * bfhi(yv.x) + bfhi(mv.x));
;                         w.y = cvt_pk_bf16(sigmoid_f(a0[2]) * bflo(yv.y) + bflo(mv.y), sigmoid_f(a0[3]) * bfhi(yv.y) + bfhi(mv.y));
;                         w.z = cvt_pk_bf16(sigmoid_f(a1[0]) * bflo(yv.z) + bflo(mv.z), sigmoid_f(a1[1]) * bfhi(yv.z) + bfhi(mv.z));
;                         w.w = cvt_pk_bf16(sigmoid_f(a1[2]) * bflo(yv.w) + bflo(mv.w), sigmoid_f(a1[3]) * bfhi(yv.w) + bfhi(mv.w));
;                         *(u32x4*)(merged + tl(rr, col0 + bj * HALF, DM)) = w;
;                     }
	v_lshlrev_b32_e32 v198, 16, v128
	v_and_b32_e32 v199, 0xffff0000, v128
	v_lshlrev_b32_e32 v200, 16, v132
	v_and_b32_e32 v201, 0xffff0000, v132
	v_fma_f32 v28, v28, v198, v200
	v_fma_f32 v29, v29, v199, v201
	v_cvt_pk_bf16_f32 v248, v28, v29
	v_lshlrev_b32_e32 v202, 16, v129
	v_and_b32_e32 v203, 0xffff0000, v129
	v_lshlrev_b32_e32 v214, 16, v133
	v_and_b32_e32 v215, 0xffff0000, v133
	v_fma_f32 v30, v30, v202, v214
	v_fma_f32 v31, v31, v203, v215
	v_cvt_pk_bf16_f32 v249, v30, v31
	v_lshlrev_b32_e32 v198, 16, v130
	v_and_b32_e32 v199, 0xffff0000, v130
	v_lshlrev_b32_e32 v200, 16, v134
	v_and_b32_e32 v201, 0xffff0000, v134
	v_fma_f32 v24, v24, v198, v200
	v_fma_f32 v25, v25, v199, v201
	v_cvt_pk_bf16_f32 v250, v24, v25
	v_lshlrev_b32_e32 v202, 16, v131
	v_and_b32_e32 v203, 0xffff0000, v131
	v_lshlrev_b32_e32 v214, 16, v135
	v_and_b32_e32 v215, 0xffff0000, v135
	v_fma_f32 v26, v26, v202, v214
	v_fma_f32 v27, v27, v203, v215
	v_cvt_pk_bf16_f32 v251, v26, v27
	global_store_dwordx4 v194, v[248:251], s[12:13]
	v_lshlrev_b32_e32 v198, 16, v136
	v_and_b32_e32 v199, 0xffff0000, v136
	v_lshlrev_b32_e32 v200, 16, v140
	v_and_b32_e32 v201, 0xffff0000, v140
	v_fma_f32 v20, v20, v198, v200
	v_fma_f32 v21, v21, v199, v201
	v_cvt_pk_bf16_f32 v252, v20, v21
	v_lshlrev_b32_e32 v202, 16, v137
	v_and_b32_e32 v203, 0xffff0000, v137
	v_lshlrev_b32_e32 v214, 16, v141
	v_and_b32_e32 v215, 0xffff0000, v141
	v_fma_f32 v22, v22, v202, v214
	v_fma_f32 v23, v23, v203, v215
	v_cvt_pk_bf16_f32 v253, v22, v23
	v_lshlrev_b32_e32 v198, 16, v138
	v_and_b32_e32 v199, 0xffff0000, v138
	v_lshlrev_b32_e32 v200, 16, v142
	v_and_b32_e32 v201, 0xffff0000, v142
	v_fma_f32 v16, v16, v198, v200
	v_fma_f32 v17, v17, v199, v201
	v_cvt_pk_bf16_f32 v254, v16, v17
	v_lshlrev_b32_e32 v202, 16, v139
	v_and_b32_e32 v203, 0xffff0000, v139
	v_lshlrev_b32_e32 v214, 16, v143
	v_and_b32_e32 v215, 0xffff0000, v143
	v_fma_f32 v18, v18, v202, v214
	v_fma_f32 v19, v19, v203, v215
	v_cvt_pk_bf16_f32 v255, v18, v19
	global_store_dwordx4 v195, v[252:255], s[12:13]
	v_lshlrev_b32_e32 v198, 16, v144
	v_and_b32_e32 v199, 0xffff0000, v144
	v_lshlrev_b32_e32 v200, 16, v148
	v_and_b32_e32 v201, 0xffff0000, v148
	v_fma_f32 v12, v12, v198, v200
	v_fma_f32 v13, v13, v199, v201
	v_cvt_pk_bf16_f32 v206, v12, v13
	v_lshlrev_b32_e32 v202, 16, v145
	v_and_b32_e32 v203, 0xffff0000, v145
	v_lshlrev_b32_e32 v214, 16, v149
	v_and_b32_e32 v215, 0xffff0000, v149
	v_fma_f32 v14, v14, v202, v214
	v_fma_f32 v15, v15, v203, v215
	v_cvt_pk_bf16_f32 v207, v14, v15
	v_lshlrev_b32_e32 v198, 16, v146
	v_and_b32_e32 v199, 0xffff0000, v146
	v_lshlrev_b32_e32 v200, 16, v150
	v_and_b32_e32 v201, 0xffff0000, v150
	v_fma_f32 v8, v8, v198, v200
	v_fma_f32 v9, v9, v199, v201
	v_cvt_pk_bf16_f32 v208, v8, v9
	v_lshlrev_b32_e32 v202, 16, v147
	v_and_b32_e32 v203, 0xffff0000, v147
	v_lshlrev_b32_e32 v214, 16, v151
	v_and_b32_e32 v215, 0xffff0000, v151
	v_fma_f32 v10, v10, v202, v214
	v_fma_f32 v11, v11, v203, v215
	v_cvt_pk_bf16_f32 v209, v10, v11
	global_store_dwordx4 v196, v[206:209], s[12:13]
	v_lshlrev_b32_e32 v198, 16, v152
	v_and_b32_e32 v199, 0xffff0000, v152
	v_lshlrev_b32_e32 v200, 16, v156
	v_and_b32_e32 v201, 0xffff0000, v156
	v_fma_f32 v4, v4, v198, v200
	v_fma_f32 v5, v5, v199, v201
	v_cvt_pk_bf16_f32 v210, v4, v5
	v_lshlrev_b32_e32 v202, 16, v153
	v_and_b32_e32 v203, 0xffff0000, v153
	v_lshlrev_b32_e32 v214, 16, v157
	v_and_b32_e32 v215, 0xffff0000, v157
	v_fma_f32 v6, v6, v202, v214
	v_fma_f32 v7, v7, v203, v215
	v_cvt_pk_bf16_f32 v211, v6, v7
	v_lshlrev_b32_e32 v198, 16, v154
	v_and_b32_e32 v199, 0xffff0000, v154
	v_lshlrev_b32_e32 v200, 16, v158
	v_and_b32_e32 v201, 0xffff0000, v158
	v_fma_f32 v0, v0, v198, v200
	v_fma_f32 v1, v1, v199, v201
	v_cvt_pk_bf16_f32 v212, v0, v1
	v_lshlrev_b32_e32 v202, 16, v155
	v_and_b32_e32 v203, 0xffff0000, v155
	v_lshlrev_b32_e32 v214, 16, v159
	v_and_b32_e32 v215, 0xffff0000, v159
	v_fma_f32 v2, v2, v202, v214
	v_fma_f32 v3, v3, v203, v215
	v_cvt_pk_bf16_f32 v213, v2, v3
	global_store_dwordx4 v197, v[210:213], s[12:13]
	s_branch .Lmy_p9_latch
.Lmy_p9_br0:
	v_mov_b32_e32 v178, v176
	v_mov_b32_e32 v180, v177
	v_add_u32_e32 v181, 0x10000, v177
	v_add_u32_e32 v179, 0x10000, v176
	v_add_u32_e32 v182, 0x800, v177
	v_add_u32_e32 v183, 0x10800, v177
	global_load_dwordx4 v[216:219], v178, s[34:35]
	v_mov_b32_e32 v220, 0
	v_mov_b32_e32 v221, 0
	v_mov_b32_e32 v222, 0
	v_mov_b32_e32 v223, 0
	global_load_dwordx4 v[224:227], v178, s[34:35] offset:256
	v_mov_b32_e32 v228, 0
	v_mov_b32_e32 v229, 0
	v_mov_b32_e32 v230, 0
	v_mov_b32_e32 v231, 0
	global_load_dwordx4 v[232:235], v179, s[34:35]
	v_mov_b32_e32 v236, 0
	v_mov_b32_e32 v237, 0
	v_mov_b32_e32 v238, 0
	v_mov_b32_e32 v239, 0
	global_load_dwordx4 v[240:243], v179, s[34:35] offset:256
	v_mov_b32_e32 v244, 0
	v_mov_b32_e32 v245, 0
	v_mov_b32_e32 v246, 0
	v_mov_b32_e32 v247, 0
	v_add_u32_e32 v192, 0x20000, v176
	v_add_u32_e32 v194, 0x1000, v177
	v_add_u32_e32 v195, 0x11000, v177
	v_add_u32_e32 v193, 0x30000, v176
	v_add_u32_e32 v196, 0x1800, v177
	v_add_u32_e32 v197, 0x11800, v177
	global_load_dwordx4 v[128:131], v192, s[34:35]
	v_mov_b32_e32 v132, 0
	v_mov_b32_e32 v133, 0
	v_mov_b32_e32 v134, 0
	v_mov_b32_e32 v135, 0
	global_load_dwordx4 v[136:139], v192, s[34:35] offset:256
	v_mov_b32_e32 v140, 0
	v_mov_b32_e32 v141, 0
	v_mov_b32_e32 v142, 0
	v_mov_b32_e32 v143, 0
	global_load_dwordx4 v[144:147], v193, s[34:35]
	v_mov_b32_e32 v148, 0
	v_mov_b32_e32 v149, 0
	v_mov_b32_e32 v150, 0
	v_mov_b32_e32 v151, 0
	global_load_dwordx4 v[152:155], v193, s[34:35] offset:256
	v_mov_b32_e32 v156, 0
	v_mov_b32_e32 v157, 0
	v_mov_b32_e32 v158, 0
	v_mov_b32_e32 v159, 0
; __device__ __forceinline__ unsigned cvt_pk_bf16(float lo, float hi) { f32x2 v = {lo, hi}; bf16x2_t b = __builtin_convertvector(v, bf16x2_t); return __builtin_bit_cast(unsigned, b); }
; __device__ __forceinline__ float bflo(unsigned w) { return __uint_as_float(w << 16); }
; __device__ __forceinline__ float sigmoid_f(float x) { return __builtin_amdgcn_rcpf(1.0f + __expf(-x)); }
;     __device__ __forceinline__ void operator()(const f32x4 (&acc)[2][2][4][2], const Unit& u, int wr, int wc, int fr, int fq) const {
;     ...
;         for (int ai = 0; ai < 2; ++ai)
; #pragma unroll
;             for (int mh = 0; mh < 2; ++mh) {
;                 u32x4 yw[2][2], mw[2][2];
; #pragma unroll
;                 for (int mm = 0; mm < 2; ++mm) {
;                     const int rr = row0 + ai * HALF + (mh * 2 + mm) * 16;
;                     const size_t off = (size_t)rr * DM + col0;
; #pragma unroll
;                     for (int bj = 0; bj < 2; ++bj) {
;                         yw[mm][bj] = *(const u32x4*)(y + off + bj * HALF);
;                         mw[mm][bj] = (u32x4){0u, 0u, 0u, 0u};
;                         if (br != 0) mw[mm][bj] = *(const u32x4*)(merged + tl(rr, col0 + bj * HALF, DM));
;                     }
;                 }
; #pragma unroll
;                 for (int mm = 0; mm < 2; ++mm) {
;                     const int m = mh * 2 + mm;
;                     const int rr = row0 + ai * HALF + m * 16;
; #pragma unroll
;                     for (int bj = 0; bj < 2; ++bj) {
;                         const f32x4 a0 = acc[ai][bj][m][0], a1 = acc[ai][bj][m][1];
;                         const u32x4 yv = yw[mm][bj], mv = mw[mm][bj];
;                         u32x4 w;
;                         w.x = cvt_pk_bf16(sigmoid_f(a0[0]) * bflo(yv.x) + bflo(mv.x), sigmoid_f(a0[1]) * bfhi(yv.x) + bfhi(mv.x));
;                         w.y = cvt_pk_bf16(sigmoid_f(a0[2]) * bflo(yv.y) + bflo(mv.y), sigmoid_f(a0[3]) * bfhi(yv.y) + bfhi(mv.y));
;                         w.z = cvt_pk_bf16(sigmoid_f(a1[0]) * bflo(yv.z) + bflo(mv.z), sigmoid_f(a1[1]) * bfhi(yv.z) + bfhi(mv.z));
;                         w.w = cvt_pk_bf16(sigmoid_f(a1[2]) * bflo(yv.w) + bflo(mv.w), sigmoid_f(a1[3]) * bfhi(yv.w) + bfhi(mv.w));
;                         *(u32x4*)(merged + tl(rr, col0 + bj * HALF, DM)) = w;
;                     }
	v_mul_f32_e32 v124, 0xbfb8aa3b, v124
	v_mul_f32_e32 v125, 0xbfb8aa3b, v125
	v_mul_f32_e32 v126, 0xbfb8aa3b, v126
	v_mul_f32_e32 v127, 0xbfb8aa3b, v127
	v_mul_f32_e32 v120, 0xbfb8aa3b, v120
	v_mul_f32_e32 v121, 0xbfb8aa3b, v121
	v_mul_f32_e32 v122, 0xbfb8aa3b, v122
	v_mul_f32_e32 v123, 0xbfb8aa3b, v123
	v_exp_f32_e32 v124, v124
	v_exp_f32_e32 v125, v125
	v_exp_f32_e32 v126, v126
	v_exp_f32_e32 v127, v127
	v_exp_f32_e32 v120, v120
	v_exp_f32_e32 v121, v121
	v_exp_f32_e32 v122, v122
	v_exp_f32_e32 v123, v123
	v_add_f32_e32 v124, 1.0, v124
	v_add_f32_e32 v125, 1.0, v125
	v_add_f32_e32 v126, 1.0, v126
	v_add_f32_e32 v127, 1.0, v127
	v_add_f32_e32 v120, 1.0, v120
	v_add_f32_e32 v121, 1.0, v121
	v_add_f32_e32 v122, 1.0, v122
	v_add_f32_e32 v123, 1.0, v123
	v_rcp_f32_e32 v124, v124
	v_rcp_f32_e32 v125, v125
	v_rcp_f32_e32 v126, v126
	v_rcp_f32_e32 v127, v127
	v_rcp_f32_e32 v120, v120
	v_rcp_f32_e32 v121, v121
	v_rcp_f32_e32 v122, v122
	v_rcp_f32_e32 v123, v123
	v_mul_f32_e32 v116, 0xbfb8aa3b, v116
	v_mul_f32_e32 v117, 0xbfb8aa3b, v117
	v_mul_f32_e32 v118, 0xbfb8aa3b, v118
	v_mul_f32_e32 v119, 0xbfb8aa3b, v119
	v_mul_f32_e32 v112, 0xbfb8aa3b, v112
	v_mul_f32_e32 v113, 0xbfb8aa3b, v113
	v_mul_f32_e32 v114, 0xbfb8aa3b, v114
	v_mul_f32_e32 v115, 0xbfb8aa3b, v115
	v_exp_f32_e32 v116, v116
	v_exp_f32_e32 v117, v117
	v_exp_f32_e32 v118, v118
	v_exp_f32_e32 v119, v119
	v_exp_f32_e32 v112, v112
	v_exp_f32_e32 v113, v113
	v_exp_f32_e32 v114, v114
	v_exp_f32_e32 v115, v115
	v_add_f32_e32 v116, 1.0, v116
	v_add_f32_e32 v117, 1.0, v117
	v_add_f32_e32 v118, 1.0, v118
	v_add_f32_e32 v119, 1.0, v119
	v_add_f32_e32 v112, 1.0, v112
	v_add_f32_e32 v113, 1.0, v113
	v_add_f32_e32 v114, 1.0, v114
	v_add_f32_e32 v115, 1.0, v115
	v_rcp_f32_e32 v116, v116
	v_rcp_f32_e32 v117, v117
	v_rcp_f32_e32 v118, v118
	v_rcp_f32_e32 v119, v119
	v_rcp_f32_e32 v112, v112
	v_rcp_f32_e32 v113, v113
	v_rcp_f32_e32 v114, v114
	v_rcp_f32_e32 v115, v115
	v_mul_f32_e32 v108, 0xbfb8aa3b, v108
	v_mul_f32_e32 v109, 0xbfb8aa3b, v109
	v_mul_f32_e32 v110, 0xbfb8aa3b, v110
	v_mul_f32_e32 v111, 0xbfb8aa3b, v111
	v_mul_f32_e32 v104, 0xbfb8aa3b, v104
	v_mul_f32_e32 v105, 0xbfb8aa3b, v105
	v_mul_f32_e32 v106, 0xbfb8aa3b, v106
	v_mul_f32_e32 v107, 0xbfb8aa3b, v107
	v_exp_f32_e32 v108, v108
	v_exp_f32_e32 v109, v109
	v_exp_f32_e32 v110, v110
	v_exp_f32_e32 v111, v111
	v_exp_f32_e32 v104, v104
	v_exp_f32_e32 v105, v105
	v_exp_f32_e32 v106, v106
	v_exp_f32_e32 v107, v107
	v_add_f32_e32 v108, 1.0, v108
	v_add_f32_e32 v109, 1.0, v109
	v_add_f32_e32 v110, 1.0, v110
	v_add_f32_e32 v111, 1.0, v111
	v_add_f32_e32 v104, 1.0, v104
	v_add_f32_e32 v105, 1.0, v105
	v_add_f32_e32 v106, 1.0, v106
	v_add_f32_e32 v107, 1.0, v107
	v_rcp_f32_e32 v108, v108
	v_rcp_f32_e32 v109, v109
	v_rcp_f32_e32 v110, v110
	v_rcp_f32_e32 v111, v111
	v_rcp_f32_e32 v104, v104
	v_rcp_f32_e32 v105, v105
	v_rcp_f32_e32 v106, v106
	v_rcp_f32_e32 v107, v107
	v_mul_f32_e32 v100, 0xbfb8aa3b, v100
	v_mul_f32_e32 v101, 0xbfb8aa3b, v101
	v_mul_f32_e32 v102, 0xbfb8aa3b, v102
	v_mul_f32_e32 v103, 0xbfb8aa3b, v103
	v_mul_f32_e32 v96, 0xbfb8aa3b, v96
	v_mul_f32_e32 v97, 0xbfb8aa3b, v97
	v_mul_f32_e32 v98, 0xbfb8aa3b, v98
	v_mul_f32_e32 v99, 0xbfb8aa3b, v99
	v_exp_f32_e32 v100, v100
	v_exp_f32_e32 v101, v101
	v_exp_f32_e32 v102, v102
	v_exp_f32_e32 v103, v103
	v_exp_f32_e32 v96, v96
	v_exp_f32_e32 v97, v97
	v_exp_f32_e32 v98, v98
	v_exp_f32_e32 v99, v99
	v_add_f32_e32 v100, 1.0, v100
	v_add_f32_e32 v101, 1.0, v101
	v_add_f32_e32 v102, 1.0, v102
	v_add_f32_e32 v103, 1.0, v103
	v_add_f32_e32 v96, 1.0, v96
	v_add_f32_e32 v97, 1.0, v97
	v_add_f32_e32 v98, 1.0, v98
	v_add_f32_e32 v99, 1.0, v99
	v_rcp_f32_e32 v100, v100
	v_rcp_f32_e32 v101, v101
	v_rcp_f32_e32 v102, v102
	v_rcp_f32_e32 v103, v103
	v_rcp_f32_e32 v96, v96
	v_rcp_f32_e32 v97, v97
	v_rcp_f32_e32 v98, v98
	v_rcp_f32_e32 v99, v99
	s_waitcnt vmcnt(4)
	v_lshlrev_b32_e32 v198, 16, v216
	v_and_b32_e32 v199, 0xffff0000, v216
	v_lshlrev_b32_e32 v200, 16, v220
	v_and_b32_e32 v201, 0xffff0000, v220
	v_fma_f32 v124, v124, v198, v200
	v_fma_f32 v125, v125, v199, v201
	v_cvt_pk_bf16_f32 v248, v124, v125
	v_lshlrev_b32_e32 v202, 16, v217
	v_and_b32_e32 v203, 0xffff0000, v217
	v_lshlrev_b32_e32 v214, 16, v221
	v_and_b32_e32 v215, 0xffff0000, v221
	v_fma_f32 v126, v126, v202, v214
	v_fma_f32 v127, v127, v203, v215
	v_cvt_pk_bf16_f32 v249, v126, v127
	v_lshlrev_b32_e32 v198, 16, v218
	v_and_b32_e32 v199, 0xffff0000, v218
	v_lshlrev_b32_e32 v200, 16, v222
	v_and_b32_e32 v201, 0xffff0000, v222
	v_fma_f32 v120, v120, v198, v200
	v_fma_f32 v121, v121, v199, v201
	v_cvt_pk_bf16_f32 v250, v120, v121
	v_lshlrev_b32_e32 v202, 16, v219
	v_and_b32_e32 v203, 0xffff0000, v219
	v_lshlrev_b32_e32 v214, 16, v223
	v_and_b32_e32 v215, 0xffff0000, v223
	v_fma_f32 v122, v122, v202, v214
	v_fma_f32 v123, v123, v203, v215
	v_cvt_pk_bf16_f32 v251, v122, v123
	global_store_dwordx4 v180, v[248:251], s[12:13]
	v_lshlrev_b32_e32 v198, 16, v224
	v_and_b32_e32 v199, 0xffff0000, v224
	v_lshlrev_b32_e32 v200, 16, v228
	v_and_b32_e32 v201, 0xffff0000, v228
	v_fma_f32 v116, v116, v198, v200
	v_fma_f32 v117, v117, v199, v201
	v_cvt_pk_bf16_f32 v252, v116, v117
	v_lshlrev_b32_e32 v202, 16, v225
	v_and_b32_e32 v203, 0xffff0000, v225
	v_lshlrev_b32_e32 v214, 16, v229
	v_and_b32_e32 v215, 0xffff0000, v229
	v_fma_f32 v118, v118, v202, v214
	v_fma_f32 v119, v119, v203, v215
	v_cvt_pk_bf16_f32 v253, v118, v119
	v_lshlrev_b32_e32 v198, 16, v226
	v_and_b32_e32 v199, 0xffff0000, v226
	v_lshlrev_b32_e32 v200, 16, v230
	v_and_b32_e32 v201, 0xffff0000, v230
	v_fma_f32 v112, v112, v198, v200
	v_fma_f32 v113, v113, v199, v201
	v_cvt_pk_bf16_f32 v254, v112, v113
; __device__ __forceinline__ unsigned cvt_pk_bf16(float lo, float hi) { f32x2 v = {lo, hi}; bf16x2_t b = __builtin_convertvector(v, bf16x2_t); return __builtin_bit_cast(unsigned, b); }
; __device__ __forceinline__ float bflo(unsigned w) { return __uint_as_float(w << 16); }
; __device__ __forceinline__ float bfhi(unsigned w) { return __uint_as_float(w & 0xffff0000u); }
; __device__ __forceinline__ float sigmoid_f(float x) { return __builtin_amdgcn_rcpf(1.0f + __expf(-x)); }
;     __device__ __forceinline__ void operator()(const f32x4 (&acc)[2][2][4][2], const Unit& u, int wr, int wc, int fr, int fq) const {
;     ...
;                 u32x4 yw[2][2], mw[2][2];
; #pragma unroll
;                 for (int mm = 0; mm < 2; ++mm) {
;                     const int rr = row0 + ai * HALF + (mh * 2 + mm) * 16;
;                     const size_t off = (size_t)rr * DM + col0;
; #pragma unroll
;                     for (int bj = 0; bj < 2; ++bj) {
;                         yw[mm][bj] = *(const u32x4*)(y + off + bj * HALF);
;                         mw[mm][bj] = (u32x4){0u, 0u, 0u, 0u};
;                         if (br != 0) mw[mm][bj] = *(const u32x4*)(merged + tl(rr, col0 + bj * HALF, DM));
;                     }
;                 }
; #pragma unroll
;                 for (int mm = 0; mm < 2; ++mm) {
;                     const int m = mh * 2 + mm;
;                     const int rr = row0 + ai * HALF + m * 16;
; #pragma unroll
;                     for (int bj = 0; bj < 2; ++bj) {
;                         const f32x4 a0 = acc[ai][bj][m][0], a1 = acc[ai][bj][m][1];
;                         const u32x4 yv = yw[mm][bj], mv = mw[mm][bj];
;                         u32x4 w;
;                         w.x = cvt_pk_bf16(sigmoid_f(a0[0]) * bflo(yv.x) + bflo(mv.x), sigmoid_f(a0[1]) * bfhi(yv.x) + bfhi(mv.x));
;                         w.y = cvt_pk_bf16(sigmoid_f(a0[2]) * bflo(yv.y) + bflo(mv.y), sigmoid_f(a0[3]) * bfhi(yv.y) + bfhi(mv.y));
;                         w.z = cvt_pk_bf16(sigmoid_f(a1[0]) * bflo(yv.z) + bflo(mv.z), sigmoid_f(a1[1]) * bfhi(yv.z) + bfhi(mv.z));
;                         w.w = cvt_pk_bf16(sigmoid_f(a1[2]) * bflo(yv.w) + bflo(mv.w), sigmoid_f(a1[3]) * bfhi(yv.w) + bfhi(mv.w));
;                         *(u32x4*)(merged + tl(rr, col0 + bj * HALF, DM)) = w;
	v_lshlrev_b32_e32 v202, 16, v227
	v_and_b32_e32 v203, 0xffff0000, v227
	v_lshlrev_b32_e32 v214, 16, v231
	v_and_b32_e32 v215, 0xffff0000, v231
	v_fma_f32 v114, v114, v202, v214
	v_fma_f32 v115, v115, v203, v215
	v_cvt_pk_bf16_f32 v255, v114, v115
	global_store_dwordx4 v181, v[252:255], s[12:13]
	v_lshlrev_b32_e32 v198, 16, v232
	v_and_b32_e32 v199, 0xffff0000, v232
	v_lshlrev_b32_e32 v200, 16, v236
	v_and_b32_e32 v201, 0xffff0000, v236
	v_fma_f32 v108, v108, v198, v200
	v_fma_f32 v109, v109, v199, v201
	v_cvt_pk_bf16_f32 v206, v108, v109
	v_lshlrev_b32_e32 v202, 16, v233
	v_and_b32_e32 v203, 0xffff0000, v233
	v_lshlrev_b32_e32 v214, 16, v237
	v_and_b32_e32 v215, 0xffff0000, v237
	v_fma_f32 v110, v110, v202, v214
	v_fma_f32 v111, v111, v203, v215
	v_cvt_pk_bf16_f32 v207, v110, v111
	v_lshlrev_b32_e32 v198, 16, v234
	v_and_b32_e32 v199, 0xffff0000, v234
	v_lshlrev_b32_e32 v200, 16, v238
	v_and_b32_e32 v201, 0xffff0000, v238
	v_fma_f32 v104, v104, v198, v200
	v_fma_f32 v105, v105, v199, v201
	v_cvt_pk_bf16_f32 v208, v104, v105
	v_lshlrev_b32_e32 v202, 16, v235
	v_and_b32_e32 v203, 0xffff0000, v235
	v_lshlrev_b32_e32 v214, 16, v239
	v_and_b32_e32 v215, 0xffff0000, v239
	v_fma_f32 v106, v106, v202, v214
	v_fma_f32 v107, v107, v203, v215
	v_cvt_pk_bf16_f32 v209, v106, v107
	global_store_dwordx4 v182, v[206:209], s[12:13]
	v_lshlrev_b32_e32 v198, 16, v240
	v_and_b32_e32 v199, 0xffff0000, v240
	v_lshlrev_b32_e32 v200, 16, v244
	v_and_b32_e32 v201, 0xffff0000, v244
	v_fma_f32 v100, v100, v198, v200
	v_fma_f32 v101, v101, v199, v201
	v_cvt_pk_bf16_f32 v210, v100, v101
	v_lshlrev_b32_e32 v202, 16, v241
	v_and_b32_e32 v203, 0xffff0000, v241
	v_lshlrev_b32_e32 v214, 16, v245
	v_and_b32_e32 v215, 0xffff0000, v245
	v_fma_f32 v102, v102, v202, v214
	v_fma_f32 v103, v103, v203, v215
	v_cvt_pk_bf16_f32 v211, v102, v103
	v_lshlrev_b32_e32 v198, 16, v242
	v_and_b32_e32 v199, 0xffff0000, v242
	v_lshlrev_b32_e32 v200, 16, v246
	v_and_b32_e32 v201, 0xffff0000, v246
	v_fma_f32 v96, v96, v198, v200
	v_fma_f32 v97, v97, v199, v201
	v_cvt_pk_bf16_f32 v212, v96, v97
	v_lshlrev_b32_e32 v202, 16, v243
	v_and_b32_e32 v203, 0xffff0000, v243
	v_lshlrev_b32_e32 v214, 16, v247
	v_and_b32_e32 v215, 0xffff0000, v247
	v_fma_f32 v98, v98, v202, v214
	v_fma_f32 v99, v99, v203, v215
	v_cvt_pk_bf16_f32 v213, v98, v99
	global_store_dwordx4 v183, v[210:213], s[12:13]
	v_add_u32_e32 v178, 0x80000, v176
	v_add_u32_e32 v180, 0x4000, v177
	v_add_u32_e32 v181, 0x14000, v177
	v_add_u32_e32 v179, 0x90000, v176
	v_add_u32_e32 v182, 0x4800, v177
	v_add_u32_e32 v183, 0x14800, v177
	global_load_dwordx4 v[216:219], v178, s[34:35]
	v_mov_b32_e32 v220, 0
	v_mov_b32_e32 v221, 0
	v_mov_b32_e32 v222, 0
	v_mov_b32_e32 v223, 0
	global_load_dwordx4 v[224:227], v178, s[34:35] offset:256
	v_mov_b32_e32 v228, 0
	v_mov_b32_e32 v229, 0
	v_mov_b32_e32 v230, 0
	v_mov_b32_e32 v231, 0
	global_load_dwordx4 v[232:235], v179, s[34:35]
	v_mov_b32_e32 v236, 0
	v_mov_b32_e32 v237, 0
	v_mov_b32_e32 v238, 0
	v_mov_b32_e32 v239, 0
	global_load_dwordx4 v[240:243], v179, s[34:35] offset:256
	v_mov_b32_e32 v244, 0
	v_mov_b32_e32 v245, 0
	v_mov_b32_e32 v246, 0
	v_mov_b32_e32 v247, 0
	v_mul_f32_e32 v92, 0xbfb8aa3b, v92
	v_mul_f32_e32 v93, 0xbfb8aa3b, v93
	v_mul_f32_e32 v94, 0xbfb8aa3b, v94
	v_mul_f32_e32 v95, 0xbfb8aa3b, v95
	v_mul_f32_e32 v88, 0xbfb8aa3b, v88
	v_mul_f32_e32 v89, 0xbfb8aa3b, v89
	v_mul_f32_e32 v90, 0xbfb8aa3b, v90
	v_mul_f32_e32 v91, 0xbfb8aa3b, v91
	v_exp_f32_e32 v92, v92
	v_exp_f32_e32 v93, v93
	v_exp_f32_e32 v94, v94
	v_exp_f32_e32 v95, v95
	v_exp_f32_e32 v88, v88
	v_exp_f32_e32 v89, v89
	v_exp_f32_e32 v90, v90
	v_exp_f32_e32 v91, v91
	v_add_f32_e32 v92, 1.0, v92
	v_add_f32_e32 v93, 1.0, v93
	v_add_f32_e32 v94, 1.0, v94
	v_add_f32_e32 v95, 1.0, v95
	v_add_f32_e32 v88, 1.0, v88
	v_add_f32_e32 v89, 1.0, v89
	v_add_f32_e32 v90, 1.0, v90
	v_add_f32_e32 v91, 1.0, v91
	v_rcp_f32_e32 v92, v92
	v_rcp_f32_e32 v93, v93
	v_rcp_f32_e32 v94, v94
	v_rcp_f32_e32 v95, v95
	v_rcp_f32_e32 v88, v88
	v_rcp_f32_e32 v89, v89
	v_rcp_f32_e32 v90, v90
	v_rcp_f32_e32 v91, v91
	v_mul_f32_e32 v84, 0xbfb8aa3b, v84
	v_mul_f32_e32 v85, 0xbfb8aa3b, v85
	v_mul_f32_e32 v86, 0xbfb8aa3b, v86
	v_mul_f32_e32 v87, 0xbfb8aa3b, v87
	v_mul_f32_e32 v80, 0xbfb8aa3b, v80
	v_mul_f32_e32 v81, 0xbfb8aa3b, v81
	v_mul_f32_e32 v82, 0xbfb8aa3b, v82
	v_mul_f32_e32 v83, 0xbfb8aa3b, v83
	v_exp_f32_e32 v84, v84
	v_exp_f32_e32 v85, v85
	v_exp_f32_e32 v86, v86
	v_exp_f32_e32 v87, v87
	v_exp_f32_e32 v80, v80
	v_exp_f32_e32 v81, v81
	v_exp_f32_e32 v82, v82
	v_exp_f32_e32 v83, v83
	v_add_f32_e32 v84, 1.0, v84
	v_add_f32_e32 v85, 1.0, v85
	v_add_f32_e32 v86, 1.0, v86
	v_add_f32_e32 v87, 1.0, v87
	v_add_f32_e32 v80, 1.0, v80
	v_add_f32_e32 v81, 1.0, v81
	v_add_f32_e32 v82, 1.0, v82
	v_add_f32_e32 v83, 1.0, v83
	v_rcp_f32_e32 v84, v84
	v_rcp_f32_e32 v85, v85
	v_rcp_f32_e32 v86, v86
	v_rcp_f32_e32 v87, v87
	v_rcp_f32_e32 v80, v80
	v_rcp_f32_e32 v81, v81
	v_rcp_f32_e32 v82, v82
	v_rcp_f32_e32 v83, v83
	v_mul_f32_e32 v76, 0xbfb8aa3b, v76
	v_mul_f32_e32 v77, 0xbfb8aa3b, v77
	v_mul_f32_e32 v78, 0xbfb8aa3b, v78
	v_mul_f32_e32 v79, 0xbfb8aa3b, v79
	v_mul_f32_e32 v72, 0xbfb8aa3b, v72
	v_mul_f32_e32 v73, 0xbfb8aa3b, v73
	v_mul_f32_e32 v74, 0xbfb8aa3b, v74
	v_mul_f32_e32 v75, 0xbfb8aa3b, v75
	v_exp_f32_e32 v76, v76
	v_exp_f32_e32 v77, v77
	v_exp_f32_e32 v78, v78
	v_exp_f32_e32 v79, v79
	v_exp_f32_e32 v72, v72
	v_exp_f32_e32 v73, v73
	v_exp_f32_e32 v74, v74
	v_exp_f32_e32 v75, v75
	v_add_f32_e32 v76, 1.0, v76
	v_add_f32_e32 v77, 1.0, v77
	v_add_f32_e32 v78, 1.0, v78
	v_add_f32_e32 v79, 1.0, v79
	v_add_f32_e32 v72, 1.0, v72
	v_add_f32_e32 v73, 1.0, v73
	v_add_f32_e32 v74, 1.0, v74
	v_add_f32_e32 v75, 1.0, v75
	v_rcp_f32_e32 v76, v76
	v_rcp_f32_e32 v77, v77
	v_rcp_f32_e32 v78, v78
	v_rcp_f32_e32 v79, v79
	v_rcp_f32_e32 v72, v72
	v_rcp_f32_e32 v73, v73
	v_rcp_f32_e32 v74, v74
	v_rcp_f32_e32 v75, v75
	v_mul_f32_e32 v68, 0xbfb8aa3b, v68
	v_mul_f32_e32 v69, 0xbfb8aa3b, v69
	v_mul_f32_e32 v70, 0xbfb8aa3b, v70
	v_mul_f32_e32 v71, 0xbfb8aa3b, v71
	v_mul_f32_e32 v64, 0xbfb8aa3b, v64
	v_mul_f32_e32 v65, 0xbfb8aa3b, v65
	v_mul_f32_e32 v66, 0xbfb8aa3b, v66
	v_mul_f32_e32 v67, 0xbfb8aa3b, v67
	v_exp_f32_e32 v68, v68
	v_exp_f32_e32 v69, v69
	v_exp_f32_e32 v70, v70
	v_exp_f32_e32 v71, v71
	v_exp_f32_e32 v64, v64
	v_exp_f32_e32 v65, v65
	v_exp_f32_e32 v66, v66
	v_exp_f32_e32 v67, v67
	v_add_f32_e32 v68, 1.0, v68
	v_add_f32_e32 v69, 1.0, v69
	v_add_f32_e32 v70, 1.0, v70
	v_add_f32_e32 v71, 1.0, v71
	v_add_f32_e32 v64, 1.0, v64
	v_add_f32_e32 v65, 1.0, v65
	v_add_f32_e32 v66, 1.0, v66
	v_add_f32_e32 v67, 1.0, v67
	v_rcp_f32_e32 v68, v68
	v_rcp_f32_e32 v69, v69
	v_rcp_f32_e32 v70, v70
	v_rcp_f32_e32 v71, v71
	v_rcp_f32_e32 v64, v64
	v_rcp_f32_e32 v65, v65
	v_rcp_f32_e32 v66, v66
	v_rcp_f32_e32 v67, v67
	s_waitcnt vmcnt(8)
; __device__ __forceinline__ unsigned cvt_pk_bf16(float lo, float hi) { f32x2 v = {lo, hi}; bf16x2_t b = __builtin_convertvector(v, bf16x2_t); return __builtin_bit_cast(unsigned, b); }
; __device__ __forceinline__ float bflo(unsigned w) { return __uint_as_float(w << 16); }
; __device__ __forceinline__ float bfhi(unsigned w) { return __uint_as_float(w & 0xffff0000u); }
; __device__ __forceinline__ float sigmoid_f(float x) { return __builtin_amdgcn_rcpf(1.0f + __expf(-x)); }
;     __device__ __forceinline__ void operator()(const f32x4 (&acc)[2][2][4][2], const Unit& u, int wr, int wc, int fr, int fq) const {
;     ...
;                 u32x4 yw[2][2], mw[2][2];
; #pragma unroll
;                 for (int mm = 0; mm < 2; ++mm) {
;                     const int rr = row0 + ai * HALF + (mh * 2 + mm) * 16;
;                     const size_t off = (size_t)rr * DM + col0;
; #pragma unroll
;                     for (int bj = 0; bj < 2; ++bj) {
;                         yw[mm][bj] = *(const u32x4*)(y + off + bj * HALF);
;                         mw[mm][bj] = (u32x4){0u, 0u, 0u, 0u};
;                         if (br != 0) mw[mm][bj] = *(const u32x4*)(merged + tl(rr, col0 + bj * HALF, DM));
;                     }
;                 }
; #pragma unroll
;                 for (int mm = 0; mm < 2; ++mm) {
;                     const int m = mh * 2 + mm;
;                     const int rr = row0 + ai * HALF + m * 16;
; #pragma unroll
;                     for (int bj = 0; bj < 2; ++bj) {
;                         const f32x4 a0 = acc[ai][bj][m][0], a1 = acc[ai][bj][m][1];
;                         const u32x4 yv = yw[mm][bj], mv = mw[mm][bj];
;                         u32x4 w;
;                         w.x = cvt_pk_bf16(sigmoid_f(a0[0]) * bflo(yv.x) + bflo(mv.x), sigmoid_f(a0[1]) * bfhi(yv.x) + bfhi(mv.x));
;                         w.y = cvt_pk_bf16(sigmoid_f(a0[2]) * bflo(yv.y) + bflo(mv.y), sigmoid_f(a0[3]) * bfhi(yv.y) + bfhi(mv.y));
;                         w.z = cvt_pk_bf16(sigmoid_f(a1[0]) * bflo(yv.z) + bflo(mv.z), sigmoid_f(a1[1]) * bfhi(yv.z) + bfhi(mv.z));
;                         w.w = cvt_pk_bf16(sigmoid_f(a1[2]) * bflo(yv.w) + bflo(mv.w), sigmoid_f(a1[3]) * bfhi(yv.w) + bfhi(mv.w));
;                         *(u32x4*)(merged + tl(rr, col0 + bj * HALF, DM)) = w;
	v_lshlrev_b32_e32 v198, 16, v128
	v_and_b32_e32 v199, 0xffff0000, v128
	v_lshlrev_b32_e32 v200, 16, v132
	v_and_b32_e32 v201, 0xffff0000, v132
	v_fma_f32 v92, v92, v198, v200
	v_fma_f32 v93, v93, v199, v201
	v_cvt_pk_bf16_f32 v248, v92, v93
	v_lshlrev_b32_e32 v202, 16, v129
	v_and_b32_e32 v203, 0xffff0000, v129
	v_lshlrev_b32_e32 v214, 16, v133
	v_and_b32_e32 v215, 0xffff0000, v133
	v_fma_f32 v94, v94, v202, v214
	v_fma_f32 v95, v95, v203, v215
	v_cvt_pk_bf16_f32 v249, v94, v95
	v_lshlrev_b32_e32 v198, 16, v130
	v_and_b32_e32 v199, 0xffff0000, v130
	v_lshlrev_b32_e32 v200, 16, v134
	v_and_b32_e32 v201, 0xffff0000, v134
	v_fma_f32 v88, v88, v198, v200
	v_fma_f32 v89, v89, v199, v201
	v_cvt_pk_bf16_f32 v250, v88, v89
	v_lshlrev_b32_e32 v202, 16, v131
	v_and_b32_e32 v203, 0xffff0000, v131
	v_lshlrev_b32_e32 v214, 16, v135
	v_and_b32_e32 v215, 0xffff0000, v135
	v_fma_f32 v90, v90, v202, v214
	v_fma_f32 v91, v91, v203, v215
	v_cvt_pk_bf16_f32 v251, v90, v91
	global_store_dwordx4 v194, v[248:251], s[12:13]
	v_lshlrev_b32_e32 v198, 16, v136
	v_and_b32_e32 v199, 0xffff0000, v136
	v_lshlrev_b32_e32 v200, 16, v140
	v_and_b32_e32 v201, 0xffff0000, v140
	v_fma_f32 v84, v84, v198, v200
	v_fma_f32 v85, v85, v199, v201
	v_cvt_pk_bf16_f32 v252, v84, v85
	v_lshlrev_b32_e32 v202, 16, v137
	v_and_b32_e32 v203, 0xffff0000, v137
	v_lshlrev_b32_e32 v214, 16, v141
	v_and_b32_e32 v215, 0xffff0000, v141
	v_fma_f32 v86, v86, v202, v214
	v_fma_f32 v87, v87, v203, v215
	v_cvt_pk_bf16_f32 v253, v86, v87
	v_lshlrev_b32_e32 v198, 16, v138
	v_and_b32_e32 v199, 0xffff0000, v138
	v_lshlrev_b32_e32 v200, 16, v142
	v_and_b32_e32 v201, 0xffff0000, v142
	v_fma_f32 v80, v80, v198, v200
	v_fma_f32 v81, v81, v199, v201
	v_cvt_pk_bf16_f32 v254, v80, v81
	v_lshlrev_b32_e32 v202, 16, v139
	v_and_b32_e32 v203, 0xffff0000, v139
	v_lshlrev_b32_e32 v214, 16, v143
	v_and_b32_e32 v215, 0xffff0000, v143
	v_fma_f32 v82, v82, v202, v214
	v_fma_f32 v83, v83, v203, v215
	v_cvt_pk_bf16_f32 v255, v82, v83
	global_store_dwordx4 v195, v[252:255], s[12:13]
	v_lshlrev_b32_e32 v198, 16, v144
	v_and_b32_e32 v199, 0xffff0000, v144
	v_lshlrev_b32_e32 v200, 16, v148
	v_and_b32_e32 v201, 0xffff0000, v148
	v_fma_f32 v76, v76, v198, v200
	v_fma_f32 v77, v77, v199, v201
	v_cvt_pk_bf16_f32 v206, v76, v77
	v_lshlrev_b32_e32 v202, 16, v145
	v_and_b32_e32 v203, 0xffff0000, v145
	v_lshlrev_b32_e32 v214, 16, v149
	v_and_b32_e32 v215, 0xffff0000, v149
	v_fma_f32 v78, v78, v202, v214
	v_fma_f32 v79, v79, v203, v215
	v_cvt_pk_bf16_f32 v207, v78, v79
	v_lshlrev_b32_e32 v198, 16, v146
	v_and_b32_e32 v199, 0xffff0000, v146
	v_lshlrev_b32_e32 v200, 16, v150
	v_and_b32_e32 v201, 0xffff0000, v150
	v_fma_f32 v72, v72, v198, v200
	v_fma_f32 v73, v73, v199, v201
	v_cvt_pk_bf16_f32 v208, v72, v73
	v_lshlrev_b32_e32 v202, 16, v147
	v_and_b32_e32 v203, 0xffff0000, v147
	v_lshlrev_b32_e32 v214, 16, v151
	v_and_b32_e32 v215, 0xffff0000, v151
	v_fma_f32 v74, v74, v202, v214
	v_fma_f32 v75, v75, v203, v215
	v_cvt_pk_bf16_f32 v209, v74, v75
	global_store_dwordx4 v196, v[206:209], s[12:13]
	v_lshlrev_b32_e32 v198, 16, v152
	v_and_b32_e32 v199, 0xffff0000, v152
	v_lshlrev_b32_e32 v200, 16, v156
	v_and_b32_e32 v201, 0xffff0000, v156
	v_fma_f32 v68, v68, v198, v200
	v_fma_f32 v69, v69, v199, v201
	v_cvt_pk_bf16_f32 v210, v68, v69
	v_lshlrev_b32_e32 v202, 16, v153
	v_and_b32_e32 v203, 0xffff0000, v153
	v_lshlrev_b32_e32 v214, 16, v157
	v_and_b32_e32 v215, 0xffff0000, v157
	v_fma_f32 v70, v70, v202, v214
	v_fma_f32 v71, v71, v203, v215
	v_cvt_pk_bf16_f32 v211, v70, v71
	v_lshlrev_b32_e32 v198, 16, v154
	v_and_b32_e32 v199, 0xffff0000, v154
	v_lshlrev_b32_e32 v200, 16, v158
	v_and_b32_e32 v201, 0xffff0000, v158
	v_fma_f32 v64, v64, v198, v200
	v_fma_f32 v65, v65, v199, v201
	v_cvt_pk_bf16_f32 v212, v64, v65
	v_lshlrev_b32_e32 v202, 16, v155
	v_and_b32_e32 v203, 0xffff0000, v155
	v_lshlrev_b32_e32 v214, 16, v159
	v_and_b32_e32 v215, 0xffff0000, v159
	v_fma_f32 v66, v66, v202, v214
	v_fma_f32 v67, v67, v203, v215
	v_cvt_pk_bf16_f32 v213, v66, v67
	global_store_dwordx4 v197, v[210:213], s[12:13]
	v_add_u32_e32 v192, 0xa0000, v176
	v_add_u32_e32 v194, 0x5000, v177
	v_add_u32_e32 v195, 0x15000, v177
	v_add_u32_e32 v193, 0xb0000, v176
	v_add_u32_e32 v196, 0x5800, v177
	v_add_u32_e32 v197, 0x15800, v177
	global_load_dwordx4 v[128:131], v192, s[34:35]
	v_mov_b32_e32 v132, 0
	v_mov_b32_e32 v133, 0
	v_mov_b32_e32 v134, 0
	v_mov_b32_e32 v135, 0
	global_load_dwordx4 v[136:139], v192, s[34:35] offset:256
	v_mov_b32_e32 v140, 0
	v_mov_b32_e32 v141, 0
	v_mov_b32_e32 v142, 0
	v_mov_b32_e32 v143, 0
	global_load_dwordx4 v[144:147], v193, s[34:35]
	v_mov_b32_e32 v148, 0
	v_mov_b32_e32 v149, 0
	v_mov_b32_e32 v150, 0
	v_mov_b32_e32 v151, 0
	global_load_dwordx4 v[152:155], v193, s[34:35] offset:256
	v_mov_b32_e32 v156, 0
	v_mov_b32_e32 v157, 0
	v_mov_b32_e32 v158, 0
	v_mov_b32_e32 v159, 0
	v_mul_f32_e32 v60, 0xbfb8aa3b, v60
	v_mul_f32_e32 v61, 0xbfb8aa3b, v61
	v_mul_f32_e32 v62, 0xbfb8aa3b, v62
	v_mul_f32_e32 v63, 0xbfb8aa3b, v63
	v_mul_f32_e32 v56, 0xbfb8aa3b, v56
	v_mul_f32_e32 v57, 0xbfb8aa3b, v57
	v_mul_f32_e32 v58, 0xbfb8aa3b, v58
	v_mul_f32_e32 v59, 0xbfb8aa3b, v59
	v_exp_f32_e32 v60, v60
	v_exp_f32_e32 v61, v61
	v_exp_f32_e32 v62, v62
	v_exp_f32_e32 v63, v63
	v_exp_f32_e32 v56, v56
	v_exp_f32_e32 v57, v57
	v_exp_f32_e32 v58, v58
	v_exp_f32_e32 v59, v59
	v_add_f32_e32 v60, 1.0, v60
	v_add_f32_e32 v61, 1.0, v61
	v_add_f32_e32 v62, 1.0, v62
	v_add_f32_e32 v63, 1.0, v63
	v_add_f32_e32 v56, 1.0, v56
	v_add_f32_e32 v57, 1.0, v57
	v_add_f32_e32 v58, 1.0, v58
	v_add_f32_e32 v59, 1.0, v59
	v_rcp_f32_e32 v60, v60
	v_rcp_f32_e32 v61, v61
	v_rcp_f32_e32 v62, v62
; __device__ __forceinline__ unsigned cvt_pk_bf16(float lo, float hi) { f32x2 v = {lo, hi}; bf16x2_t b = __builtin_convertvector(v, bf16x2_t); return __builtin_bit_cast(unsigned, b); }
; __device__ __forceinline__ float bflo(unsigned w) { return __uint_as_float(w << 16); }
; __device__ __forceinline__ float bfhi(unsigned w) { return __uint_as_float(w & 0xffff0000u); }
; __device__ __forceinline__ float sigmoid_f(float x) { return __builtin_amdgcn_rcpf(1.0f + __expf(-x)); }
;     __device__ __forceinline__ void operator()(const f32x4 (&acc)[2][2][4][2], const Unit& u, int wr, int wc, int fr, int fq) const {
;     ...
;                 u32x4 yw[2][2], mw[2][2];
; #pragma unroll
;                 for (int mm = 0; mm < 2; ++mm) {
;                     const int rr = row0 + ai * HALF + (mh * 2 + mm) * 16;
;                     const size_t off = (size_t)rr * DM + col0;
; #pragma unroll
;                     for (int bj = 0; bj < 2; ++bj) {
;                         yw[mm][bj] = *(const u32x4*)(y + off + bj * HALF);
;                         mw[mm][bj] = (u32x4){0u, 0u, 0u, 0u};
;                         if (br != 0) mw[mm][bj] = *(const u32x4*)(merged + tl(rr, col0 + bj * HALF, DM));
;                     }
;                 }
; #pragma unroll
;                 for (int mm = 0; mm < 2; ++mm) {
;                     const int m = mh * 2 + mm;
;                     const int rr = row0 + ai * HALF + m * 16;
; #pragma unroll
;                     for (int bj = 0; bj < 2; ++bj) {
;                         const f32x4 a0 = acc[ai][bj][m][0], a1 = acc[ai][bj][m][1];
;                         const u32x4 yv = yw[mm][bj], mv = mw[mm][bj];
;                         u32x4 w;
;                         w.x = cvt_pk_bf16(sigmoid_f(a0[0]) * bflo(yv.x) + bflo(mv.x), sigmoid_f(a0[1]) * bfhi(yv.x) + bfhi(mv.x));
;                         w.y = cvt_pk_bf16(sigmoid_f(a0[2]) * bflo(yv.y) + bflo(mv.y), sigmoid_f(a0[3]) * bfhi(yv.y) + bfhi(mv.y));
;                         w.z = cvt_pk_bf16(sigmoid_f(a1[0]) * bflo(yv.z) + bflo(mv.z), sigmoid_f(a1[1]) * bfhi(yv.z) + bfhi(mv.z));
;                         w.w = cvt_pk_bf16(sigmoid_f(a1[2]) * bflo(yv.w) + bflo(mv.w), sigmoid_f(a1[3]) * bfhi(yv.w) + bfhi(mv.w));
;                         *(u32x4*)(merged + tl(rr, col0 + bj * HALF, DM)) = w;
	v_rcp_f32_e32 v63, v63
	v_rcp_f32_e32 v56, v56
	v_rcp_f32_e32 v57, v57
	v_rcp_f32_e32 v58, v58
	v_rcp_f32_e32 v59, v59
	v_mul_f32_e32 v52, 0xbfb8aa3b, v52
	v_mul_f32_e32 v53, 0xbfb8aa3b, v53
	v_mul_f32_e32 v54, 0xbfb8aa3b, v54
	v_mul_f32_e32 v55, 0xbfb8aa3b, v55
	v_mul_f32_e32 v48, 0xbfb8aa3b, v48
	v_mul_f32_e32 v49, 0xbfb8aa3b, v49
	v_mul_f32_e32 v50, 0xbfb8aa3b, v50
	v_mul_f32_e32 v51, 0xbfb8aa3b, v51
	v_exp_f32_e32 v52, v52
	v_exp_f32_e32 v53, v53
	v_exp_f32_e32 v54, v54
	v_exp_f32_e32 v55, v55
	v_exp_f32_e32 v48, v48
	v_exp_f32_e32 v49, v49
	v_exp_f32_e32 v50, v50
	v_exp_f32_e32 v51, v51
	v_add_f32_e32 v52, 1.0, v52
	v_add_f32_e32 v53, 1.0, v53
	v_add_f32_e32 v54, 1.0, v54
	v_add_f32_e32 v55, 1.0, v55
	v_add_f32_e32 v48, 1.0, v48
	v_add_f32_e32 v49, 1.0, v49
	v_add_f32_e32 v50, 1.0, v50
	v_add_f32_e32 v51, 1.0, v51
	v_rcp_f32_e32 v52, v52
	v_rcp_f32_e32 v53, v53
	v_rcp_f32_e32 v54, v54
	v_rcp_f32_e32 v55, v55
	v_rcp_f32_e32 v48, v48
	v_rcp_f32_e32 v49, v49
	v_rcp_f32_e32 v50, v50
	v_rcp_f32_e32 v51, v51
	v_mul_f32_e32 v44, 0xbfb8aa3b, v44
	v_mul_f32_e32 v45, 0xbfb8aa3b, v45
	v_mul_f32_e32 v46, 0xbfb8aa3b, v46
	v_mul_f32_e32 v47, 0xbfb8aa3b, v47
	v_mul_f32_e32 v40, 0xbfb8aa3b, v40
	v_mul_f32_e32 v41, 0xbfb8aa3b, v41
	v_mul_f32_e32 v42, 0xbfb8aa3b, v42
	v_mul_f32_e32 v43, 0xbfb8aa3b, v43
	v_exp_f32_e32 v44, v44
	v_exp_f32_e32 v45, v45
	v_exp_f32_e32 v46, v46
	v_exp_f32_e32 v47, v47
	v_exp_f32_e32 v40, v40
	v_exp_f32_e32 v41, v41
	v_exp_f32_e32 v42, v42
	v_exp_f32_e32 v43, v43
	v_add_f32_e32 v44, 1.0, v44
	v_add_f32_e32 v45, 1.0, v45
	v_add_f32_e32 v46, 1.0, v46
	v_add_f32_e32 v47, 1.0, v47
	v_add_f32_e32 v40, 1.0, v40
	v_add_f32_e32 v41, 1.0, v41
	v_add_f32_e32 v42, 1.0, v42
	v_add_f32_e32 v43, 1.0, v43
	v_rcp_f32_e32 v44, v44
	v_rcp_f32_e32 v45, v45
	v_rcp_f32_e32 v46, v46
	v_rcp_f32_e32 v47, v47
	v_rcp_f32_e32 v40, v40
	v_rcp_f32_e32 v41, v41
	v_rcp_f32_e32 v42, v42
	v_rcp_f32_e32 v43, v43
	v_mul_f32_e32 v36, 0xbfb8aa3b, v36
	v_mul_f32_e32 v37, 0xbfb8aa3b, v37
	v_mul_f32_e32 v38, 0xbfb8aa3b, v38
	v_mul_f32_e32 v39, 0xbfb8aa3b, v39
	v_mul_f32_e32 v32, 0xbfb8aa3b, v32
	v_mul_f32_e32 v33, 0xbfb8aa3b, v33
	v_mul_f32_e32 v34, 0xbfb8aa3b, v34
	v_mul_f32_e32 v35, 0xbfb8aa3b, v35
	v_exp_f32_e32 v36, v36
	v_exp_f32_e32 v37, v37
	v_exp_f32_e32 v38, v38
	v_exp_f32_e32 v39, v39
	v_exp_f32_e32 v32, v32
	v_exp_f32_e32 v33, v33
	v_exp_f32_e32 v34, v34
	v_exp_f32_e32 v35, v35
	v_add_f32_e32 v36, 1.0, v36
	v_add_f32_e32 v37, 1.0, v37
	v_add_f32_e32 v38, 1.0, v38
	v_add_f32_e32 v39, 1.0, v39
	v_add_f32_e32 v32, 1.0, v32
	v_add_f32_e32 v33, 1.0, v33
	v_add_f32_e32 v34, 1.0, v34
	v_add_f32_e32 v35, 1.0, v35
	v_rcp_f32_e32 v36, v36
	v_rcp_f32_e32 v37, v37
	v_rcp_f32_e32 v38, v38
	v_rcp_f32_e32 v39, v39
	v_rcp_f32_e32 v32, v32
	v_rcp_f32_e32 v33, v33
	v_rcp_f32_e32 v34, v34
	v_rcp_f32_e32 v35, v35
	s_waitcnt vmcnt(8)
	v_lshlrev_b32_e32 v198, 16, v216
	v_and_b32_e32 v199, 0xffff0000, v216
	v_lshlrev_b32_e32 v200, 16, v220
	v_and_b32_e32 v201, 0xffff0000, v220
	v_fma_f32 v60, v60, v198, v200
	v_fma_f32 v61, v61, v199, v201
	v_cvt_pk_bf16_f32 v248, v60, v61
	v_lshlrev_b32_e32 v202, 16, v217
	v_and_b32_e32 v203, 0xffff0000, v217
	v_lshlrev_b32_e32 v214, 16, v221
	v_and_b32_e32 v215, 0xffff0000, v221
	v_fma_f32 v62, v62, v202, v214
	v_fma_f32 v63, v63, v203, v215
	v_cvt_pk_bf16_f32 v249, v62, v63
	v_lshlrev_b32_e32 v198, 16, v218
	v_and_b32_e32 v199, 0xffff0000, v218
	v_lshlrev_b32_e32 v200, 16, v222
	v_and_b32_e32 v201, 0xffff0000, v222
	v_fma_f32 v56, v56, v198, v200
	v_fma_f32 v57, v57, v199, v201
	v_cvt_pk_bf16_f32 v250, v56, v57
	v_lshlrev_b32_e32 v202, 16, v219
	v_and_b32_e32 v203, 0xffff0000, v219
	v_lshlrev_b32_e32 v214, 16, v223
	v_and_b32_e32 v215, 0xffff0000, v223
	v_fma_f32 v58, v58, v202, v214
	v_fma_f32 v59, v59, v203, v215
	v_cvt_pk_bf16_f32 v251, v58, v59
	global_store_dwordx4 v180, v[248:251], s[12:13]
	v_lshlrev_b32_e32 v198, 16, v224
	v_and_b32_e32 v199, 0xffff0000, v224
	v_lshlrev_b32_e32 v200, 16, v228
	v_and_b32_e32 v201, 0xffff0000, v228
	v_fma_f32 v52, v52, v198, v200
	v_fma_f32 v53, v53, v199, v201
	v_cvt_pk_bf16_f32 v252, v52, v53
	v_lshlrev_b32_e32 v202, 16, v225
	v_and_b32_e32 v203, 0xffff0000, v225
	v_lshlrev_b32_e32 v214, 16, v229
	v_and_b32_e32 v215, 0xffff0000, v229
	v_fma_f32 v54, v54, v202, v214
	v_fma_f32 v55, v55, v203, v215
	v_cvt_pk_bf16_f32 v253, v54, v55
	v_lshlrev_b32_e32 v198, 16, v226
	v_and_b32_e32 v199, 0xffff0000, v226
	v_lshlrev_b32_e32 v200, 16, v230
	v_and_b32_e32 v201, 0xffff0000, v230
	v_fma_f32 v48, v48, v198, v200
	v_fma_f32 v49, v49, v199, v201
	v_cvt_pk_bf16_f32 v254, v48, v49
	v_lshlrev_b32_e32 v202, 16, v227
	v_and_b32_e32 v203, 0xffff0000, v227
	v_lshlrev_b32_e32 v214, 16, v231
	v_and_b32_e32 v215, 0xffff0000, v231
	v_fma_f32 v50, v50, v202, v214
	v_fma_f32 v51, v51, v203, v215
	v_cvt_pk_bf16_f32 v255, v50, v51
	global_store_dwordx4 v181, v[252:255], s[12:13]
	v_lshlrev_b32_e32 v198, 16, v232
	v_and_b32_e32 v199, 0xffff0000, v232
	v_lshlrev_b32_e32 v200, 16, v236
	v_and_b32_e32 v201, 0xffff0000, v236
	v_fma_f32 v44, v44, v198, v200
	v_fma_f32 v45, v45, v199, v201
	v_cvt_pk_bf16_f32 v206, v44, v45
	v_lshlrev_b32_e32 v202, 16, v233
	v_and_b32_e32 v203, 0xffff0000, v233
	v_lshlrev_b32_e32 v214, 16, v237
	v_and_b32_e32 v215, 0xffff0000, v237
	v_fma_f32 v46, v46, v202, v214
	v_fma_f32 v47, v47, v203, v215
	v_cvt_pk_bf16_f32 v207, v46, v47
	v_lshlrev_b32_e32 v198, 16, v234
	v_and_b32_e32 v199, 0xffff0000, v234
	v_lshlrev_b32_e32 v200, 16, v238
	v_and_b32_e32 v201, 0xffff0000, v238
	v_fma_f32 v40, v40, v198, v200
	v_fma_f32 v41, v41, v199, v201
	v_cvt_pk_bf16_f32 v208, v40, v41
	v_lshlrev_b32_e32 v202, 16, v235
; __device__ __forceinline__ unsigned cvt_pk_bf16(float lo, float hi) { f32x2 v = {lo, hi}; bf16x2_t b = __builtin_convertvector(v, bf16x2_t); return __builtin_bit_cast(unsigned, b); }
; __device__ __forceinline__ float bflo(unsigned w) { return __uint_as_float(w << 16); }
; __device__ __forceinline__ float bfhi(unsigned w) { return __uint_as_float(w & 0xffff0000u); }
; __device__ __forceinline__ float sigmoid_f(float x) { return __builtin_amdgcn_rcpf(1.0f + __expf(-x)); }
;     __device__ __forceinline__ void operator()(const f32x4 (&acc)[2][2][4][2], const Unit& u, int wr, int wc, int fr, int fq) const {
;     ...
;                 u32x4 yw[2][2], mw[2][2];
; #pragma unroll
;                 for (int mm = 0; mm < 2; ++mm) {
;                     const int rr = row0 + ai * HALF + (mh * 2 + mm) * 16;
;                     const size_t off = (size_t)rr * DM + col0;
; #pragma unroll
;                     for (int bj = 0; bj < 2; ++bj) {
;                         yw[mm][bj] = *(const u32x4*)(y + off + bj * HALF);
;                         mw[mm][bj] = (u32x4){0u, 0u, 0u, 0u};
;                         if (br != 0) mw[mm][bj] = *(const u32x4*)(merged + tl(rr, col0 + bj * HALF, DM));
;                     }
;                 }
; #pragma unroll
;                 for (int mm = 0; mm < 2; ++mm) {
;                     const int m = mh * 2 + mm;
;                     const int rr = row0 + ai * HALF + m * 16;
; #pragma unroll
;                     for (int bj = 0; bj < 2; ++bj) {
;                         const f32x4 a0 = acc[ai][bj][m][0], a1 = acc[ai][bj][m][1];
;                         const u32x4 yv = yw[mm][bj], mv = mw[mm][bj];
;                         u32x4 w;
;                         w.x = cvt_pk_bf16(sigmoid_f(a0[0]) * bflo(yv.x) + bflo(mv.x), sigmoid_f(a0[1]) * bfhi(yv.x) + bfhi(mv.x));
;                         w.y = cvt_pk_bf16(sigmoid_f(a0[2]) * bflo(yv.y) + bflo(mv.y), sigmoid_f(a0[3]) * bfhi(yv.y) + bfhi(mv.y));
;                         w.z = cvt_pk_bf16(sigmoid_f(a1[0]) * bflo(yv.z) + bflo(mv.z), sigmoid_f(a1[1]) * bfhi(yv.z) + bfhi(mv.z));
;                         w.w = cvt_pk_bf16(sigmoid_f(a1[2]) * bflo(yv.w) + bflo(mv.w), sigmoid_f(a1[3]) * bfhi(yv.w) + bfhi(mv.w));
;                         *(u32x4*)(merged + tl(rr, col0 + bj * HALF, DM)) = w;
	v_and_b32_e32 v203, 0xffff0000, v235
	v_lshlrev_b32_e32 v214, 16, v239
	v_and_b32_e32 v215, 0xffff0000, v239
	v_fma_f32 v42, v42, v202, v214
	v_fma_f32 v43, v43, v203, v215
	v_cvt_pk_bf16_f32 v209, v42, v43
	global_store_dwordx4 v182, v[206:209], s[12:13]
	v_lshlrev_b32_e32 v198, 16, v240
	v_and_b32_e32 v199, 0xffff0000, v240
	v_lshlrev_b32_e32 v200, 16, v244
	v_and_b32_e32 v201, 0xffff0000, v244
	v_fma_f32 v36, v36, v198, v200
	v_fma_f32 v37, v37, v199, v201
	v_cvt_pk_bf16_f32 v210, v36, v37
	v_lshlrev_b32_e32 v202, 16, v241
	v_and_b32_e32 v203, 0xffff0000, v241
	v_lshlrev_b32_e32 v214, 16, v245
	v_and_b32_e32 v215, 0xffff0000, v245
	v_fma_f32 v38, v38, v202, v214
	v_fma_f32 v39, v39, v203, v215
	v_cvt_pk_bf16_f32 v211, v38, v39
	v_lshlrev_b32_e32 v198, 16, v242
	v_and_b32_e32 v199, 0xffff0000, v242
	v_lshlrev_b32_e32 v200, 16, v246
	v_and_b32_e32 v201, 0xffff0000, v246
	v_fma_f32 v32, v32, v198, v200
	v_fma_f32 v33, v33, v199, v201
	v_cvt_pk_bf16_f32 v212, v32, v33
	v_lshlrev_b32_e32 v202, 16, v243
	v_and_b32_e32 v203, 0xffff0000, v243
	v_lshlrev_b32_e32 v214, 16, v247
	v_and_b32_e32 v215, 0xffff0000, v247
	v_fma_f32 v34, v34, v202, v214
	v_fma_f32 v35, v35, v203, v215
	v_cvt_pk_bf16_f32 v213, v34, v35
	global_store_dwordx4 v183, v[210:213], s[12:13]
	v_mul_f32_e32 v28, 0xbfb8aa3b, v28
	v_mul_f32_e32 v29, 0xbfb8aa3b, v29
	v_mul_f32_e32 v30, 0xbfb8aa3b, v30
	v_mul_f32_e32 v31, 0xbfb8aa3b, v31
	v_mul_f32_e32 v24, 0xbfb8aa3b, v24
	v_mul_f32_e32 v25, 0xbfb8aa3b, v25
	v_mul_f32_e32 v26, 0xbfb8aa3b, v26
	v_mul_f32_e32 v27, 0xbfb8aa3b, v27
	v_exp_f32_e32 v28, v28
	v_exp_f32_e32 v29, v29
	v_exp_f32_e32 v30, v30
	v_exp_f32_e32 v31, v31
	v_exp_f32_e32 v24, v24
	v_exp_f32_e32 v25, v25
	v_exp_f32_e32 v26, v26
	v_exp_f32_e32 v27, v27
	v_add_f32_e32 v28, 1.0, v28
	v_add_f32_e32 v29, 1.0, v29
	v_add_f32_e32 v30, 1.0, v30
	v_add_f32_e32 v31, 1.0, v31
	v_add_f32_e32 v24, 1.0, v24
	v_add_f32_e32 v25, 1.0, v25
	v_add_f32_e32 v26, 1.0, v26
	v_add_f32_e32 v27, 1.0, v27
	v_rcp_f32_e32 v28, v28
	v_rcp_f32_e32 v29, v29
	v_rcp_f32_e32 v30, v30
	v_rcp_f32_e32 v31, v31
	v_rcp_f32_e32 v24, v24
	v_rcp_f32_e32 v25, v25
	v_rcp_f32_e32 v26, v26
	v_rcp_f32_e32 v27, v27
	v_mul_f32_e32 v20, 0xbfb8aa3b, v20
	v_mul_f32_e32 v21, 0xbfb8aa3b, v21
	v_mul_f32_e32 v22, 0xbfb8aa3b, v22
	v_mul_f32_e32 v23, 0xbfb8aa3b, v23
	v_mul_f32_e32 v16, 0xbfb8aa3b, v16
	v_mul_f32_e32 v17, 0xbfb8aa3b, v17
	v_mul_f32_e32 v18, 0xbfb8aa3b, v18
	v_mul_f32_e32 v19, 0xbfb8aa3b, v19
	v_exp_f32_e32 v20, v20
	v_exp_f32_e32 v21, v21
	v_exp_f32_e32 v22, v22
	v_exp_f32_e32 v23, v23
	v_exp_f32_e32 v16, v16
	v_exp_f32_e32 v17, v17
	v_exp_f32_e32 v18, v18
	v_exp_f32_e32 v19, v19
	v_add_f32_e32 v20, 1.0, v20
	v_add_f32_e32 v21, 1.0, v21
	v_add_f32_e32 v22, 1.0, v22
	v_add_f32_e32 v23, 1.0, v23
	v_add_f32_e32 v16, 1.0, v16
	v_add_f32_e32 v17, 1.0, v17
	v_add_f32_e32 v18, 1.0, v18
	v_add_f32_e32 v19, 1.0, v19
	v_rcp_f32_e32 v20, v20
	v_rcp_f32_e32 v21, v21
	v_rcp_f32_e32 v22, v22
	v_rcp_f32_e32 v23, v23
	v_rcp_f32_e32 v16, v16
	v_rcp_f32_e32 v17, v17
	v_rcp_f32_e32 v18, v18
	v_rcp_f32_e32 v19, v19
	v_mul_f32_e32 v12, 0xbfb8aa3b, v12
	v_mul_f32_e32 v13, 0xbfb8aa3b, v13
	v_mul_f32_e32 v14, 0xbfb8aa3b, v14
	v_mul_f32_e32 v15, 0xbfb8aa3b, v15
	v_mul_f32_e32 v8, 0xbfb8aa3b, v8
	v_mul_f32_e32 v9, 0xbfb8aa3b, v9
	v_mul_f32_e32 v10, 0xbfb8aa3b, v10
	v_mul_f32_e32 v11, 0xbfb8aa3b, v11
	v_exp_f32_e32 v12, v12
	v_exp_f32_e32 v13, v13
	v_exp_f32_e32 v14, v14
	v_exp_f32_e32 v15, v15
	v_exp_f32_e32 v8, v8
	v_exp_f32_e32 v9, v9
	v_exp_f32_e32 v10, v10
	v_exp_f32_e32 v11, v11
	v_add_f32_e32 v12, 1.0, v12
	v_add_f32_e32 v13, 1.0, v13
	v_add_f32_e32 v14, 1.0, v14
	v_add_f32_e32 v15, 1.0, v15
	v_add_f32_e32 v8, 1.0, v8
	v_add_f32_e32 v9, 1.0, v9
	v_add_f32_e32 v10, 1.0, v10
	v_add_f32_e32 v11, 1.0, v11
	v_rcp_f32_e32 v12, v12
	v_rcp_f32_e32 v13, v13
	v_rcp_f32_e32 v14, v14
	v_rcp_f32_e32 v15, v15
	v_rcp_f32_e32 v8, v8
	v_rcp_f32_e32 v9, v9
	v_rcp_f32_e32 v10, v10
	v_rcp_f32_e32 v11, v11
	v_mul_f32_e32 v4, 0xbfb8aa3b, v4
	v_mul_f32_e32 v5, 0xbfb8aa3b, v5
	v_mul_f32_e32 v6, 0xbfb8aa3b, v6
	v_mul_f32_e32 v7, 0xbfb8aa3b, v7
	v_mul_f32_e32 v0, 0xbfb8aa3b, v0
	v_mul_f32_e32 v1, 0xbfb8aa3b, v1
	v_mul_f32_e32 v2, 0xbfb8aa3b, v2
	v_mul_f32_e32 v3, 0xbfb8aa3b, v3
	v_exp_f32_e32 v4, v4
	v_exp_f32_e32 v5, v5
	v_exp_f32_e32 v6, v6
	v_exp_f32_e32 v7, v7
	v_exp_f32_e32 v0, v0
	v_exp_f32_e32 v1, v1
	v_exp_f32_e32 v2, v2
	v_exp_f32_e32 v3, v3
	v_add_f32_e32 v4, 1.0, v4
	v_add_f32_e32 v5, 1.0, v5
	v_add_f32_e32 v6, 1.0, v6
	v_add_f32_e32 v7, 1.0, v7
	v_add_f32_e32 v0, 1.0, v0
	v_add_f32_e32 v1, 1.0, v1
	v_add_f32_e32 v2, 1.0, v2
	v_add_f32_e32 v3, 1.0, v3
	v_rcp_f32_e32 v4, v4
	v_rcp_f32_e32 v5, v5
	v_rcp_f32_e32 v6, v6
	v_rcp_f32_e32 v7, v7
	v_rcp_f32_e32 v0, v0
	v_rcp_f32_e32 v1, v1
	v_rcp_f32_e32 v2, v2
	v_rcp_f32_e32 v3, v3
	s_waitcnt vmcnt(4)
; __device__ __forceinline__ unsigned cvt_pk_bf16(float lo, float hi) { f32x2 v = {lo, hi}; bf16x2_t b = __builtin_convertvector(v, bf16x2_t); return __builtin_bit_cast(unsigned, b); }
; __device__ __forceinline__ float bflo(unsigned w) { return __uint_as_float(w << 16); }
; __device__ __forceinline__ float bfhi(unsigned w) { return __uint_as_float(w & 0xffff0000u); }
; __device__ __forceinline__ float sigmoid_f(float x) { return __builtin_amdgcn_rcpf(1.0f + __expf(-x)); }
; __device__ __forceinline__ size_t tl(int r, int c, int K) { return ((size_t)(r >> 8) * (size_t)(K >> 6) + (size_t)(c >> 6)) * 16384 + (size_t)((r & 255) << 6) + (size_t)(c & 63); }
;     __device__ __forceinline__ void operator()(const f32x4 (&acc)[2][2][4][2], const Unit& u, int wr, int wc, int fr, int fq) const {
;     ...
;                 for (int mm = 0; mm < 2; ++mm) {
;                     const int m = mh * 2 + mm;
;                     const int rr = row0 + ai * HALF + m * 16;
; #pragma unroll
;                     for (int bj = 0; bj < 2; ++bj) {
;                         const f32x4 a0 = acc[ai][bj][m][0], a1 = acc[ai][bj][m][1];
;                         const u32x4 yv = yw[mm][bj], mv = mw[mm][bj];
;                         u32x4 w;
;                         w.x = cvt_pk_bf16(sigmoid_f(a0[0]) * bflo(yv.x) + bflo(mv.x), sigmoid_f(a0[1]) * bfhi(yv.x) + bfhi(mv.x));
;                         w.y = cvt_pk_bf16(sigmoid_f(a0[2]) * bflo(yv.y) + bflo(mv.y), sigmoid_f(a0[3]) * bfhi(yv.y) + bfhi(mv.y));
;                         w.z = cvt_pk_bf16(sigmoid_f(a1[0]) * bflo(yv.z) + bflo(mv.z), sigmoid_f(a1[1]) * bfhi(yv.z) + bfhi(mv.z));
;                         w.w = cvt_pk_bf16(sigmoid_f(a1[2]) * bflo(yv.w) + bflo(mv.w), sigmoid_f(a1[3]) * bfhi(yv.w) + bfhi(mv.w));
;                         *(u32x4*)(merged + tl(rr, col0 + bj * HALF, DM)) = w;
;                     }
	v_lshlrev_b32_e32 v198, 16, v128
	v_and_b32_e32 v199, 0xffff0000, v128
	v_lshlrev_b32_e32 v200, 16, v132
	v_and_b32_e32 v201, 0xffff0000, v132
	v_fma_f32 v28, v28, v198, v200
	v_fma_f32 v29, v29, v199, v201
	v_cvt_pk_bf16_f32 v248, v28, v29
	v_lshlrev_b32_e32 v202, 16, v129
	v_and_b32_e32 v203, 0xffff0000, v129
	v_lshlrev_b32_e32 v214, 16, v133
	v_and_b32_e32 v215, 0xffff0000, v133
	v_fma_f32 v30, v30, v202, v214
	v_fma_f32 v31, v31, v203, v215
	v_cvt_pk_bf16_f32 v249, v30, v31
	v_lshlrev_b32_e32 v198, 16, v130
	v_and_b32_e32 v199, 0xffff0000, v130
	v_lshlrev_b32_e32 v200, 16, v134
	v_and_b32_e32 v201, 0xffff0000, v134
	v_fma_f32 v24, v24, v198, v200
	v_fma_f32 v25, v25, v199, v201
	v_cvt_pk_bf16_f32 v250, v24, v25
	v_lshlrev_b32_e32 v202, 16, v131
	v_and_b32_e32 v203, 0xffff0000, v131
	v_lshlrev_b32_e32 v214, 16, v135
	v_and_b32_e32 v215, 0xffff0000, v135
	v_fma_f32 v26, v26, v202, v214
	v_fma_f32 v27, v27, v203, v215
	v_cvt_pk_bf16_f32 v251, v26, v27
	global_store_dwordx4 v194, v[248:251], s[12:13]
	v_lshlrev_b32_e32 v198, 16, v136
	v_and_b32_e32 v199, 0xffff0000, v136
	v_lshlrev_b32_e32 v200, 16, v140
	v_and_b32_e32 v201, 0xffff0000, v140
	v_fma_f32 v20, v20, v198, v200
	v_fma_f32 v21, v21, v199, v201
	v_cvt_pk_bf16_f32 v252, v20, v21
	v_lshlrev_b32_e32 v202, 16, v137
	v_and_b32_e32 v203, 0xffff0000, v137
	v_lshlrev_b32_e32 v214, 16, v141
	v_and_b32_e32 v215, 0xffff0000, v141
	v_fma_f32 v22, v22, v202, v214
	v_fma_f32 v23, v23, v203, v215
	v_cvt_pk_bf16_f32 v253, v22, v23
	v_lshlrev_b32_e32 v198, 16, v138
	v_and_b32_e32 v199, 0xffff0000, v138
	v_lshlrev_b32_e32 v200, 16, v142
	v_and_b32_e32 v201, 0xffff0000, v142
	v_fma_f32 v16, v16, v198, v200
	v_fma_f32 v17, v17, v199, v201
	v_cvt_pk_bf16_f32 v254, v16, v17
	v_lshlrev_b32_e32 v202, 16, v139
	v_and_b32_e32 v203, 0xffff0000, v139
	v_lshlrev_b32_e32 v214, 16, v143
	v_and_b32_e32 v215, 0xffff0000, v143
	v_fma_f32 v18, v18, v202, v214
	v_fma_f32 v19, v19, v203, v215
	v_cvt_pk_bf16_f32 v255, v18, v19
	global_store_dwordx4 v195, v[252:255], s[12:13]
	v_lshlrev_b32_e32 v198, 16, v144
	v_and_b32_e32 v199, 0xffff0000, v144
	v_lshlrev_b32_e32 v200, 16, v148
	v_and_b32_e32 v201, 0xffff0000, v148
	v_fma_f32 v12, v12, v198, v200
	v_fma_f32 v13, v13, v199, v201
	v_cvt_pk_bf16_f32 v206, v12, v13
	v_lshlrev_b32_e32 v202, 16, v145
	v_and_b32_e32 v203, 0xffff0000, v145
	v_lshlrev_b32_e32 v214, 16, v149
	v_and_b32_e32 v215, 0xffff0000, v149
	v_fma_f32 v14, v14, v202, v214
	v_fma_f32 v15, v15, v203, v215
	v_cvt_pk_bf16_f32 v207, v14, v15
	v_lshlrev_b32_e32 v198, 16, v146
	v_and_b32_e32 v199, 0xffff0000, v146
	v_lshlrev_b32_e32 v200, 16, v150
	v_and_b32_e32 v201, 0xffff0000, v150
	v_fma_f32 v8, v8, v198, v200
	v_fma_f32 v9, v9, v199, v201
	v_cvt_pk_bf16_f32 v208, v8, v9
	v_lshlrev_b32_e32 v202, 16, v147
	v_and_b32_e32 v203, 0xffff0000, v147
	v_lshlrev_b32_e32 v214, 16, v151
	v_and_b32_e32 v215, 0xffff0000, v151
	v_fma_f32 v10, v10, v202, v214
	v_fma_f32 v11, v11, v203, v215
	v_cvt_pk_bf16_f32 v209, v10, v11
	global_store_dwordx4 v196, v[206:209], s[12:13]
	v_lshlrev_b32_e32 v198, 16, v152
	v_and_b32_e32 v199, 0xffff0000, v152
	v_lshlrev_b32_e32 v200, 16, v156
	v_and_b32_e32 v201, 0xffff0000, v156
	v_fma_f32 v4, v4, v198, v200
	v_fma_f32 v5, v5, v199, v201
	v_cvt_pk_bf16_f32 v210, v4, v5
	v_lshlrev_b32_e32 v202, 16, v153
	v_and_b32_e32 v203, 0xffff0000, v153
	v_lshlrev_b32_e32 v214, 16, v157
	v_and_b32_e32 v215, 0xffff0000, v157
	v_fma_f32 v6, v6, v202, v214
	v_fma_f32 v7, v7, v203, v215
	v_cvt_pk_bf16_f32 v211, v6, v7
	v_lshlrev_b32_e32 v198, 16, v154
	v_and_b32_e32 v199, 0xffff0000, v154
	v_lshlrev_b32_e32 v200, 16, v158
	v_and_b32_e32 v201, 0xffff0000, v158
	v_fma_f32 v0, v0, v198, v200
	v_fma_f32 v1, v1, v199, v201
	v_cvt_pk_bf16_f32 v212, v0, v1
	v_lshlrev_b32_e32 v202, 16, v155
	v_and_b32_e32 v203, 0xffff0000, v155
	v_lshlrev_b32_e32 v214, 16, v159
	v_and_b32_e32 v215, 0xffff0000, v159
	v_fma_f32 v2, v2, v202, v214
	v_fma_f32 v3, v3, v203, v215
	v_cvt_pk_bf16_f32 v213, v2, v3
	global_store_dwordx4 v197, v[210:213], s[12:13]
	s_branch .Lmy_p9_latch

; __global__ void __launch_bounds__(512, 2) mega(Params Parg) {
	.amdhsa_kernel _Z4mega6Params
		.amdhsa_group_segment_fixed_size 0
		.amdhsa_private_segment_fixed_size 0
		.amdhsa_kernarg_size 544
		.amdhsa_user_sgpr_count 2
		.amdhsa_user_sgpr_dispatch_ptr 0
		.amdhsa_user_sgpr_queue_ptr 0
		.amdhsa_user_sgpr_kernarg_segment_ptr 1
		.amdhsa_user_sgpr_dispatch_id 0
		.amdhsa_user_sgpr_kernarg_preload_length 0
		.amdhsa_user_sgpr_kernarg_preload_offset 0
		.amdhsa_user_sgpr_private_segment_size 0
		.amdhsa_uses_dynamic_stack 0
		.amdhsa_enable_private_segment 0
		.amdhsa_system_sgpr_workgroup_id_x 1
		.amdhsa_system_sgpr_workgroup_id_y 0
		.amdhsa_system_sgpr_workgroup_id_z 0
		.amdhsa_system_sgpr_workgroup_info 0
		.amdhsa_system_vgpr_workitem_id 2
		.amdhsa_next_free_vgpr 256
		.amdhsa_next_free_sgpr 102
		.amdhsa_accum_offset 256
		.amdhsa_reserve_vcc 1
		.amdhsa_float_round_mode_32 0
		.amdhsa_float_round_mode_16_64 0
		.amdhsa_float_denorm_mode_32 3
		.amdhsa_float_denorm_mode_16_64 3
		.amdhsa_dx10_clamp 1
		.amdhsa_ieee_mode 1
		.amdhsa_fp16_overflow 0
		.amdhsa_tg_split 0
		.amdhsa_exception_fp_ieee_invalid_op 0
		.amdhsa_exception_fp_denorm_src 0
		.amdhsa_exception_fp_ieee_div_zero 0
		.amdhsa_exception_fp_ieee_overflow 0
		.amdhsa_exception_fp_ieee_underflow 0
		.amdhsa_exception_fp_ieee_inexact 0
		.amdhsa_exception_int_div_zero 0
	.end_amdhsa_kernel

; __global__ void __launch_bounds__(512, 2) mega(Params Parg) {
amdhsa.kernels:
  - .agpr_count:     0
    .args:
      - .offset:         0
        .size:           288
        .value_kind:     by_value
      - .offset:         288
        .size:           4
        .value_kind:     hidden_block_count_x
      - .offset:         292
        .size:           4
        .value_kind:     hidden_block_count_y
      - .offset:         296
        .size:           4
        .value_kind:     hidden_block_count_z
      - .offset:         300
        .size:           2
        .value_kind:     hidden_group_size_x
      - .offset:         302
        .size:           2
        .value_kind:     hidden_group_size_y
      - .offset:         304
        .size:           2
        .value_kind:     hidden_group_size_z
      - .offset:         306
        .size:           2
        .value_kind:     hidden_remainder_x
      - .offset:         308
        .size:           2
        .value_kind:     hidden_remainder_y
      - .offset:         310
        .size:           2
        .value_kind:     hidden_remainder_z
      - .offset:         328
        .size:           8
        .value_kind:     hidden_global_offset_x
      - .offset:         336
        .size:           8
        .value_kind:     hidden_global_offset_y
      - .offset:         344
        .size:           8
        .value_kind:     hidden_global_offset_z
      - .offset:         352
        .size:           2
        .value_kind:     hidden_grid_dims
      - .offset:         376
        .size:           8
        .value_kind:     hidden_multigrid_sync_arg
      - .offset:         408
        .size:           4
        .value_kind:     hidden_dynamic_lds_size
    .group_segment_fixed_size: 0
    .kernarg_segment_align: 8
    .kernarg_segment_size: 544
    .language:       OpenCL C
    .language_version:
      - 2
      - 0
    .max_flat_workgroup_size: 512
    .name:           _Z4mega6Params
    .private_segment_fixed_size: 0
    .sgpr_count:     108
    .sgpr_spill_count: 0
    .symbol:         _Z4mega6Params.kd
    .uniform_work_group_size: 1
    .uses_dynamic_stack: false
    .vgpr_count:     256
    .vgpr_spill_count: 0
    .wavefront_size: 64
